# v9: GEMM first-K-iteration peeled (no accumulator zeroing) in all 4 loops; FFN1 SwiGLU epilogue 6 VALU/elem + incremental store addresses; NA bias table loads batched; S5 state reads hoisted; GQA Q ho
# speedup vs baseline: 1.0149x; 1.0149x over previous
; #define PG8_STAGE(bufoff, gbase, voff) do { _Pragma("unroll") for (int _i = 0; _i < 2; ++_i) \
;         __builtin_amdgcn_global_load_lds((const unsigned*)((const char*)(gbase) + (voff)[_i]), (PG8_LAS unsigned*)(lds + (bufoff) + ldsw + _i * 8192), 16, 0, 0); } while (0)
; #define PG8_LDA(dst, b, h) do { _Pragma("unroll") for (int m = 0; m < 4; ++m) _Pragma("unroll") for (int k = 0; k < 2; ++k) dst[m][k] = *(const PG8_LAS bf16x8*)(lds + PG8_SA(b, h) + aoff + m * 2048 + k * 1024); } while (0)
; #define PG8_LDB(dst, b, h) do { _Pragma("unroll") for (int n = 0; n < 2; ++n) _Pragma("unroll") for (int k = 0; k < 2; ++k) dst[n][k] = *(const PG8_LAS bf16x8*)(lds + PG8_SB(b, h) + boff + n * 2048 + k * 1024); } while (0)
; #define PG8_MMA(ai, bj, At, Bt) do { __builtin_amdgcn_s_setprio(1); _Pragma("unroll") for (int m = 0; m < 4; ++m) _Pragma("unroll") for (int n = 0; n < 2; ++n) _Pragma("unroll") for (int k = 0; k < 2; ++k) \
;         acc[ai][bj][m][n] = __builtin_amdgcn_mfma_f32_16x16x32_bf16(Bt[n][k], At[m][k], acc[ai][bj][m][n], 0, 0, 0); __builtin_amdgcn_s_setprio(0); } while (0)
; #define PG8_WAIT_V(n) asm volatile("s_waitcnt vmcnt(" #n ")" ::: "memory")
; #define PG8_WAIT_L(n) asm volatile("s_waitcnt lgkmcnt(" #n ")" ::: "memory")
; #define PG8_BAR __builtin_amdgcn_s_barrier()
; #define PG8_SCHED __builtin_amdgcn_sched_barrier(0)
; template <class Epi, class Sched, bool ALIGN_EPI = false, bool SP2 = false>
; __device__ __forceinline__ void gemm_phase(PG8_LAS unsigned char* lds, const Gemm g, const Sched& S, const Epi& E) {
;     ...
;     f32x4 acc[2][2][4][2];
; #pragma unroll
;     for (int a = 0; a < 2; ++a)
; #pragma unroll
;         for (int b = 0; b < 2; ++b)
; #pragma unroll
;             for (int m = 0; m < 4; ++m)
; #pragma unroll
;                 for (int n = 0; n < 2; ++n) acc[a][b][m][n] = (f32x4){0.f, 0.f, 0.f, 0.f};
;     ...
;             PG8_LDB(B0, 0, 0); PG8_LDB(B1, 0, 1); PG8_SCHED; PG8_LDA(At, 0, 0); PG8_STAGE(PG8_SA(1, 1), a1 + hstep, voffA);
;             PG8_WAIT_V(8); PG8_WAIT_L(0); PG8_BAR; PG8_MMA(0, 0, At, B0); PG8_MMA(0, 1, At, B1); PG8_BAR; PG8_SCHED;
;             PG8_LDA(At, 0, 1); PG8_STAGE(PG8_SB(0, 0), b2, voffB); PG8_STAGE(PG8_SB(0, 1), b2 + hstep, voffB); PG8_STAGE(PG8_SA(0, 0), a2, voffA);
;             PG8_WAIT_V(8); PG8_WAIT_L(0); PG8_BAR; PG8_MMA(1, 0, At, B0); PG8_MMA(1, 1, At, B1); PG8_BAR; PG8_SCHED;
.LBB0_198:
	s_ashr_i32 s23, s22, 31
	s_lshl_b64 s[16:17], s[22:23], 18
	s_add_u32 s46, s4, s16
	s_addc_u32 s47, s5, s17
	s_and_b64 s[16:17], s[40:41], exec
	s_cselect_b32 s11, s47, s3
	s_cselect_b32 s16, s46, s2
	s_ashr_i32 s19, s18, 31
	s_lshl_b64 s[48:49], s[18:19], 18
	s_add_u32 s48, s20, s48
	s_addc_u32 s49, s54, s49
	s_and_b64 s[50:51], s[40:41], exec
	s_cselect_b32 s17, s49, s25
	s_cselect_b32 s19, s48, s24
	s_add_u32 s2, s2, 0x20080
	s_addc_u32 s3, s3, 0
	s_add_u32 s23, s24, 0x100
	s_addc_u32 s35, s25, 0
	s_mov_b32 s65, -2
	s_waitcnt vmcnt(0)
	s_waitcnt vmcnt(0)
	s_add_u32 s24, s2, 0xfffe0080
	s_addc_u32 s25, s3, -1
	s_add_i32 s66, 0, 0x10000
	s_cmp_eq_u32 s65, 4
	s_cselect_b32 s51, s11, s25
	s_cselect_b32 s50, s16, s24
	s_cselect_b32 s25, s17, s35
	s_cselect_b32 s24, s19, s23
	s_add_i32 s68, 0, 0x14000
	v_add_u32_e32 v78, s66, v252
	v_add_u32_e32 v126, s68, v252
	ds_read_b128 v[42:45], v78
	ds_read_b128 v[54:57], v78 offset:1024
	ds_read_b128 v[66:69], v78 offset:2048
	ds_read_b128 v[78:81], v78 offset:3072
	ds_read_b128 v[90:93], v126
	ds_read_b128 v[102:105], v126 offset:1024
	ds_read_b128 v[114:117], v126 offset:2048
	ds_read_b128 v[126:129], v126 offset:3072
	v_lshl_add_u64 v[194:195], s[2:3], 0, v[212:213]
	s_add_i32 m0, s57, 0xc000
	ds_read_b128 v[138:141], v241
	ds_read_b128 v[142:145], v241 offset:1024
	ds_read_b128 v[146:149], v241 offset:2048
	ds_read_b128 v[158:161], v241 offset:3072
	ds_read_b128 v[170:173], v241 offset:4096
	ds_read_b128 v[182:185], v241 offset:5120
	ds_read_b128 v[186:189], v241 offset:6144
	ds_read_b128 v[190:193], v241 offset:7168
	global_load_lds_dwordx4 v[194:195], off
	v_lshl_add_u64 v[194:195], s[2:3], 0, v[214:215]
	s_add_i32 m0, s57, 0xe000
	s_nop 0
	global_load_lds_dwordx4 v[194:195], off
	s_waitcnt vmcnt(8)
	s_waitcnt lgkmcnt(0)
	s_barrier
	s_setprio 1
	v_mfma_f32_16x16x32_bf16 v[178:181], v[42:45], v[138:141], 0
	v_mfma_f32_16x16x32_bf16 v[174:177], v[66:69], v[138:141], 0
	v_mfma_f32_16x16x32_bf16 v[166:169], v[42:45], v[146:149], 0
	v_mfma_f32_16x16x32_bf16 v[162:165], v[66:69], v[146:149], 0
	v_mfma_f32_16x16x32_bf16 v[154:157], v[42:45], v[170:173], 0
	v_mfma_f32_16x16x32_bf16 v[150:153], v[66:69], v[170:173], 0
	v_mfma_f32_16x16x32_bf16 v[134:137], v[42:45], v[186:189], 0
	v_mfma_f32_16x16x32_bf16 v[130:133], v[66:69], v[186:189], 0
	v_mfma_f32_16x16x32_bf16 v[178:181], v[54:57], v[142:145], v[178:181]
	v_mfma_f32_16x16x32_bf16 v[174:177], v[78:81], v[142:145], v[174:177]
	v_mfma_f32_16x16x32_bf16 v[166:169], v[54:57], v[158:161], v[166:169]
	v_mfma_f32_16x16x32_bf16 v[162:165], v[78:81], v[158:161], v[162:165]
	v_mfma_f32_16x16x32_bf16 v[154:157], v[54:57], v[182:185], v[154:157]
	v_mfma_f32_16x16x32_bf16 v[150:153], v[78:81], v[182:185], v[150:153]
	v_mfma_f32_16x16x32_bf16 v[134:137], v[54:57], v[190:193], v[134:137]
	v_mfma_f32_16x16x32_bf16 v[130:133], v[78:81], v[190:193], v[130:133]
	v_mfma_f32_16x16x32_bf16 v[74:77], v[90:93], v[138:141], 0
	v_mfma_f32_16x16x32_bf16 v[70:73], v[114:117], v[138:141], 0
	v_mfma_f32_16x16x32_bf16 v[62:65], v[90:93], v[146:149], 0
	v_mfma_f32_16x16x32_bf16 v[58:61], v[114:117], v[146:149], 0
	v_mfma_f32_16x16x32_bf16 v[50:53], v[90:93], v[170:173], 0
	v_mfma_f32_16x16x32_bf16 v[46:49], v[114:117], v[170:173], 0
	v_mfma_f32_16x16x32_bf16 v[38:41], v[90:93], v[186:189], 0
	v_mfma_f32_16x16x32_bf16 v[34:37], v[114:117], v[186:189], 0
	v_mfma_f32_16x16x32_bf16 v[74:77], v[102:105], v[142:145], v[74:77]
	v_mfma_f32_16x16x32_bf16 v[70:73], v[126:129], v[142:145], v[70:73]
	v_mfma_f32_16x16x32_bf16 v[62:65], v[102:105], v[158:161], v[62:65]
	v_mfma_f32_16x16x32_bf16 v[58:61], v[126:129], v[158:161], v[58:61]
	v_mfma_f32_16x16x32_bf16 v[50:53], v[102:105], v[182:185], v[50:53]
	v_mfma_f32_16x16x32_bf16 v[46:49], v[126:129], v[182:185], v[46:49]
	v_mfma_f32_16x16x32_bf16 v[38:41], v[102:105], v[190:193], v[38:41]
	v_mfma_f32_16x16x32_bf16 v[34:37], v[126:129], v[190:193], v[34:37]
	s_setprio 0
	s_barrier
	s_add_i32 s66, s66, s55
	v_lshl_add_u64 v[198:199], s[24:25], 0, v[0:1]
	s_mov_b32 m0, s66
	ds_read_b128 v[138:141], v241 offset:16384
	ds_read_b128 v[142:145], v241 offset:17408
	ds_read_b128 v[146:149], v241 offset:18432
	ds_read_b128 v[158:161], v241 offset:19456
	ds_read_b128 v[170:173], v241 offset:20480
	ds_read_b128 v[182:185], v241 offset:21504
	ds_read_b128 v[186:189], v241 offset:22528
	ds_read_b128 v[190:193], v241 offset:23552
	global_load_lds_dwordx4 v[198:199], off
	s_add_i32 m0, s66, 0x2000
	s_add_u32 s66, s24, 0x20000
	v_lshl_add_u64 v[200:201], s[24:25], 0, v[206:207]
	s_addc_u32 s67, s25, 0
	s_add_i32 s68, s68, s55
	global_load_lds_dwordx4 v[200:201], off
	v_lshl_add_u64 v[194:195], s[66:67], 0, v[0:1]
	s_mov_b32 m0, s68
	v_lshl_add_u64 v[216:217], s[50:51], 0, v[210:211]
	global_load_lds_dwordx4 v[194:195], off
	v_lshl_add_u64 v[194:195], s[66:67], 0, v[206:207]
	s_add_i32 m0, s68, 0x2000
	v_lshl_add_u64 v[218:219], s[50:51], 0, v[208:209]
	global_load_lds_dwordx4 v[194:195], off
	s_mov_b32 m0, s57
	s_nop 0
	global_load_lds_dwordx4 v[216:217], off
	s_mov_b32 m0, s58
	s_nop 0
	global_load_lds_dwordx4 v[218:219], off
	s_waitcnt vmcnt(8)
	s_waitcnt lgkmcnt(0)
	s_barrier
; #define PG8_STAGE(bufoff, gbase, voff) do { _Pragma("unroll") for (int _i = 0; _i < 2; ++_i) \
;         __builtin_amdgcn_global_load_lds((const unsigned*)((const char*)(gbase) + (voff)[_i]), (PG8_LAS unsigned*)(lds + (bufoff) + ldsw + _i * 8192), 16, 0, 0); } while (0)
; #define PG8_LDA(dst, b, h) do { _Pragma("unroll") for (int m = 0; m < 4; ++m) _Pragma("unroll") for (int k = 0; k < 2; ++k) dst[m][k] = *(const PG8_LAS bf16x8*)(lds + PG8_SA(b, h) + aoff + m * 2048 + k * 1024); } while (0)
; #define PG8_LDB(dst, b, h) do { _Pragma("unroll") for (int n = 0; n < 2; ++n) _Pragma("unroll") for (int k = 0; k < 2; ++k) dst[n][k] = *(const PG8_LAS bf16x8*)(lds + PG8_SB(b, h) + boff + n * 2048 + k * 1024); } while (0)
; #define PG8_MMA(ai, bj, At, Bt) do { __builtin_amdgcn_s_setprio(1); _Pragma("unroll") for (int m = 0; m < 4; ++m) _Pragma("unroll") for (int n = 0; n < 2; ++n) _Pragma("unroll") for (int k = 0; k < 2; ++k) \
;         acc[ai][bj][m][n] = __builtin_amdgcn_mfma_f32_16x16x32_bf16(Bt[n][k], At[m][k], acc[ai][bj][m][n], 0, 0, 0); __builtin_amdgcn_s_setprio(0); } while (0)
; #define PG8_WAIT_V(n) asm volatile("s_waitcnt vmcnt(" #n ")" ::: "memory")
; #define PG8_WAIT_L(n) asm volatile("s_waitcnt lgkmcnt(" #n ")" ::: "memory")
; #define PG8_BAR __builtin_amdgcn_s_barrier()
; #define PG8_SCHED __builtin_amdgcn_sched_barrier(0)
; template <class Epi, class Sched, bool ALIGN_EPI = false, bool SP2 = false>
; __device__ __forceinline__ void gemm_phase(PG8_LAS unsigned char* lds, const Gemm g, const Sched& S, const Epi& E) {
;     ...
;             PG8_WAIT_V(8); PG8_WAIT_L(0); PG8_BAR; PG8_MMA(1, 0, At, B0); PG8_MMA(1, 1, At, B1); PG8_BAR; PG8_SCHED;
;             PG8_LDB(B0, 1, 0); PG8_LDB(B1, 1, 1); PG8_SCHED; PG8_LDA(At, 1, 0); PG8_STAGE(PG8_SA(0, 1), a2 + hstep, voffA);
;             PG8_WAIT_V(8); PG8_WAIT_L(0); PG8_BAR; PG8_MMA(0, 0, At, B0); PG8_MMA(0, 1, At, B1); PG8_BAR; PG8_SCHED;
	s_setprio 1
	v_mfma_f32_16x16x32_bf16 v[122:125], v[42:45], v[138:141], 0
	v_mfma_f32_16x16x32_bf16 v[118:121], v[66:69], v[138:141], 0
	v_mfma_f32_16x16x32_bf16 v[110:113], v[42:45], v[146:149], 0
	v_mfma_f32_16x16x32_bf16 v[106:109], v[66:69], v[146:149], 0
	v_mfma_f32_16x16x32_bf16 v[98:101], v[42:45], v[170:173], 0
	v_mfma_f32_16x16x32_bf16 v[94:97], v[66:69], v[170:173], 0
	v_mfma_f32_16x16x32_bf16 v[42:45], v[42:45], v[186:189], 0
	v_mfma_f32_16x16x32_bf16 v[122:125], v[54:57], v[142:145], v[122:125]
	v_mfma_f32_16x16x32_bf16 v[118:121], v[78:81], v[142:145], v[118:121]
	v_mfma_f32_16x16x32_bf16 v[110:113], v[54:57], v[158:161], v[110:113]
	v_mfma_f32_16x16x32_bf16 v[106:109], v[78:81], v[158:161], v[106:109]
	v_mfma_f32_16x16x32_bf16 v[98:101], v[54:57], v[182:185], v[98:101]
	v_mfma_f32_16x16x32_bf16 v[94:97], v[78:81], v[182:185], v[94:97]
	v_mfma_f32_16x16x32_bf16 v[42:45], v[54:57], v[190:193], v[42:45]
	v_mfma_f32_16x16x32_bf16 v[54:57], v[66:69], v[186:189], 0
	v_mfma_f32_16x16x32_bf16 v[54:57], v[78:81], v[190:193], v[54:57]
	v_mfma_f32_16x16x32_bf16 v[30:33], v[90:93], v[138:141], 0
	v_mfma_f32_16x16x32_bf16 v[26:29], v[114:117], v[138:141], 0
	v_mfma_f32_16x16x32_bf16 v[22:25], v[90:93], v[146:149], 0
	v_mfma_f32_16x16x32_bf16 v[18:21], v[114:117], v[146:149], 0
	v_mfma_f32_16x16x32_bf16 v[14:17], v[90:93], v[170:173], 0
	v_mfma_f32_16x16x32_bf16 v[10:13], v[114:117], v[170:173], 0
	v_mfma_f32_16x16x32_bf16 v[6:9], v[90:93], v[186:189], 0
	v_mfma_f32_16x16x32_bf16 v[2:5], v[114:117], v[186:189], 0
	v_mfma_f32_16x16x32_bf16 v[30:33], v[102:105], v[142:145], v[30:33]
	v_mfma_f32_16x16x32_bf16 v[26:29], v[126:129], v[142:145], v[26:29]
	v_mfma_f32_16x16x32_bf16 v[22:25], v[102:105], v[158:161], v[22:25]
	v_mfma_f32_16x16x32_bf16 v[18:21], v[126:129], v[158:161], v[18:21]
	v_mfma_f32_16x16x32_bf16 v[14:17], v[102:105], v[182:185], v[14:17]
	v_mfma_f32_16x16x32_bf16 v[10:13], v[126:129], v[182:185], v[10:13]
	v_mfma_f32_16x16x32_bf16 v[6:9], v[102:105], v[190:193], v[6:9]
	v_mfma_f32_16x16x32_bf16 v[2:5], v[126:129], v[190:193], v[2:5]
	s_setprio 0
	s_barrier
	s_add_i32 s66, 0, 0x18000
	v_add_u32_e32 v86, s66, v252
	s_add_i32 s67, 0, 0x1c000
	ds_read_b128 v[66:69], v86
	ds_read_b128 v[78:81], v86 offset:1024
	ds_read_b128 v[82:85], v86 offset:2048
	ds_read_b128 v[90:93], v86 offset:3072
	v_add_u32_e32 v86, s67, v252
	ds_read_b128 v[102:105], v86
	ds_read_b128 v[114:117], v86 offset:1024
	ds_read_b128 v[126:129], v86 offset:2048
	ds_read_b128 v[138:141], v86 offset:3072
	s_add_u32 s50, s50, 0x20000
	s_addc_u32 s51, s51, 0
	s_mov_b32 m0, s59
	v_lshl_add_u64 v[194:195], s[50:51], 0, v[210:211]
	ds_read_b128 v[86:89], v241 offset:32768
	ds_read_b128 v[142:145], v241 offset:33792
	ds_read_b128 v[146:149], v241 offset:34816
	ds_read_b128 v[158:161], v241 offset:35840
	ds_read_b128 v[170:173], v241 offset:36864
	ds_read_b128 v[182:185], v241 offset:37888
	ds_read_b128 v[186:189], v241 offset:38912
	ds_read_b128 v[190:193], v241 offset:39936
	global_load_lds_dwordx4 v[194:195], off
	v_lshl_add_u64 v[194:195], s[50:51], 0, v[208:209]
	s_mov_b32 m0, s60
	s_nop 0
	global_load_lds_dwordx4 v[194:195], off
	s_waitcnt vmcnt(8)
	s_waitcnt lgkmcnt(0)
	s_barrier
	s_setprio 1
	v_mfma_f32_16x16x32_bf16 v[178:181], v[66:69], v[86:89], v[178:181]
	v_mfma_f32_16x16x32_bf16 v[174:177], v[82:85], v[86:89], v[174:177]
	v_mfma_f32_16x16x32_bf16 v[166:169], v[66:69], v[146:149], v[166:169]
	v_mfma_f32_16x16x32_bf16 v[162:165], v[82:85], v[146:149], v[162:165]
	v_mfma_f32_16x16x32_bf16 v[154:157], v[66:69], v[170:173], v[154:157]
	v_mfma_f32_16x16x32_bf16 v[150:153], v[82:85], v[170:173], v[150:153]
	v_mfma_f32_16x16x32_bf16 v[134:137], v[66:69], v[186:189], v[134:137]
	v_mfma_f32_16x16x32_bf16 v[130:133], v[82:85], v[186:189], v[130:133]
	v_mfma_f32_16x16x32_bf16 v[178:181], v[78:81], v[142:145], v[178:181]
	v_mfma_f32_16x16x32_bf16 v[174:177], v[90:93], v[142:145], v[174:177]
	v_mfma_f32_16x16x32_bf16 v[166:169], v[78:81], v[158:161], v[166:169]
	v_mfma_f32_16x16x32_bf16 v[162:165], v[90:93], v[158:161], v[162:165]
	v_mfma_f32_16x16x32_bf16 v[154:157], v[78:81], v[182:185], v[154:157]
	v_mfma_f32_16x16x32_bf16 v[150:153], v[90:93], v[182:185], v[150:153]
	v_mfma_f32_16x16x32_bf16 v[134:137], v[78:81], v[190:193], v[134:137]
	v_mfma_f32_16x16x32_bf16 v[130:133], v[90:93], v[190:193], v[130:133]
	v_mfma_f32_16x16x32_bf16 v[74:77], v[102:105], v[86:89], v[74:77]
	v_mfma_f32_16x16x32_bf16 v[70:73], v[126:129], v[86:89], v[70:73]
	v_mfma_f32_16x16x32_bf16 v[62:65], v[102:105], v[146:149], v[62:65]
	v_mfma_f32_16x16x32_bf16 v[58:61], v[126:129], v[146:149], v[58:61]
	v_mfma_f32_16x16x32_bf16 v[50:53], v[102:105], v[170:173], v[50:53]
	v_mfma_f32_16x16x32_bf16 v[46:49], v[126:129], v[170:173], v[46:49]
	v_mfma_f32_16x16x32_bf16 v[38:41], v[102:105], v[186:189], v[38:41]
	v_mfma_f32_16x16x32_bf16 v[34:37], v[126:129], v[186:189], v[34:37]
	v_mfma_f32_16x16x32_bf16 v[74:77], v[114:117], v[142:145], v[74:77]
	v_mfma_f32_16x16x32_bf16 v[70:73], v[138:141], v[142:145], v[70:73]
	v_mfma_f32_16x16x32_bf16 v[62:65], v[114:117], v[158:161], v[62:65]
	v_mfma_f32_16x16x32_bf16 v[58:61], v[138:141], v[158:161], v[58:61]
	v_mfma_f32_16x16x32_bf16 v[50:53], v[114:117], v[182:185], v[50:53]
	v_mfma_f32_16x16x32_bf16 v[46:49], v[138:141], v[182:185], v[46:49]
	v_mfma_f32_16x16x32_bf16 v[38:41], v[114:117], v[190:193], v[38:41]
	v_mfma_f32_16x16x32_bf16 v[34:37], v[138:141], v[190:193], v[34:37]
	s_setprio 0
	s_barrier
; #define PG8_STAGE(bufoff, gbase, voff) do { _Pragma("unroll") for (int _i = 0; _i < 2; ++_i) \
;         __builtin_amdgcn_global_load_lds((const unsigned*)((const char*)(gbase) + (voff)[_i]), (PG8_LAS unsigned*)(lds + (bufoff) + ldsw + _i * 8192), 16, 0, 0); } while (0)
; #define PG8_LDA(dst, b, h) do { _Pragma("unroll") for (int m = 0; m < 4; ++m) _Pragma("unroll") for (int k = 0; k < 2; ++k) dst[m][k] = *(const PG8_LAS bf16x8*)(lds + PG8_SA(b, h) + aoff + m * 2048 + k * 1024); } while (0)
; #define PG8_MMA(ai, bj, At, Bt) do { __builtin_amdgcn_s_setprio(1); _Pragma("unroll") for (int m = 0; m < 4; ++m) _Pragma("unroll") for (int n = 0; n < 2; ++n) _Pragma("unroll") for (int k = 0; k < 2; ++k) \
;         acc[ai][bj][m][n] = __builtin_amdgcn_mfma_f32_16x16x32_bf16(Bt[n][k], At[m][k], acc[ai][bj][m][n], 0, 0, 0); __builtin_amdgcn_s_setprio(0); } while (0)
; #define PG8_WAIT_V(n) asm volatile("s_waitcnt vmcnt(" #n ")" ::: "memory")
; #define PG8_WAIT_L(n) asm volatile("s_waitcnt lgkmcnt(" #n ")" ::: "memory")
; #define PG8_BAR __builtin_amdgcn_s_barrier()
; #define PG8_SCHED __builtin_amdgcn_sched_barrier(0)
; template <class Epi, class Sched, bool ALIGN_EPI = false, bool SP2 = false>
; __device__ __forceinline__ void gemm_phase(PG8_LAS unsigned char* lds, const Gemm g, const Sched& S, const Epi& E) {
;     ...
;             PG8_LDA(At, 1, 1); PG8_STAGE(PG8_SB(1, 0), b3, voffB); PG8_STAGE(PG8_SB(1, 1), b3 + hstep, voffB); PG8_STAGE(PG8_SA(1, 0), a3, voffA);
;             PG8_WAIT_V(8); PG8_WAIT_L(0); PG8_BAR; PG8_MMA(1, 0, At, B0); PG8_MMA(1, 1, At, B1); PG8_BAR; PG8_SCHED;
	s_add_i32 s50, s66, s55
	v_lshl_add_u64 v[86:87], v[198:199], 0, s[28:29]
	s_mov_b32 m0, s50
	ds_read_b128 v[142:145], v241 offset:49152
	ds_read_b128 v[146:149], v241 offset:50176
	ds_read_b128 v[158:161], v241 offset:51200
	ds_read_b128 v[170:173], v241 offset:52224
	ds_read_b128 v[182:185], v241 offset:53248
	ds_read_b128 v[186:189], v241 offset:54272
	ds_read_b128 v[190:193], v241 offset:55296
	ds_read_b128 v[194:197], v241 offset:56320
	global_load_lds_dwordx4 v[86:87], off
	s_add_i32 m0, s50, 0x2000
	s_add_u32 s24, s24, 0x20080
	v_lshl_add_u64 v[86:87], v[200:201], 0, s[28:29]
	s_addc_u32 s25, s25, 0
	s_add_i32 s50, s67, s55
	global_load_lds_dwordx4 v[86:87], off
	v_lshl_add_u64 v[86:87], s[24:25], 0, v[0:1]
	s_mov_b32 m0, s50
	s_nop 0
	global_load_lds_dwordx4 v[86:87], off
	v_lshl_add_u64 v[86:87], s[24:25], 0, v[206:207]
	s_add_i32 m0, s50, 0x2000
	s_nop 0
	global_load_lds_dwordx4 v[86:87], off
	v_lshl_add_u64 v[86:87], v[216:217], 0, s[28:29]
	s_mov_b32 m0, s61
	s_nop 0
	global_load_lds_dwordx4 v[86:87], off
	v_lshl_add_u64 v[86:87], v[218:219], 0, s[28:29]
	s_mov_b32 m0, s62
	s_nop 0
	global_load_lds_dwordx4 v[86:87], off
	s_waitcnt vmcnt(8)
	s_waitcnt lgkmcnt(0)
	s_barrier
	s_setprio 1
	v_mfma_f32_16x16x32_bf16 v[86:89], v[66:69], v[142:145], v[122:125]
	v_mfma_f32_16x16x32_bf16 v[122:125], v[78:81], v[146:149], v[86:89]
	v_mfma_f32_16x16x32_bf16 v[86:89], v[82:85], v[142:145], v[118:121]
	v_mfma_f32_16x16x32_bf16 v[118:121], v[90:93], v[146:149], v[86:89]
	v_mfma_f32_16x16x32_bf16 v[86:89], v[66:69], v[158:161], v[110:113]
	v_mfma_f32_16x16x32_bf16 v[110:113], v[78:81], v[170:173], v[86:89]
	v_mfma_f32_16x16x32_bf16 v[86:89], v[82:85], v[158:161], v[106:109]
	v_mfma_f32_16x16x32_bf16 v[106:109], v[90:93], v[170:173], v[86:89]
	v_mfma_f32_16x16x32_bf16 v[86:89], v[66:69], v[182:185], v[98:101]
	v_mfma_f32_16x16x32_bf16 v[98:101], v[78:81], v[186:189], v[86:89]
	v_mfma_f32_16x16x32_bf16 v[86:89], v[82:85], v[182:185], v[94:97]
	v_mfma_f32_16x16x32_bf16 v[42:45], v[66:69], v[190:193], v[42:45]
	v_mfma_f32_16x16x32_bf16 v[94:97], v[90:93], v[186:189], v[86:89]
	v_mfma_f32_16x16x32_bf16 v[86:89], v[78:81], v[194:197], v[42:45]
	v_mfma_f32_16x16x32_bf16 v[42:45], v[82:85], v[190:193], v[54:57]
	v_mfma_f32_16x16x32_bf16 v[82:85], v[90:93], v[194:197], v[42:45]
	v_mfma_f32_16x16x32_bf16 v[30:33], v[102:105], v[142:145], v[30:33]
	v_mfma_f32_16x16x32_bf16 v[26:29], v[126:129], v[142:145], v[26:29]
	v_mfma_f32_16x16x32_bf16 v[22:25], v[102:105], v[158:161], v[22:25]
	v_mfma_f32_16x16x32_bf16 v[18:21], v[126:129], v[158:161], v[18:21]
	v_mfma_f32_16x16x32_bf16 v[14:17], v[102:105], v[182:185], v[14:17]
	v_mfma_f32_16x16x32_bf16 v[10:13], v[126:129], v[182:185], v[10:13]
	v_mfma_f32_16x16x32_bf16 v[6:9], v[102:105], v[190:193], v[6:9]
	v_mfma_f32_16x16x32_bf16 v[2:5], v[126:129], v[190:193], v[2:5]
	v_mfma_f32_16x16x32_bf16 v[30:33], v[114:117], v[146:149], v[30:33]
	v_mfma_f32_16x16x32_bf16 v[26:29], v[138:141], v[146:149], v[26:29]
	v_mfma_f32_16x16x32_bf16 v[22:25], v[114:117], v[170:173], v[22:25]
	v_mfma_f32_16x16x32_bf16 v[18:21], v[138:141], v[170:173], v[18:21]
	v_mfma_f32_16x16x32_bf16 v[14:17], v[114:117], v[186:189], v[14:17]
	v_mfma_f32_16x16x32_bf16 v[10:13], v[138:141], v[186:189], v[10:13]
	v_mfma_f32_16x16x32_bf16 v[6:9], v[114:117], v[194:197], v[6:9]
	v_mfma_f32_16x16x32_bf16 v[2:5], v[138:141], v[194:197], v[2:5]
	s_setprio 0
	s_barrier
	s_add_i32 s65, s65, 2
	s_add_u32 s2, s2, 0x100
	s_addc_u32 s3, s3, 0
	s_add_u32 s23, s23, 0x100
	s_addc_u32 s35, s35, 0
	s_cmp_gt_u32 s65, 5

; #define LAS __attribute__((address_space(3)))
; #define CFENCE() asm volatile("" ::: "memory")
; #define MFMA32(a, b, c) __builtin_amdgcn_mfma_f32_32x32x16_bf16((a), (b), (c), 0, 0, 0)
; __device__ __forceinline__ unsigned cvtpk_s(float lo, float hi) { f32x2_t v = {lo, hi}; bf16x2_t r = __builtin_convertvector(v, bf16x2_t); return __builtin_bit_cast(unsigned, r); }
; template <int DIR> __device__ __forceinline__ void s5_task2(const PP P, int sA, int sB, int g, LAS unsigned char* wl, int lane) {
;     ...
;         for (int k = 0; k < 4; ++k) {
;         const int blk = blk4 + k;
;         const int tb = dir ? (nblk - 1 - blk) * 16 : blk * 16;
;         const bf16x8 ucur = ucur4[k];
;         f32x16 bu0 = {}, bu1 = {}, bu2 = {}, bu3 = {};
;         bu0 = MFMA32(ucur, bfr[0], bu0); bu1 = MFMA32(ucur, bfr[1], bu1); bu2 = MFMA32(ucur, bfr[2], bu2); bu3 = MFMA32(ucur, bfr[3], bu3);
; #pragma unroll
;         for (int i = 0; i < 16; ++i) {
;             const float n0r = fmaf(are[0], sre0, fmaf(-aim[0], sim0, bu0[i])), n0i = fmaf(are[0], sim0, fmaf(aim[0], sre0, bu1[i]));
;             sre0 = n0r; sim0 = n0i;
;             asm volatile("" : "+v"(sre0), "+v"(sim0));
;             const float n1r = fmaf(are[1], sre1, fmaf(-aim[1], sim1, bu2[i])), n1i = fmaf(are[1], sim1, fmaf(aim[1], sre1, bu3[i]));
;             sre1 = n1r; sim1 = n1i;
;             asm volatile("" : "+v"(sre1), "+v"(sim1));
;             const int tau = dir ? 15 - i : i;
;             u32x2 w; w.x = cvtpk_s(sre0, sim0); w.y = cvtpk_s(sre1, sim1);
;             *(LAS u32x2*)(sst + tau * SST_PITCH + pl * 8) = w;
;         }
;         CFENCE();
; #pragma unroll
;         for (int sq = 0; sq < 2; ++sq) {
;             f32x4 acc = {0.f, 0.f, 0.f, 0.f};
; #pragma unroll
;             for (int kb = 0; kb < 4; ++kb) {
;                 const bf16x8 a = *(const LAS bf16x8*)(wl + sq * SST_BYTES + cc * SST_PITCH + (kb * 32 + q * 8) * 2);
;                 acc = __builtin_amdgcn_mfma_f32_16x16x32_bf16(cf[kb], a, acc, 0, 0, 0);
.LBB0_259:
	v_mfma_f32_32x32x16_bf16 v[68:83], v[24:27], v[98:101], 0
	s_xor_b32 s3, s8, 0xffffffe
	s_add_i32 s3, s3, s4
	s_lshl_b32 s3, s3, 4
	s_ashr_i32 s5, s3, 31
	s_mov_b32 s6, 0xfffd0000
	s_mov_b32 s7, -1
	v_lshl_add_u64 v[182:183], v[182:183], 0, s[6:7]
	v_mfma_f32_32x32x16_bf16 v[50:65], v[24:27], v[102:105], 0
	s_nop 3
	v_fma_f32 v0, -v174, v33, v68
	v_fmac_f32_e32 v0, v196, v28
	s_and_b64 vcc, exec, s[0:1]
	v_mfma_f32_32x32x16_bf16 v[2:17], v[24:27], v[106:109], 0
	v_mfma_f32_32x32x16_bf16 v[34:49], v[24:27], v[110:113], 0
	s_nop 2
	v_fma_f32 v24, v174, v28, v50
	s_nop 6
	v_fma_f32 v2, -v176, v67, v2
	v_fmac_f32_e32 v24, v196, v33
	v_fmac_f32_e32 v2, v175, v18
	v_fma_f32 v25, v176, v18, v34
	v_fmac_f32_e32 v25, v175, v67
	v_cvt_pk_bf16_f32 v18, v0, v24
	v_cvt_pk_bf16_f32 v19, v2, v25
	ds_write_b64 v192, v[18:19] offset:4080
	v_fma_f32 v18, -v174, v24, v69
	v_fmac_f32_e32 v18, v196, v0
	v_fma_f32 v0, v174, v0, v51
	v_fmac_f32_e32 v0, v196, v24
	v_fma_f32 v24, v176, v2, v35
	v_fma_f32 v19, -v176, v25, v3
	v_fmac_f32_e32 v24, v175, v25
	v_fma_f32 v25, -v174, v0, v70
	v_fmac_f32_e32 v19, v175, v2
	v_cvt_pk_bf16_f32 v2, v18, v0
	v_fmac_f32_e32 v25, v196, v18
	v_fma_f32 v18, v174, v18, v52
	v_fmac_f32_e32 v18, v196, v0
	v_fma_f32 v0, -v176, v24, v4
	v_fma_f32 v4, v176, v19, v36
	v_cvt_pk_bf16_f32 v3, v19, v24
	v_fmac_f32_e32 v0, v175, v19
	v_fmac_f32_e32 v4, v175, v24
	ds_write_b64 v192, v[2:3] offset:3808
	s_nop 0
	v_fma_f32 v5, -v176, v4, v5
	v_cvt_pk_bf16_f32 v3, v0, v4
	v_fma_f32 v19, -v174, v18, v71
	v_fma_f32 v24, v174, v25, v53
	v_fmac_f32_e32 v5, v175, v0
	v_fma_f32 v0, v176, v0, v37
	v_cvt_pk_bf16_f32 v2, v25, v18
	v_fmac_f32_e32 v19, v196, v25
	v_fmac_f32_e32 v24, v196, v18
	v_fmac_f32_e32 v0, v175, v4
	ds_write_b64 v192, v[2:3] offset:3536
	s_nop 0
	v_fma_f32 v4, -v174, v24, v72
	v_fma_f32 v18, v174, v19, v54
	v_fma_f32 v6, -v176, v0, v6
	v_cvt_pk_bf16_f32 v2, v19, v24
	v_cvt_pk_bf16_f32 v3, v5, v0
	v_fmac_f32_e32 v4, v196, v19
	v_fmac_f32_e32 v18, v196, v24
	v_fmac_f32_e32 v6, v175, v5
	v_fma_f32 v5, v176, v5, v38
	ds_write_b64 v192, v[2:3] offset:3264
	v_fmac_f32_e32 v5, v175, v0
	v_fma_f32 v0, -v174, v18, v73
	v_cvt_pk_bf16_f32 v2, v4, v18
	v_fmac_f32_e32 v0, v196, v4
	v_fma_f32 v4, v174, v4, v55
	v_fma_f32 v7, -v176, v5, v7
	v_cvt_pk_bf16_f32 v3, v6, v5
	v_fmac_f32_e32 v4, v196, v18
	v_fmac_f32_e32 v7, v175, v6
	v_fma_f32 v6, v176, v6, v39
	ds_write_b64 v192, v[2:3] offset:2992
	v_fmac_f32_e32 v6, v175, v5
	v_fma_f32 v5, -v174, v4, v74
	v_cvt_pk_bf16_f32 v2, v0, v4
	v_fmac_f32_e32 v5, v196, v0
	v_fma_f32 v0, v174, v0, v56
	v_fmac_f32_e32 v0, v196, v4
	v_fma_f32 v4, -v176, v6, v8
	v_cvt_pk_bf16_f32 v3, v7, v6
	v_fmac_f32_e32 v4, v175, v7
	v_fma_f32 v7, v176, v7, v40
	ds_write_b64 v192, v[2:3] offset:2720
	v_fmac_f32_e32 v7, v175, v6
	v_fma_f32 v6, -v174, v0, v75
	v_cvt_pk_bf16_f32 v2, v5, v0
	v_fmac_f32_e32 v6, v196, v5
	v_fma_f32 v5, v174, v5, v57
	v_fmac_f32_e32 v5, v196, v0
	v_fma_f32 v0, -v176, v7, v9
	v_cvt_pk_bf16_f32 v3, v4, v7
	v_fmac_f32_e32 v0, v175, v4
	v_fma_f32 v4, v176, v4, v41
	ds_write_b64 v192, v[2:3] offset:2448
	v_fmac_f32_e32 v4, v175, v7
	v_fma_f32 v7, -v174, v5, v76
	v_cvt_pk_bf16_f32 v2, v6, v5
	v_fmac_f32_e32 v7, v196, v6
	v_fma_f32 v6, v174, v6, v58
	v_fmac_f32_e32 v6, v196, v5
	v_fma_f32 v5, -v176, v4, v10
	v_cvt_pk_bf16_f32 v3, v0, v4
	v_fmac_f32_e32 v5, v175, v0
	v_fma_f32 v0, v176, v0, v42
	ds_write_b64 v192, v[2:3] offset:2176
	v_fmac_f32_e32 v0, v175, v4
	v_fma_f32 v4, -v174, v6, v77
	v_cvt_pk_bf16_f32 v2, v7, v6
	v_fmac_f32_e32 v4, v196, v7
	v_fma_f32 v7, v174, v7, v59
	v_fmac_f32_e32 v7, v196, v6
	v_fma_f32 v6, -v176, v0, v11
	v_cvt_pk_bf16_f32 v3, v5, v0
	v_fmac_f32_e32 v6, v175, v5
	v_fma_f32 v5, v176, v5, v43
	ds_write_b64 v192, v[2:3] offset:1904
	v_fmac_f32_e32 v5, v175, v0
	v_fma_f32 v0, -v174, v7, v78
	v_cvt_pk_bf16_f32 v2, v4, v7
	v_fmac_f32_e32 v0, v196, v4
	v_fma_f32 v4, v174, v4, v60
	v_fmac_f32_e32 v4, v196, v7
	v_fma_f32 v7, -v176, v5, v12
	v_cvt_pk_bf16_f32 v3, v6, v5
	v_fmac_f32_e32 v7, v175, v6
	v_fma_f32 v6, v176, v6, v44
	ds_write_b64 v192, v[2:3] offset:1632
	v_fmac_f32_e32 v6, v175, v5
	v_fma_f32 v5, -v174, v4, v79
	v_cvt_pk_bf16_f32 v2, v0, v4
	v_fmac_f32_e32 v5, v196, v0
	v_fma_f32 v0, v174, v0, v61
	v_fmac_f32_e32 v0, v196, v4
	v_fma_f32 v4, -v176, v6, v13
	v_cvt_pk_bf16_f32 v3, v7, v6
	v_fmac_f32_e32 v4, v175, v7
	v_fma_f32 v7, v176, v7, v45
	ds_write_b64 v192, v[2:3] offset:1360
	v_fmac_f32_e32 v7, v175, v6
	v_fma_f32 v6, -v174, v0, v80
	v_cvt_pk_bf16_f32 v2, v5, v0
	v_fmac_f32_e32 v6, v196, v5
	v_fma_f32 v5, v174, v5, v62
	v_fmac_f32_e32 v5, v196, v0
	v_fma_f32 v0, -v176, v7, v14
	v_cvt_pk_bf16_f32 v3, v4, v7
	v_fmac_f32_e32 v0, v175, v4
	v_fma_f32 v4, v176, v4, v46
	ds_write_b64 v192, v[2:3] offset:1088
	v_fmac_f32_e32 v4, v175, v7
	v_fma_f32 v7, -v174, v5, v81
	v_cvt_pk_bf16_f32 v2, v6, v5
	v_fmac_f32_e32 v7, v196, v6
	v_fma_f32 v6, v174, v6, v63
	v_fmac_f32_e32 v6, v196, v5
	v_fma_f32 v5, -v176, v4, v15
	v_cvt_pk_bf16_f32 v3, v0, v4
	v_fmac_f32_e32 v5, v175, v0
	v_fma_f32 v0, v176, v0, v47
	ds_write_b64 v192, v[2:3] offset:816
	v_fmac_f32_e32 v0, v175, v4
	v_fma_f32 v4, -v174, v6, v82
	v_cvt_pk_bf16_f32 v2, v7, v6
	v_fmac_f32_e32 v4, v196, v7
	v_fma_f32 v7, v174, v7, v64
	v_fmac_f32_e32 v7, v196, v6
	v_fma_f32 v6, -v176, v0, v16
	v_cvt_pk_bf16_f32 v3, v5, v0
	v_fmac_f32_e32 v6, v175, v5
	v_fma_f32 v5, v176, v5, v48
	v_fmac_f32_e32 v5, v175, v0
	ds_write_b64 v192, v[2:3] offset:544
	v_add_u32_e32 v0, v193, v194
	v_fma_f32 v36, -v174, v7, v83
	v_fmac_f32_e32 v65, v174, v4
	v_fma_f32 v37, -v176, v5, v17
	v_fmac_f32_e32 v49, v176, v6
	v_cvt_pk_bf16_f32 v2, v4, v7
	v_cvt_pk_bf16_f32 v3, v6, v5
	v_fmac_f32_e32 v36, v196, v4
	v_fmac_f32_e32 v65, v196, v7
	v_fmac_f32_e32 v37, v175, v6
	v_fmac_f32_e32 v49, v175, v5
	ds_write_b64 v192, v[2:3] offset:272
	v_mfma_f32_32x32x16_bf16 v[66:81], v[20:23], v[98:101], 0
	v_cvt_pk_bf16_f32 v2, v36, v65
	v_cvt_pk_bf16_f32 v3, v37, v49
	ds_write_b64 v192, v[2:3]
	ds_read_b128 v[2:5], v0
	ds_read_b128 v[6:9], v0 offset:64
	ds_read_b128 v[206:209], v0 offset:128
	ds_read_b128 v[210:213], v0 offset:192
	s_nop 6
	v_fma_f32 v38, -v174, v65, v66
	s_waitcnt lgkmcnt(3)
; #define LAS __attribute__((address_space(3)))
; #define CFENCE() asm volatile("" ::: "memory")
; #define MFMA32(a, b, c) __builtin_amdgcn_mfma_f32_32x32x16_bf16((a), (b), (c), 0, 0, 0)
; __device__ __forceinline__ unsigned cvtpk_s(float lo, float hi) { f32x2_t v = {lo, hi}; bf16x2_t r = __builtin_convertvector(v, bf16x2_t); return __builtin_bit_cast(unsigned, r); }
; template <int DIR> __device__ __forceinline__ void s5_task2(const PP P, int sA, int sB, int g, LAS unsigned char* wl, int lane) {
;     ...
;         bu0 = MFMA32(ucur, bfr[0], bu0); bu1 = MFMA32(ucur, bfr[1], bu1); bu2 = MFMA32(ucur, bfr[2], bu2); bu3 = MFMA32(ucur, bfr[3], bu3);
; #pragma unroll
;         for (int i = 0; i < 16; ++i) {
;             const float n0r = fmaf(are[0], sre0, fmaf(-aim[0], sim0, bu0[i])), n0i = fmaf(are[0], sim0, fmaf(aim[0], sre0, bu1[i]));
;             sre0 = n0r; sim0 = n0i;
;             asm volatile("" : "+v"(sre0), "+v"(sim0));
;             const float n1r = fmaf(are[1], sre1, fmaf(-aim[1], sim1, bu2[i])), n1i = fmaf(are[1], sim1, fmaf(aim[1], sre1, bu3[i]));
;             sre1 = n1r; sim1 = n1i;
;             asm volatile("" : "+v"(sre1), "+v"(sim1));
;             const int tau = dir ? 15 - i : i;
;             u32x2 w; w.x = cvtpk_s(sre0, sim0); w.y = cvtpk_s(sre1, sim1);
;             *(LAS u32x2*)(sst + tau * SST_PITCH + pl * 8) = w;
;         }
;         CFENCE();
; #pragma unroll
;         for (int sq = 0; sq < 2; ++sq) {
;             f32x4 acc = {0.f, 0.f, 0.f, 0.f};
; #pragma unroll
;             for (int kb = 0; kb < 4; ++kb) {
;                 const bf16x8 a = *(const LAS bf16x8*)(wl + sq * SST_BYTES + cc * SST_PITCH + (kb * 32 + q * 8) * 2);
;                 acc = __builtin_amdgcn_mfma_f32_16x16x32_bf16(cf[kb], a, acc, 0, 0, 0);
;             }
;             bf16_t* yp = Y + ((sq ? rowB : rowA) + tb + cc) * 512 + g * 16 + q * 4;
;             u32x2 yw; yw.x = cvtpk_s(acc[0], acc[1]); yw.y = cvtpk_s(acc[2], acc[3]);
;             *(u32x2*)yp = yw;
;         }
	v_mfma_f32_16x16x32_bf16 v[2:5], v[114:117], v[2:5], 0
	v_fmac_f32_e32 v38, v196, v36
	s_waitcnt lgkmcnt(2)
	v_mfma_f32_16x16x32_bf16 v[2:5], v[118:121], v[6:9], v[2:5]
	s_waitcnt lgkmcnt(1)
	v_mfma_f32_16x16x32_bf16 v[2:5], v[122:125], v[206:209], v[2:5]
	s_waitcnt lgkmcnt(0)
	v_mfma_f32_16x16x32_bf16 v[2:5], v[126:129], v[210:213], v[2:5]
	ds_read_b128 v[6:9], v0 offset:4416
	v_mfma_f32_32x32x16_bf16 v[82:97], v[20:23], v[106:109], 0
	s_nop 5
	v_cvt_pk_bf16_f32 v2, v2, v3
	v_cvt_pk_bf16_f32 v3, v4, v5
	global_store_dwordx2 v[186:187], v[2:3], off
	ds_read_b128 v[2:5], v0 offset:4352
	ds_read_b128 v[214:217], v0 offset:4480
	ds_read_b128 v[218:221], v0 offset:4544
	v_lshl_add_u64 v[186:187], v[186:187], 0, s[68:69]
	s_waitcnt lgkmcnt(2)
	v_mfma_f32_16x16x32_bf16 v[2:5], v[114:117], v[2:5], 0
	s_waitcnt lgkmcnt(3)
	v_mfma_f32_16x16x32_bf16 v[2:5], v[118:121], v[6:9], v[2:5]
	s_waitcnt lgkmcnt(1)
	v_mfma_f32_16x16x32_bf16 v[2:5], v[122:125], v[214:217], v[2:5]
	s_waitcnt lgkmcnt(0)
	v_mfma_f32_16x16x32_bf16 v[2:5], v[126:129], v[218:221], v[2:5]
	s_nop 7
	v_cvt_pk_bf16_f32 v2, v2, v3
	v_cvt_pk_bf16_f32 v3, v4, v5
	v_mfma_f32_32x32x16_bf16 v[4:19], v[20:23], v[102:105], 0
	global_store_dwordx2 v[184:185], v[2:3], off
	v_lshl_add_u64 v[184:185], v[184:185], 0, s[68:69]
	v_mfma_f32_32x32x16_bf16 v[20:35], v[20:23], v[110:113], 0
	s_nop 8
	v_fma_f32 v4, v174, v36, v4
	v_fmac_f32_e32 v4, v196, v65
	v_fma_f32 v36, -v176, v49, v82
	v_fmac_f32_e32 v36, v175, v37
	v_fma_f32 v5, v174, v38, v5
	v_cvt_pk_bf16_f32 v2, v38, v4
	v_fma_f32 v20, v176, v37, v20
	v_fmac_f32_e32 v20, v175, v49
	v_fma_f32 v37, -v174, v4, v67
	v_fmac_f32_e32 v37, v196, v38
	v_cvt_pk_bf16_f32 v3, v36, v20
	v_fmac_f32_e32 v5, v196, v4
	v_fma_f32 v4, -v176, v20, v83
	v_fma_f32 v21, v176, v36, v21
	ds_write_b64 v192, v[2:3] offset:4080
	v_fmac_f32_e32 v4, v175, v36
	v_fmac_f32_e32 v21, v175, v20
	v_fma_f32 v6, v174, v37, v6
	v_cvt_pk_bf16_f32 v2, v37, v5
	v_fma_f32 v20, -v174, v5, v68
	v_fmac_f32_e32 v6, v196, v5
	v_fma_f32 v5, -v176, v21, v84
	v_cvt_pk_bf16_f32 v3, v4, v21
	v_fmac_f32_e32 v20, v196, v37
	v_fmac_f32_e32 v5, v175, v4
	v_fma_f32 v4, v176, v4, v22
	ds_write_b64 v192, v[2:3] offset:3808
	v_fmac_f32_e32 v4, v175, v21
	v_fma_f32 v7, v174, v20, v7
	v_cvt_pk_bf16_f32 v2, v20, v6
	v_fma_f32 v21, -v174, v6, v69
	v_fmac_f32_e32 v7, v196, v6
	v_fma_f32 v6, -v176, v4, v85
	v_cvt_pk_bf16_f32 v3, v5, v4
	v_fmac_f32_e32 v21, v196, v20
	v_fmac_f32_e32 v6, v175, v5
	v_fma_f32 v5, v176, v5, v23
	ds_write_b64 v192, v[2:3] offset:3536
	v_fmac_f32_e32 v5, v175, v4
	v_fma_f32 v8, v174, v21, v8
	v_cvt_pk_bf16_f32 v2, v21, v7
	v_fma_f32 v4, -v174, v7, v70
	v_fmac_f32_e32 v8, v196, v7
	v_fma_f32 v7, -v176, v5, v86
	v_cvt_pk_bf16_f32 v3, v6, v5
	v_fmac_f32_e32 v4, v196, v21
	v_fmac_f32_e32 v7, v175, v6
	v_fma_f32 v6, v176, v6, v24
	ds_write_b64 v192, v[2:3] offset:3264
	v_fmac_f32_e32 v6, v175, v5
	v_fma_f32 v5, -v174, v8, v71
	v_cvt_pk_bf16_f32 v2, v4, v8
	v_fmac_f32_e32 v5, v196, v4
	v_fma_f32 v4, v174, v4, v9
	v_fmac_f32_e32 v4, v196, v8
	v_fma_f32 v8, -v176, v6, v87
	v_cvt_pk_bf16_f32 v3, v7, v6
	v_fmac_f32_e32 v8, v175, v7
	v_fma_f32 v7, v176, v7, v25
	ds_write_b64 v192, v[2:3] offset:2992
	v_fmac_f32_e32 v7, v175, v6
	v_fma_f32 v6, -v174, v4, v72
	v_cvt_pk_bf16_f32 v2, v5, v4
	v_fmac_f32_e32 v6, v196, v5
	v_fma_f32 v5, v174, v5, v10
	v_fmac_f32_e32 v5, v196, v4
	v_fma_f32 v4, -v176, v7, v88
	v_cvt_pk_bf16_f32 v3, v8, v7
	v_fmac_f32_e32 v4, v175, v8
	v_fma_f32 v8, v176, v8, v26
	ds_write_b64 v192, v[2:3] offset:2720
	v_fmac_f32_e32 v8, v175, v7
	v_fma_f32 v7, -v174, v5, v73
	v_cvt_pk_bf16_f32 v2, v6, v5
	v_fmac_f32_e32 v7, v196, v6
	v_fma_f32 v6, v174, v6, v11
	v_fmac_f32_e32 v6, v196, v5
	v_fma_f32 v5, -v176, v8, v89
	v_cvt_pk_bf16_f32 v3, v4, v8
	v_fmac_f32_e32 v5, v175, v4
	v_fma_f32 v4, v176, v4, v27
	ds_write_b64 v192, v[2:3] offset:2448
	v_fmac_f32_e32 v4, v175, v8
	v_fma_f32 v8, -v174, v6, v74
	v_cvt_pk_bf16_f32 v2, v7, v6
	v_fmac_f32_e32 v8, v196, v7
	v_fma_f32 v7, v174, v7, v12
	v_fmac_f32_e32 v7, v196, v6
	v_fma_f32 v6, -v176, v4, v90
	v_cvt_pk_bf16_f32 v3, v5, v4
	v_fmac_f32_e32 v6, v175, v5
	v_fma_f32 v5, v176, v5, v28
	ds_write_b64 v192, v[2:3] offset:2176
	v_fmac_f32_e32 v5, v175, v4
	v_fma_f32 v4, -v174, v7, v75
	v_cvt_pk_bf16_f32 v2, v8, v7
	v_fmac_f32_e32 v4, v196, v8
	v_fma_f32 v8, v174, v8, v13
	v_fmac_f32_e32 v8, v196, v7
	v_fma_f32 v7, -v176, v5, v91
	v_cvt_pk_bf16_f32 v3, v6, v5
	v_fmac_f32_e32 v7, v175, v6
	v_fma_f32 v6, v176, v6, v29
	ds_write_b64 v192, v[2:3] offset:1904
	v_fmac_f32_e32 v6, v175, v5
	v_fma_f32 v5, -v174, v8, v76
	v_cvt_pk_bf16_f32 v2, v4, v8
	v_fmac_f32_e32 v5, v196, v4
	v_fma_f32 v4, v174, v4, v14
	v_fmac_f32_e32 v4, v196, v8
	v_fma_f32 v8, -v176, v6, v92
	v_cvt_pk_bf16_f32 v3, v7, v6
	v_fmac_f32_e32 v8, v175, v7
	v_fma_f32 v7, v176, v7, v30
	ds_write_b64 v192, v[2:3] offset:1632
	v_fmac_f32_e32 v7, v175, v6
	v_fma_f32 v6, -v174, v4, v77
	v_cvt_pk_bf16_f32 v2, v5, v4
	v_fmac_f32_e32 v6, v196, v5
	v_fma_f32 v5, v174, v5, v15
	v_fmac_f32_e32 v5, v196, v4
	v_fma_f32 v4, -v176, v7, v93
	v_cvt_pk_bf16_f32 v3, v8, v7
	v_fmac_f32_e32 v4, v175, v8
	v_fma_f32 v8, v176, v8, v31
	ds_write_b64 v192, v[2:3] offset:1360
	v_fmac_f32_e32 v8, v175, v7
	v_fma_f32 v7, -v174, v5, v78
	v_cvt_pk_bf16_f32 v2, v6, v5
	v_fmac_f32_e32 v7, v196, v6
	v_fma_f32 v6, v174, v6, v16
	v_fmac_f32_e32 v6, v196, v5
	v_fma_f32 v5, -v176, v8, v94
	v_cvt_pk_bf16_f32 v3, v4, v8
	v_fmac_f32_e32 v5, v175, v4
	v_fma_f32 v4, v176, v4, v32
	ds_write_b64 v192, v[2:3] offset:1088
	v_fmac_f32_e32 v4, v175, v8
	v_fma_f32 v8, -v174, v6, v79
	v_cvt_pk_bf16_f32 v2, v7, v6
	v_fmac_f32_e32 v8, v196, v7
	v_fma_f32 v7, v174, v7, v17
	v_fmac_f32_e32 v7, v196, v6
	v_fma_f32 v6, -v176, v4, v95
	v_cvt_pk_bf16_f32 v3, v5, v4
	v_fmac_f32_e32 v6, v175, v5
	v_fma_f32 v5, v176, v5, v33
	ds_write_b64 v192, v[2:3] offset:816
	v_fmac_f32_e32 v5, v175, v4
	v_fma_f32 v4, -v174, v7, v80
	v_cvt_pk_bf16_f32 v2, v8, v7
	v_fmac_f32_e32 v4, v196, v8
	v_fma_f32 v8, v174, v8, v18
	v_fmac_f32_e32 v8, v196, v7
	v_fma_f32 v7, -v176, v5, v96
	v_cvt_pk_bf16_f32 v3, v6, v5
	v_fmac_f32_e32 v7, v175, v6
	v_fma_f32 v6, v176, v6, v34
	v_fmac_f32_e32 v6, v175, v5
	ds_write_b64 v192, v[2:3] offset:544
	v_mov_b32_e32 v11, s5
	v_fma_f32 v18, -v174, v8, v81
	v_fmac_f32_e32 v19, v174, v4
	v_fma_f32 v20, -v176, v6, v97
	v_fmac_f32_e32 v35, v176, v7
	v_cvt_pk_bf16_f32 v2, v4, v8
	v_cvt_pk_bf16_f32 v3, v7, v6
	v_fmac_f32_e32 v18, v196, v4
	v_fmac_f32_e32 v19, v196, v8
	v_fmac_f32_e32 v20, v175, v7
	v_fmac_f32_e32 v35, v175, v6
	ds_write_b64 v192, v[2:3] offset:272
	v_or_b32_e32 v10, s3, v156
	v_cvt_pk_bf16_f32 v2, v18, v19
	v_cvt_pk_bf16_f32 v3, v20, v35
	ds_write_b64 v192, v[2:3]
	ds_read_b128 v[2:5], v0
	ds_read_b128 v[6:9], v0 offset:64
	ds_read_b128 v[206:209], v0 offset:128
	ds_read_b128 v[210:213], v0 offset:192
	s_waitcnt lgkmcnt(3)
; #define LAS __attribute__((address_space(3)))
; #define CFENCE() asm volatile("" ::: "memory")
; #define MFMA32(a, b, c) __builtin_amdgcn_mfma_f32_32x32x16_bf16((a), (b), (c), 0, 0, 0)
; __device__ __forceinline__ unsigned cvtpk_s(float lo, float hi) { f32x2_t v = {lo, hi}; bf16x2_t r = __builtin_convertvector(v, bf16x2_t); return __builtin_bit_cast(unsigned, r); }
; template <int DIR> __device__ __forceinline__ void s5_task2(const PP P, int sA, int sB, int g, LAS unsigned char* wl, int lane) {
;     ...
;         bu0 = MFMA32(ucur, bfr[0], bu0); bu1 = MFMA32(ucur, bfr[1], bu1); bu2 = MFMA32(ucur, bfr[2], bu2); bu3 = MFMA32(ucur, bfr[3], bu3);
; #pragma unroll
;         for (int i = 0; i < 16; ++i) {
;             const float n0r = fmaf(are[0], sre0, fmaf(-aim[0], sim0, bu0[i])), n0i = fmaf(are[0], sim0, fmaf(aim[0], sre0, bu1[i]));
;             sre0 = n0r; sim0 = n0i;
;             asm volatile("" : "+v"(sre0), "+v"(sim0));
;             const float n1r = fmaf(are[1], sre1, fmaf(-aim[1], sim1, bu2[i])), n1i = fmaf(are[1], sim1, fmaf(aim[1], sre1, bu3[i]));
;             sre1 = n1r; sim1 = n1i;
;             asm volatile("" : "+v"(sre1), "+v"(sim1));
;             const int tau = dir ? 15 - i : i;
;             u32x2 w; w.x = cvtpk_s(sre0, sim0); w.y = cvtpk_s(sre1, sim1);
;             *(LAS u32x2*)(sst + tau * SST_PITCH + pl * 8) = w;
;         }
;         CFENCE();
; #pragma unroll
;         for (int sq = 0; sq < 2; ++sq) {
;             f32x4 acc = {0.f, 0.f, 0.f, 0.f};
; #pragma unroll
;             for (int kb = 0; kb < 4; ++kb) {
;                 const bf16x8 a = *(const LAS bf16x8*)(wl + sq * SST_BYTES + cc * SST_PITCH + (kb * 32 + q * 8) * 2);
;                 acc = __builtin_amdgcn_mfma_f32_16x16x32_bf16(cf[kb], a, acc, 0, 0, 0);
;             }
;             bf16_t* yp = Y + ((sq ? rowB : rowA) + tb + cc) * 512 + g * 16 + q * 4;
;             u32x2 yw; yw.x = cvtpk_s(acc[0], acc[1]); yw.y = cvtpk_s(acc[2], acc[3]);
;             *(u32x2*)yp = yw;
;         }
	v_mfma_f32_16x16x32_bf16 v[2:5], v[114:117], v[2:5], 0
	s_xor_b32 s3, s8, 0xffffffd
	s_add_i32 s3, s3, s4
	s_lshl_b32 s3, s3, 4
	s_waitcnt lgkmcnt(2)
	v_mfma_f32_16x16x32_bf16 v[2:5], v[118:121], v[6:9], v[2:5]
	s_ashr_i32 s5, s3, 31
	s_waitcnt lgkmcnt(1)
	v_mfma_f32_16x16x32_bf16 v[2:5], v[122:125], v[206:209], v[2:5]
	s_waitcnt lgkmcnt(0)
	v_mfma_f32_16x16x32_bf16 v[2:5], v[126:129], v[210:213], v[2:5]
	v_lshl_add_u64 v[6:7], v[10:11], 0, s[64:65]
	v_lshlrev_b64 v[6:7], 10, v[6:7]
	v_lshl_add_u64 v[6:7], v[180:181], 0, v[6:7]
	s_nop 4
	v_cvt_pk_bf16_f32 v2, v2, v3
	v_cvt_pk_bf16_f32 v3, v4, v5
	global_store_dwordx2 v[6:7], v[2:3], off
	ds_read_b128 v[2:5], v0 offset:4352
	ds_read_b128 v[6:9], v0 offset:4416
	ds_read_b128 v[214:217], v0 offset:4480
	ds_read_b128 v[218:221], v0 offset:4544
	s_waitcnt lgkmcnt(3)
	v_mfma_f32_16x16x32_bf16 v[2:5], v[114:117], v[2:5], 0
	s_waitcnt lgkmcnt(2)
	v_mfma_f32_16x16x32_bf16 v[2:5], v[118:121], v[6:9], v[2:5]
	s_waitcnt lgkmcnt(1)
	v_mfma_f32_16x16x32_bf16 v[2:5], v[122:125], v[214:217], v[2:5]
	s_waitcnt lgkmcnt(0)
	v_mfma_f32_16x16x32_bf16 v[2:5], v[126:129], v[218:221], v[2:5]
	v_lshl_add_u64 v[6:7], v[10:11], 0, s[66:67]
	v_lshlrev_b64 v[6:7], 10, v[6:7]
	v_lshl_add_u64 v[6:7], v[180:181], 0, v[6:7]
	s_nop 4
	v_cvt_pk_bf16_f32 v2, v2, v3
	v_cvt_pk_bf16_f32 v3, v4, v5
	v_mfma_f32_32x32x16_bf16 v[68:83], v[150:153], v[106:109], 0
	global_store_dwordx2 v[6:7], v[2:3], off
	v_mfma_f32_32x32x16_bf16 v[52:67], v[150:153], v[98:101], 0
	s_nop 9
	v_fma_f32 v22, -v176, v35, v68
	v_fmac_f32_e32 v22, v175, v20
	v_mfma_f32_32x32x16_bf16 v[2:17], v[150:153], v[102:105], 0
	v_fma_f32 v21, -v174, v19, v52
	v_fmac_f32_e32 v21, v196, v18
	v_mfma_f32_32x32x16_bf16 v[36:51], v[150:153], v[110:113], 0
	s_nop 8
	v_fma_f32 v2, v174, v18, v2
	v_fmac_f32_e32 v2, v196, v19
	s_waitcnt vmcnt(5)
	v_mov_b64_e32 v[152:153], v[140:141]
	v_cvt_pk_bf16_f32 v18, v21, v2
	v_mov_b64_e32 v[150:151], v[138:139]
	v_fma_f32 v20, v176, v20, v36
	v_fmac_f32_e32 v20, v175, v35
	s_nop 0
	v_cvt_pk_bf16_f32 v19, v22, v20
	ds_write_b64 v192, v[18:19] offset:4080
	v_fma_f32 v18, -v174, v2, v53
	v_fmac_f32_e32 v18, v196, v21
	v_fma_f32 v19, v174, v21, v3
	v_fma_f32 v21, -v176, v20, v69
	v_fmac_f32_e32 v19, v196, v2
	v_fmac_f32_e32 v21, v175, v22
	v_fma_f32 v22, v176, v22, v37
	v_fmac_f32_e32 v22, v175, v20
	v_fma_f32 v20, -v174, v19, v54
	v_fma_f32 v4, v174, v18, v4
	v_cvt_pk_bf16_f32 v2, v18, v19
	v_cvt_pk_bf16_f32 v3, v21, v22
	v_fmac_f32_e32 v20, v196, v18
	v_fmac_f32_e32 v4, v196, v19
	v_fma_f32 v18, -v176, v22, v70
	v_fma_f32 v19, v176, v21, v38
	ds_write_b64 v192, v[2:3] offset:3808
	v_fmac_f32_e32 v18, v175, v21
	v_fmac_f32_e32 v19, v175, v22
	v_fma_f32 v5, v174, v20, v5
	v_cvt_pk_bf16_f32 v2, v20, v4
	v_fma_f32 v21, -v174, v4, v55
	v_fmac_f32_e32 v5, v196, v4
	v_fma_f32 v4, -v176, v19, v71
	v_cvt_pk_bf16_f32 v3, v18, v19
	v_fmac_f32_e32 v21, v196, v20
	v_fmac_f32_e32 v4, v175, v18
	v_fma_f32 v18, v176, v18, v39
	ds_write_b64 v192, v[2:3] offset:3536
	v_fmac_f32_e32 v18, v175, v19
	v_fma_f32 v6, v174, v21, v6
	v_cvt_pk_bf16_f32 v2, v21, v5
	v_fma_f32 v19, -v174, v5, v56
	v_fmac_f32_e32 v6, v196, v5
	v_fma_f32 v5, -v176, v18, v72
	v_cvt_pk_bf16_f32 v3, v4, v18
	v_fmac_f32_e32 v19, v196, v21
	v_fmac_f32_e32 v5, v175, v4
	v_fma_f32 v4, v176, v4, v40
	ds_write_b64 v192, v[2:3] offset:3264
	v_fmac_f32_e32 v4, v175, v18
	v_fma_f32 v7, v174, v19, v7
	v_cvt_pk_bf16_f32 v2, v19, v6
	v_fma_f32 v18, -v174, v6, v57
	v_fmac_f32_e32 v7, v196, v6
	v_fma_f32 v6, -v176, v4, v73
	v_cvt_pk_bf16_f32 v3, v5, v4
	v_fmac_f32_e32 v18, v196, v19
	v_fmac_f32_e32 v6, v175, v5
	v_fma_f32 v5, v176, v5, v41
	ds_write_b64 v192, v[2:3] offset:2992
	v_fmac_f32_e32 v5, v175, v4
	v_fma_f32 v8, v174, v18, v8
	v_cvt_pk_bf16_f32 v2, v18, v7
	v_fma_f32 v4, -v174, v7, v58
	v_fmac_f32_e32 v8, v196, v7
	v_fma_f32 v7, -v176, v5, v74
	v_cvt_pk_bf16_f32 v3, v6, v5
	v_fmac_f32_e32 v4, v196, v18
	v_fmac_f32_e32 v7, v175, v6
	v_fma_f32 v6, v176, v6, v42
	ds_write_b64 v192, v[2:3] offset:2720
	v_fmac_f32_e32 v6, v175, v5
	v_fma_f32 v5, -v174, v8, v59
	v_cvt_pk_bf16_f32 v2, v4, v8
	v_fmac_f32_e32 v5, v196, v4
	v_fma_f32 v4, v174, v4, v9
	v_fmac_f32_e32 v4, v196, v8
	v_fma_f32 v8, -v176, v6, v75
	v_cvt_pk_bf16_f32 v3, v7, v6
	v_fmac_f32_e32 v8, v175, v7
	v_fma_f32 v7, v176, v7, v43
	ds_write_b64 v192, v[2:3] offset:2448
	v_fmac_f32_e32 v7, v175, v6
	v_fma_f32 v6, -v174, v4, v60
	v_cvt_pk_bf16_f32 v2, v5, v4
	v_fmac_f32_e32 v6, v196, v5
	v_fma_f32 v5, v174, v5, v10
	v_fmac_f32_e32 v5, v196, v4
	v_fma_f32 v4, -v176, v7, v76
	v_cvt_pk_bf16_f32 v3, v8, v7
	v_fmac_f32_e32 v4, v175, v8
	v_fma_f32 v8, v176, v8, v44
	ds_write_b64 v192, v[2:3] offset:2176
	v_fmac_f32_e32 v8, v175, v7
	v_fma_f32 v7, -v174, v5, v61
	v_cvt_pk_bf16_f32 v2, v6, v5
	v_fmac_f32_e32 v7, v196, v6
	v_fma_f32 v6, v174, v6, v11
	v_fmac_f32_e32 v6, v196, v5
	v_fma_f32 v5, -v176, v8, v77
	v_cvt_pk_bf16_f32 v3, v4, v8
	v_fmac_f32_e32 v5, v175, v4
	v_fma_f32 v4, v176, v4, v45
	ds_write_b64 v192, v[2:3] offset:1904
	v_fmac_f32_e32 v4, v175, v8
	v_fma_f32 v8, -v174, v6, v62
	v_cvt_pk_bf16_f32 v2, v7, v6
	v_fmac_f32_e32 v8, v196, v7
	v_fma_f32 v7, v174, v7, v12
	v_fmac_f32_e32 v7, v196, v6
	v_fma_f32 v6, -v176, v4, v78
	v_cvt_pk_bf16_f32 v3, v5, v4
	v_fmac_f32_e32 v6, v175, v5
	v_fma_f32 v5, v176, v5, v46
	ds_write_b64 v192, v[2:3] offset:1632
	v_fmac_f32_e32 v5, v175, v4
	v_fma_f32 v4, -v174, v7, v63
	v_cvt_pk_bf16_f32 v2, v8, v7
	v_fmac_f32_e32 v4, v196, v8
	v_fma_f32 v8, v174, v8, v13
	v_fmac_f32_e32 v8, v196, v7
	v_fma_f32 v7, -v176, v5, v79
	v_cvt_pk_bf16_f32 v3, v6, v5
	v_fmac_f32_e32 v7, v175, v6
	v_fma_f32 v6, v176, v6, v47
; #define LAS __attribute__((address_space(3)))
; #define CFENCE() asm volatile("" ::: "memory")
; #define MFMA32(a, b, c) __builtin_amdgcn_mfma_f32_32x32x16_bf16((a), (b), (c), 0, 0, 0)
; __device__ __forceinline__ unsigned cvtpk_s(float lo, float hi) { f32x2_t v = {lo, hi}; bf16x2_t r = __builtin_convertvector(v, bf16x2_t); return __builtin_bit_cast(unsigned, r); }
; template <int DIR> __device__ __forceinline__ void s5_task2(const PP P, int sA, int sB, int g, LAS unsigned char* wl, int lane) {
;     ...
;         bu0 = MFMA32(ucur, bfr[0], bu0); bu1 = MFMA32(ucur, bfr[1], bu1); bu2 = MFMA32(ucur, bfr[2], bu2); bu3 = MFMA32(ucur, bfr[3], bu3);
; #pragma unroll
;         for (int i = 0; i < 16; ++i) {
;             const float n0r = fmaf(are[0], sre0, fmaf(-aim[0], sim0, bu0[i])), n0i = fmaf(are[0], sim0, fmaf(aim[0], sre0, bu1[i]));
;             sre0 = n0r; sim0 = n0i;
;             asm volatile("" : "+v"(sre0), "+v"(sim0));
;             const float n1r = fmaf(are[1], sre1, fmaf(-aim[1], sim1, bu2[i])), n1i = fmaf(are[1], sim1, fmaf(aim[1], sre1, bu3[i]));
;             sre1 = n1r; sim1 = n1i;
;             asm volatile("" : "+v"(sre1), "+v"(sim1));
;             const int tau = dir ? 15 - i : i;
;             u32x2 w; w.x = cvtpk_s(sre0, sim0); w.y = cvtpk_s(sre1, sim1);
;             *(LAS u32x2*)(sst + tau * SST_PITCH + pl * 8) = w;
;         }
;         CFENCE();
; #pragma unroll
;         for (int sq = 0; sq < 2; ++sq) {
;             f32x4 acc = {0.f, 0.f, 0.f, 0.f};
; #pragma unroll
;             for (int kb = 0; kb < 4; ++kb) {
;                 const bf16x8 a = *(const LAS bf16x8*)(wl + sq * SST_BYTES + cc * SST_PITCH + (kb * 32 + q * 8) * 2);
;                 acc = __builtin_amdgcn_mfma_f32_16x16x32_bf16(cf[kb], a, acc, 0, 0, 0);
;             }
;             bf16_t* yp = Y + ((sq ? rowB : rowA) + tb + cc) * 512 + g * 16 + q * 4;
;             u32x2 yw; yw.x = cvtpk_s(acc[0], acc[1]); yw.y = cvtpk_s(acc[2], acc[3]);
;             *(u32x2*)yp = yw;
;         }
	ds_write_b64 v192, v[2:3] offset:1360
	v_fmac_f32_e32 v6, v175, v5
	v_fma_f32 v5, -v174, v8, v64
	v_cvt_pk_bf16_f32 v2, v4, v8
	v_fmac_f32_e32 v5, v196, v4
	v_fma_f32 v4, v174, v4, v14
	v_fmac_f32_e32 v4, v196, v8
	v_fma_f32 v8, -v176, v6, v80
	v_cvt_pk_bf16_f32 v3, v7, v6
	v_fmac_f32_e32 v8, v175, v7
	v_fma_f32 v7, v176, v7, v48
	ds_write_b64 v192, v[2:3] offset:1088
	v_fmac_f32_e32 v7, v175, v6
	v_fma_f32 v6, -v174, v4, v65
	v_cvt_pk_bf16_f32 v2, v5, v4
	v_fmac_f32_e32 v6, v196, v5
	v_fma_f32 v5, v174, v5, v15
	v_fmac_f32_e32 v5, v196, v4
	v_fma_f32 v4, -v176, v7, v81
	v_cvt_pk_bf16_f32 v3, v8, v7
	v_fmac_f32_e32 v4, v175, v8
	v_fma_f32 v8, v176, v8, v49
	ds_write_b64 v192, v[2:3] offset:816
	v_fmac_f32_e32 v8, v175, v7
	v_fma_f32 v7, -v174, v5, v66
	v_cvt_pk_bf16_f32 v2, v6, v5
	v_fmac_f32_e32 v7, v196, v6
	v_fma_f32 v6, v174, v6, v16
	v_fmac_f32_e32 v6, v196, v5
	v_fma_f32 v5, -v176, v8, v82
	v_cvt_pk_bf16_f32 v3, v4, v8
	v_fmac_f32_e32 v5, v175, v4
	v_fma_f32 v4, v176, v4, v50
	v_fmac_f32_e32 v4, v175, v8
	ds_write_b64 v192, v[2:3] offset:544
	v_mov_b32_e32 v11, s5
	v_fma_f32 v12, -v174, v6, v67
	v_fmac_f32_e32 v17, v174, v7
	v_fma_f32 v13, -v176, v4, v83
	v_fmac_f32_e32 v51, v176, v5
	v_cvt_pk_bf16_f32 v2, v7, v6
	v_cvt_pk_bf16_f32 v3, v5, v4
	v_fmac_f32_e32 v12, v196, v7
	v_fmac_f32_e32 v17, v196, v6
	v_fmac_f32_e32 v13, v175, v5
	v_fmac_f32_e32 v51, v175, v4
	ds_write_b64 v192, v[2:3] offset:272
	v_or_b32_e32 v10, s3, v156
	v_cvt_pk_bf16_f32 v2, v12, v17
	v_cvt_pk_bf16_f32 v3, v13, v51
	ds_write_b64 v192, v[2:3]
	ds_read_b128 v[2:5], v0
	ds_read_b128 v[6:9], v0 offset:64
	ds_read_b128 v[206:209], v0 offset:128
	ds_read_b128 v[210:213], v0 offset:192
	s_waitcnt lgkmcnt(3)
	v_mfma_f32_16x16x32_bf16 v[2:5], v[114:117], v[2:5], 0
	s_xor_b32 s3, s8, 0xffffffc
	s_add_i32 s3, s3, s4
	s_lshl_b32 s3, s3, 4
	s_waitcnt lgkmcnt(2)
	v_mfma_f32_16x16x32_bf16 v[2:5], v[118:121], v[6:9], v[2:5]
	s_ashr_i32 s5, s3, 31
	s_mov_b32 s8, s2
	s_waitcnt lgkmcnt(1)
	v_mfma_f32_16x16x32_bf16 v[2:5], v[122:125], v[206:209], v[2:5]
	s_waitcnt lgkmcnt(0)
	v_mfma_f32_16x16x32_bf16 v[2:5], v[126:129], v[210:213], v[2:5]
	v_lshl_add_u64 v[6:7], v[10:11], 0, s[64:65]
	v_lshlrev_b64 v[6:7], 10, v[6:7]
	v_lshl_add_u64 v[6:7], v[180:181], 0, v[6:7]
	s_nop 4
	v_cvt_pk_bf16_f32 v2, v2, v3
	v_cvt_pk_bf16_f32 v3, v4, v5
	global_store_dwordx2 v[6:7], v[2:3], off
	ds_read_b128 v[2:5], v0 offset:4352
	ds_read_b128 v[6:9], v0 offset:4416
	ds_read_b128 v[214:217], v0 offset:4480
	ds_read_b128 v[218:221], v0 offset:4544
	s_waitcnt lgkmcnt(3)
	v_mfma_f32_16x16x32_bf16 v[2:5], v[114:117], v[2:5], 0
	s_waitcnt lgkmcnt(2)
	v_mfma_f32_16x16x32_bf16 v[2:5], v[118:121], v[6:9], v[2:5]
	s_waitcnt lgkmcnt(1)
	v_mfma_f32_16x16x32_bf16 v[2:5], v[122:125], v[214:217], v[2:5]
	v_mfma_f32_32x32x16_bf16 v[34:49], v[146:149], v[98:101], 0
	v_mfma_f32_32x32x16_bf16 v[18:33], v[146:149], v[102:105], 0
	v_mfma_f32_32x32x16_bf16 v[68:83], v[146:149], v[106:109], 0
	v_mfma_f32_32x32x16_bf16 v[52:67], v[146:149], v[110:113], 0
	s_waitcnt vmcnt(5)
	v_mov_b64_e32 v[148:149], v[144:145]
	v_mov_b64_e32 v[146:147], v[142:143]
	s_waitcnt lgkmcnt(0)
	v_mfma_f32_16x16x32_bf16 v[2:5], v[126:129], v[218:221], v[2:5]
	v_lshl_add_u64 v[6:7], v[10:11], 0, s[66:67]
	v_lshlrev_b64 v[6:7], 10, v[6:7]
	v_lshl_add_u64 v[6:7], v[180:181], 0, v[6:7]
	v_mov_b32_e32 v11, s5
	v_or_b32_e32 v10, s3, v156
	s_nop 2
	v_cvt_pk_bf16_f32 v2, v2, v3
	v_cvt_pk_bf16_f32 v3, v4, v5
	v_fma_f32 v4, -v174, v17, v34
	v_fma_f32 v5, v174, v12, v18
	global_store_dwordx2 v[6:7], v[2:3], off
	v_fmac_f32_e32 v4, v196, v12
	v_fmac_f32_e32 v5, v196, v17
	v_fma_f32 v6, -v176, v51, v68
	v_fma_f32 v7, v176, v13, v52
	v_fma_f32 v8, -v174, v5, v35
	v_fmac_f32_e32 v6, v175, v13
	v_fmac_f32_e32 v7, v175, v51
	v_cvt_pk_bf16_f32 v2, v4, v5
	v_fmac_f32_e32 v8, v196, v4
	v_fma_f32 v4, v174, v4, v19
	v_fmac_f32_e32 v4, v196, v5
	v_fma_f32 v5, -v176, v7, v69
	v_cvt_pk_bf16_f32 v3, v6, v7
	v_fmac_f32_e32 v5, v175, v6
	v_fma_f32 v6, v176, v6, v53
	ds_write_b64 v192, v[2:3] offset:4080
	v_fmac_f32_e32 v6, v175, v7
	v_fma_f32 v7, -v174, v4, v36
	v_cvt_pk_bf16_f32 v2, v8, v4
	v_fmac_f32_e32 v7, v196, v8
	v_fma_f32 v8, v174, v8, v20
	v_fmac_f32_e32 v8, v196, v4
	v_fma_f32 v4, -v176, v6, v70
	v_cvt_pk_bf16_f32 v3, v5, v6
	v_fmac_f32_e32 v4, v175, v5
	v_fma_f32 v5, v176, v5, v54
	ds_write_b64 v192, v[2:3] offset:3808
	v_fmac_f32_e32 v5, v175, v6
	v_fma_f32 v6, -v174, v8, v37
	v_cvt_pk_bf16_f32 v2, v7, v8
	v_fmac_f32_e32 v6, v196, v7
	v_fma_f32 v7, v174, v7, v21
	v_fmac_f32_e32 v7, v196, v8
	v_fma_f32 v8, -v176, v5, v71
	v_cvt_pk_bf16_f32 v3, v4, v5
	v_fmac_f32_e32 v8, v175, v4
	v_fma_f32 v4, v176, v4, v55
	ds_write_b64 v192, v[2:3] offset:3536
	v_fmac_f32_e32 v4, v175, v5
	v_fma_f32 v5, -v174, v7, v38
	v_cvt_pk_bf16_f32 v2, v6, v7
	v_fmac_f32_e32 v5, v196, v6
	v_fma_f32 v6, v174, v6, v22
	v_fmac_f32_e32 v6, v196, v7
	v_fma_f32 v7, -v176, v4, v72
	v_cvt_pk_bf16_f32 v3, v8, v4
	v_fmac_f32_e32 v7, v175, v8
	v_fma_f32 v8, v176, v8, v56
	ds_write_b64 v192, v[2:3] offset:3264
	v_fmac_f32_e32 v8, v175, v4
	v_fma_f32 v4, -v174, v6, v39
	v_cvt_pk_bf16_f32 v2, v5, v6
	v_fmac_f32_e32 v4, v196, v5
	v_fma_f32 v5, v174, v5, v23
	v_fmac_f32_e32 v5, v196, v6
; #define LAS __attribute__((address_space(3)))
; #define CFENCE() asm volatile("" ::: "memory")
; #define MFMA32(a, b, c) __builtin_amdgcn_mfma_f32_32x32x16_bf16((a), (b), (c), 0, 0, 0)
; __device__ __forceinline__ unsigned cvtpk_s(float lo, float hi) { f32x2_t v = {lo, hi}; bf16x2_t r = __builtin_convertvector(v, bf16x2_t); return __builtin_bit_cast(unsigned, r); }
; template <int DIR> __device__ __forceinline__ void s5_task2(const PP P, int sA, int sB, int g, LAS unsigned char* wl, int lane) {
;     ...
;         bu0 = MFMA32(ucur, bfr[0], bu0); bu1 = MFMA32(ucur, bfr[1], bu1); bu2 = MFMA32(ucur, bfr[2], bu2); bu3 = MFMA32(ucur, bfr[3], bu3);
; #pragma unroll
;         for (int i = 0; i < 16; ++i) {
;             const float n0r = fmaf(are[0], sre0, fmaf(-aim[0], sim0, bu0[i])), n0i = fmaf(are[0], sim0, fmaf(aim[0], sre0, bu1[i]));
;             sre0 = n0r; sim0 = n0i;
;             asm volatile("" : "+v"(sre0), "+v"(sim0));
;             const float n1r = fmaf(are[1], sre1, fmaf(-aim[1], sim1, bu2[i])), n1i = fmaf(are[1], sim1, fmaf(aim[1], sre1, bu3[i]));
;             sre1 = n1r; sim1 = n1i;
;             asm volatile("" : "+v"(sre1), "+v"(sim1));
;             const int tau = dir ? 15 - i : i;
;             u32x2 w; w.x = cvtpk_s(sre0, sim0); w.y = cvtpk_s(sre1, sim1);
;             *(LAS u32x2*)(sst + tau * SST_PITCH + pl * 8) = w;
;         }
;         CFENCE();
; #pragma unroll
;         for (int sq = 0; sq < 2; ++sq) {
;             f32x4 acc = {0.f, 0.f, 0.f, 0.f};
; #pragma unroll
;             for (int kb = 0; kb < 4; ++kb) {
;                 const bf16x8 a = *(const LAS bf16x8*)(wl + sq * SST_BYTES + cc * SST_PITCH + (kb * 32 + q * 8) * 2);
;                 acc = __builtin_amdgcn_mfma_f32_16x16x32_bf16(cf[kb], a, acc, 0, 0, 0);
;             }
;             bf16_t* yp = Y + ((sq ? rowB : rowA) + tb + cc) * 512 + g * 16 + q * 4;
;             u32x2 yw; yw.x = cvtpk_s(acc[0], acc[1]); yw.y = cvtpk_s(acc[2], acc[3]);
;             *(u32x2*)yp = yw;
;         }
	v_fma_f32 v6, -v176, v8, v73
	v_cvt_pk_bf16_f32 v3, v7, v8
	v_fmac_f32_e32 v6, v175, v7
	v_fma_f32 v7, v176, v7, v57
	ds_write_b64 v192, v[2:3] offset:2992
	v_fmac_f32_e32 v7, v175, v8
	v_fma_f32 v8, -v174, v5, v40
	v_cvt_pk_bf16_f32 v2, v4, v5
	v_fmac_f32_e32 v8, v196, v4
	v_fma_f32 v4, v174, v4, v24
	v_fmac_f32_e32 v4, v196, v5
	v_fma_f32 v5, -v176, v7, v74
	v_cvt_pk_bf16_f32 v3, v6, v7
	v_fmac_f32_e32 v5, v175, v6
	v_fma_f32 v6, v176, v6, v58
	ds_write_b64 v192, v[2:3] offset:2720
	v_fmac_f32_e32 v6, v175, v7
	v_fma_f32 v7, -v174, v4, v41
	v_cvt_pk_bf16_f32 v2, v8, v4
	v_fmac_f32_e32 v7, v196, v8
	v_fma_f32 v8, v174, v8, v25
	v_fmac_f32_e32 v8, v196, v4
	v_fma_f32 v4, -v176, v6, v75
	v_cvt_pk_bf16_f32 v3, v5, v6
	v_fmac_f32_e32 v4, v175, v5
	v_fma_f32 v5, v176, v5, v59
	ds_write_b64 v192, v[2:3] offset:2448
	v_fmac_f32_e32 v5, v175, v6
	v_fma_f32 v6, -v174, v8, v42
	v_cvt_pk_bf16_f32 v2, v7, v8
	v_fmac_f32_e32 v6, v196, v7
	v_fma_f32 v7, v174, v7, v26
	v_fmac_f32_e32 v7, v196, v8
	v_fma_f32 v8, -v176, v5, v76
	v_cvt_pk_bf16_f32 v3, v4, v5
	v_fmac_f32_e32 v8, v175, v4
	v_fma_f32 v4, v176, v4, v60
	ds_write_b64 v192, v[2:3] offset:2176
	v_fmac_f32_e32 v4, v175, v5
	v_fma_f32 v5, -v174, v7, v43
	v_cvt_pk_bf16_f32 v2, v6, v7
	v_fmac_f32_e32 v5, v196, v6
	v_fma_f32 v6, v174, v6, v27
	v_fmac_f32_e32 v6, v196, v7
	v_fma_f32 v7, -v176, v4, v77
	v_cvt_pk_bf16_f32 v3, v8, v4
	v_fmac_f32_e32 v7, v175, v8
	v_fma_f32 v8, v176, v8, v61
	ds_write_b64 v192, v[2:3] offset:1904
	v_fmac_f32_e32 v8, v175, v4
	v_fma_f32 v4, -v174, v6, v44
	v_cvt_pk_bf16_f32 v2, v5, v6
	v_fmac_f32_e32 v4, v196, v5
	v_fma_f32 v5, v174, v5, v28
	v_fmac_f32_e32 v5, v196, v6
	v_fma_f32 v6, -v176, v8, v78
	v_cvt_pk_bf16_f32 v3, v7, v8
	v_fmac_f32_e32 v6, v175, v7
	v_fma_f32 v7, v176, v7, v62
	ds_write_b64 v192, v[2:3] offset:1632
	v_fmac_f32_e32 v7, v175, v8
	v_fma_f32 v8, -v174, v5, v45
	v_cvt_pk_bf16_f32 v2, v4, v5
	v_fmac_f32_e32 v8, v196, v4
	v_fma_f32 v4, v174, v4, v29
	v_fmac_f32_e32 v4, v196, v5
	v_fma_f32 v5, -v176, v7, v79
	v_cvt_pk_bf16_f32 v3, v6, v7
	v_fmac_f32_e32 v5, v175, v6
	v_fma_f32 v6, v176, v6, v63
	ds_write_b64 v192, v[2:3] offset:1360
	v_fmac_f32_e32 v6, v175, v7
	v_fma_f32 v7, -v174, v4, v46
	v_cvt_pk_bf16_f32 v2, v8, v4
	v_fmac_f32_e32 v7, v196, v8
	v_fma_f32 v8, v174, v8, v30
	v_fmac_f32_e32 v8, v196, v4
	v_fma_f32 v4, -v176, v6, v80
	v_cvt_pk_bf16_f32 v3, v5, v6
	v_fmac_f32_e32 v4, v175, v5
	v_fma_f32 v5, v176, v5, v64
	ds_write_b64 v192, v[2:3] offset:1088
	v_fmac_f32_e32 v5, v175, v6
	v_fma_f32 v6, -v174, v8, v47
	v_cvt_pk_bf16_f32 v2, v7, v8
	v_fmac_f32_e32 v6, v196, v7
	v_fma_f32 v7, v174, v7, v31
	v_fmac_f32_e32 v7, v196, v8
	v_fma_f32 v8, -v176, v5, v81
	v_cvt_pk_bf16_f32 v3, v4, v5
	v_fmac_f32_e32 v8, v175, v4
	v_fma_f32 v4, v176, v4, v65
	ds_write_b64 v192, v[2:3] offset:816
	v_fmac_f32_e32 v4, v175, v5
	v_fma_f32 v5, -v174, v7, v48
	v_cvt_pk_bf16_f32 v2, v6, v7
	v_fmac_f32_e32 v5, v196, v6
	v_fma_f32 v6, v174, v6, v32
	v_fmac_f32_e32 v6, v196, v7
	v_fma_f32 v7, -v176, v4, v82
	v_cvt_pk_bf16_f32 v3, v8, v4
	v_fmac_f32_e32 v7, v175, v8
	v_fma_f32 v8, v176, v8, v66
	v_fmac_f32_e32 v8, v175, v4
	ds_write_b64 v192, v[2:3] offset:544
	v_mov_b64_e32 v[24:25], v[130:131]
	v_fma_f32 v28, -v174, v6, v49
	v_fmac_f32_e32 v33, v174, v5
	v_fma_f32 v18, -v176, v8, v83
	v_fmac_f32_e32 v67, v176, v7
	v_cvt_pk_bf16_f32 v2, v5, v6
	v_cvt_pk_bf16_f32 v3, v7, v8
	v_fmac_f32_e32 v28, v196, v5
	v_fmac_f32_e32 v33, v196, v6
	v_fmac_f32_e32 v18, v175, v7
	v_fmac_f32_e32 v67, v175, v8
	ds_write_b64 v192, v[2:3] offset:272
	v_mov_b64_e32 v[20:21], v[134:135]
	v_cvt_pk_bf16_f32 v2, v28, v33
	v_cvt_pk_bf16_f32 v3, v18, v67
	ds_write_b64 v192, v[2:3]
	ds_read_b128 v[2:5], v0
	ds_read_b128 v[6:9], v0 offset:64
	ds_read_b128 v[206:209], v0 offset:128
	ds_read_b128 v[210:213], v0 offset:192
	s_waitcnt lgkmcnt(3)
	v_mfma_f32_16x16x32_bf16 v[2:5], v[114:117], v[2:5], 0
	v_mov_b64_e32 v[26:27], v[132:133]
	v_mov_b64_e32 v[22:23], v[136:137]
	s_waitcnt lgkmcnt(2)
	v_mfma_f32_16x16x32_bf16 v[2:5], v[118:121], v[6:9], v[2:5]
	s_waitcnt lgkmcnt(1)
	v_mfma_f32_16x16x32_bf16 v[2:5], v[122:125], v[206:209], v[2:5]
	s_waitcnt lgkmcnt(0)
	v_mfma_f32_16x16x32_bf16 v[2:5], v[126:129], v[210:213], v[2:5]
	v_lshl_add_u64 v[6:7], v[10:11], 0, s[64:65]
	v_lshlrev_b64 v[6:7], 10, v[6:7]
	v_lshl_add_u64 v[6:7], v[180:181], 0, v[6:7]
	s_nop 4
	v_cvt_pk_bf16_f32 v2, v2, v3
	v_cvt_pk_bf16_f32 v3, v4, v5
	global_store_dwordx2 v[6:7], v[2:3], off
	ds_read_b128 v[2:5], v0 offset:4352
	ds_read_b128 v[6:9], v0 offset:4416
	ds_read_b128 v[214:217], v0 offset:4480
	ds_read_b128 v[218:221], v0 offset:4544
	s_waitcnt lgkmcnt(3)
	v_mfma_f32_16x16x32_bf16 v[2:5], v[114:117], v[2:5], 0
	s_waitcnt lgkmcnt(2)
	v_mfma_f32_16x16x32_bf16 v[2:5], v[118:121], v[6:9], v[2:5]
	s_waitcnt lgkmcnt(1)
	v_mfma_f32_16x16x32_bf16 v[2:5], v[122:125], v[214:217], v[2:5]
	s_waitcnt lgkmcnt(0)
	v_mfma_f32_16x16x32_bf16 v[2:5], v[126:129], v[218:221], v[2:5]
	v_lshl_add_u64 v[6:7], v[10:11], 0, s[66:67]
	v_lshlrev_b64 v[6:7], 10, v[6:7]
	v_lshl_add_u64 v[6:7], v[180:181], 0, v[6:7]
	s_nop 4
	v_cvt_pk_bf16_f32 v2, v2, v3
	v_cvt_pk_bf16_f32 v3, v4, v5
	global_store_dwordx2 v[6:7], v[2:3], off
	s_cbranch_vccnz .LBB0_262

; #define LAS __attribute__((address_space(3)))
; #define MFMA32(a, b, c) __builtin_amdgcn_mfma_f32_32x32x16_bf16((a), (b), (c), 0, 0, 0)
; __device__ __forceinline__ unsigned cvtpk_s(float lo, float hi) { f32x2_t v = {lo, hi}; bf16x2_t r = __builtin_convertvector(v, bf16x2_t); return __builtin_bit_cast(unsigned, r); }
; template <int DIR> __device__ __forceinline__ void s5_task2(const PP P, int sA, int sB, int g, LAS unsigned char* wl, int lane) {
;     ...
;         bu0 = MFMA32(ucur, bfr[0], bu0); bu1 = MFMA32(ucur, bfr[1], bu1); bu2 = MFMA32(ucur, bfr[2], bu2); bu3 = MFMA32(ucur, bfr[3], bu3);
; #pragma unroll
;         for (int i = 0; i < 16; ++i) {
;             const float n0r = fmaf(are[0], sre0, fmaf(-aim[0], sim0, bu0[i])), n0i = fmaf(are[0], sim0, fmaf(aim[0], sre0, bu1[i]));
;             sre0 = n0r; sim0 = n0i;
;             asm volatile("" : "+v"(sre0), "+v"(sim0));
;             const float n1r = fmaf(are[1], sre1, fmaf(-aim[1], sim1, bu2[i])), n1i = fmaf(are[1], sim1, fmaf(aim[1], sre1, bu3[i]));
;             sre1 = n1r; sim1 = n1i;
;             asm volatile("" : "+v"(sre1), "+v"(sim1));
;             const int tau = dir ? 15 - i : i;
;             u32x2 w; w.x = cvtpk_s(sre0, sim0); w.y = cvtpk_s(sre1, sim1);
;             *(LAS u32x2*)(sst + tau * SST_PITCH + pl * 8) = w;
;         }
.LBB0_297:
	v_mfma_f32_32x32x16_bf16 v[34:49], v[2:5], v[90:93], 0
	v_add_u32_e32 v145, v193, v194
	v_lshl_add_u64 v[174:175], v[150:151], 0, s[20:21]
	v_lshl_add_u64 v[176:177], v[148:149], 0, s[20:21]
	s_mov_b64 s[6:7], 0x30000
	v_lshl_add_u64 v[148:149], v[148:149], 0, s[48:49]
	v_lshl_add_u64 v[150:151], v[150:151], 0, s[48:49]
	v_lshl_add_u64 v[152:153], v[152:153], 0, s[6:7]
	v_mfma_f32_32x32x16_bf16 v[66:81], v[2:5], v[86:89], 0
	s_nop 3
	v_fma_f32 v25, v142, v28, v34
	v_fmac_f32_e32 v25, v173, v17
	s_add_i32 s4, s4, 4
	v_mfma_f32_32x32x16_bf16 v[50:65], v[2:5], v[94:97], 0
	s_nop 3
	v_fma_f32 v0, -v142, v17, v66
	v_fmac_f32_e32 v0, v173, v28
	v_mfma_f32_32x32x16_bf16 v[4:19], v[2:5], v[98:101], 0
	s_nop 4
	v_fma_f32 v26, -v144, v33, v50
	v_fmac_f32_e32 v26, v143, v24
	v_cvt_pk_bf16_f32 v2, v0, v25
	s_nop 3
	v_fma_f32 v4, v144, v24, v4
	v_fma_f32 v24, -v142, v25, v67
	v_fmac_f32_e32 v4, v143, v33
	v_fmac_f32_e32 v24, v173, v0
	v_fma_f32 v0, v142, v0, v35
	v_fmac_f32_e32 v0, v173, v25
	v_cvt_pk_bf16_f32 v3, v26, v4
	v_fma_f32 v5, v144, v26, v5
	ds_write_b64 v192, v[2:3]
	v_fma_f32 v25, -v144, v4, v51
	v_fmac_f32_e32 v5, v143, v4
	v_fma_f32 v4, -v142, v0, v68
	v_fmac_f32_e32 v25, v143, v26
	v_cvt_pk_bf16_f32 v2, v24, v0
	v_fmac_f32_e32 v4, v173, v24
	v_fma_f32 v24, v142, v24, v36
	v_fmac_f32_e32 v24, v173, v0
	v_cvt_pk_bf16_f32 v3, v25, v5
	v_fma_f32 v6, v144, v25, v6
	ds_write_b64 v192, v[2:3] offset:272
	v_fma_f32 v0, -v144, v5, v52
	v_fmac_f32_e32 v6, v143, v5
	v_fma_f32 v5, -v142, v24, v69
	v_fmac_f32_e32 v0, v143, v25
	v_cvt_pk_bf16_f32 v2, v4, v24
	v_fmac_f32_e32 v5, v173, v4
	v_fma_f32 v4, v142, v4, v37
	v_fmac_f32_e32 v4, v173, v24
	v_fma_f32 v24, -v144, v6, v53
	v_cvt_pk_bf16_f32 v3, v0, v6
	v_fmac_f32_e32 v24, v143, v0
	v_fma_f32 v0, v144, v0, v7
	ds_write_b64 v192, v[2:3] offset:544
	v_fmac_f32_e32 v0, v143, v6
	v_fma_f32 v6, -v142, v4, v70
	v_cvt_pk_bf16_f32 v2, v5, v4
	v_fmac_f32_e32 v6, v173, v5
	v_fma_f32 v5, v142, v5, v38
	v_fmac_f32_e32 v5, v173, v4
	v_cvt_pk_bf16_f32 v3, v24, v0
	v_fma_f32 v7, v144, v24, v8
	ds_write_b64 v192, v[2:3] offset:816
	v_fma_f32 v4, -v144, v0, v54
	v_fmac_f32_e32 v7, v143, v0
	v_fma_f32 v0, -v142, v5, v71
	v_fmac_f32_e32 v4, v143, v24
	v_cvt_pk_bf16_f32 v2, v6, v5
	v_fmac_f32_e32 v0, v173, v6
	v_fma_f32 v6, v142, v6, v39
	v_fmac_f32_e32 v6, v173, v5
	v_fma_f32 v5, -v144, v7, v55
	v_cvt_pk_bf16_f32 v3, v4, v7
	v_fmac_f32_e32 v5, v143, v4
	v_fma_f32 v4, v144, v4, v9
	ds_write_b64 v192, v[2:3] offset:1088
	v_fmac_f32_e32 v4, v143, v7
	v_fma_f32 v7, -v142, v6, v72
	v_cvt_pk_bf16_f32 v2, v0, v6
	v_fmac_f32_e32 v7, v173, v0
	v_fma_f32 v0, v142, v0, v40
	v_fmac_f32_e32 v0, v173, v6
	v_fma_f32 v6, -v144, v4, v56
	v_cvt_pk_bf16_f32 v3, v5, v4
	v_fmac_f32_e32 v6, v143, v5
	v_fma_f32 v5, v144, v5, v10
	ds_write_b64 v192, v[2:3] offset:1360
	v_fmac_f32_e32 v5, v143, v4
	v_fma_f32 v4, -v142, v0, v73
	v_cvt_pk_bf16_f32 v2, v7, v0
	v_fmac_f32_e32 v4, v173, v7
	v_fma_f32 v7, v142, v7, v41
	v_fmac_f32_e32 v7, v173, v0
	v_fma_f32 v0, -v144, v5, v57
	v_cvt_pk_bf16_f32 v3, v6, v5
	v_fmac_f32_e32 v0, v143, v6
	v_fma_f32 v6, v144, v6, v11
	ds_write_b64 v192, v[2:3] offset:1632
	v_fmac_f32_e32 v6, v143, v5
	v_fma_f32 v5, -v142, v7, v74
	v_cvt_pk_bf16_f32 v2, v4, v7
	v_fmac_f32_e32 v5, v173, v4
	v_fma_f32 v4, v142, v4, v42
	v_fmac_f32_e32 v4, v173, v7
	v_fma_f32 v7, -v144, v6, v58
	v_cvt_pk_bf16_f32 v3, v0, v6
	v_fmac_f32_e32 v7, v143, v0
	v_fma_f32 v0, v144, v0, v12
	ds_write_b64 v192, v[2:3] offset:1904
	v_fmac_f32_e32 v0, v143, v6
	v_fma_f32 v6, -v142, v4, v75
	v_cvt_pk_bf16_f32 v2, v5, v4
	v_fmac_f32_e32 v6, v173, v5
	v_fma_f32 v5, v142, v5, v43
	v_fmac_f32_e32 v5, v173, v4
	v_fma_f32 v4, -v144, v0, v59
	v_cvt_pk_bf16_f32 v3, v7, v0
	v_fmac_f32_e32 v4, v143, v7
	v_fma_f32 v7, v144, v7, v13
	ds_write_b64 v192, v[2:3] offset:2176
	v_fmac_f32_e32 v7, v143, v0
	v_fma_f32 v0, -v142, v5, v76
	v_cvt_pk_bf16_f32 v2, v6, v5
	v_fmac_f32_e32 v0, v173, v6
	v_fma_f32 v6, v142, v6, v44
	v_fmac_f32_e32 v6, v173, v5
	v_fma_f32 v5, -v144, v7, v60
	v_cvt_pk_bf16_f32 v3, v4, v7
	v_fmac_f32_e32 v5, v143, v4
	v_fma_f32 v4, v144, v4, v14
	ds_write_b64 v192, v[2:3] offset:2448
	v_fmac_f32_e32 v4, v143, v7
	v_fma_f32 v7, -v142, v6, v77
	v_cvt_pk_bf16_f32 v2, v0, v6
	v_fmac_f32_e32 v7, v173, v0
	v_fma_f32 v0, v142, v0, v45
	v_fmac_f32_e32 v0, v173, v6
	v_fma_f32 v6, -v144, v4, v61
	v_cvt_pk_bf16_f32 v3, v5, v4
	v_fmac_f32_e32 v6, v143, v5
	v_fma_f32 v5, v144, v5, v15
	ds_write_b64 v192, v[2:3] offset:2720
	v_fmac_f32_e32 v5, v143, v4
	v_fma_f32 v4, -v142, v0, v78
	v_cvt_pk_bf16_f32 v2, v7, v0
	v_fmac_f32_e32 v4, v173, v7
	v_fma_f32 v7, v142, v7, v46
	v_fmac_f32_e32 v7, v173, v0
	v_fma_f32 v0, -v144, v5, v62
	v_cvt_pk_bf16_f32 v3, v6, v5
	v_fmac_f32_e32 v0, v143, v6
	v_fma_f32 v6, v144, v6, v16
	ds_write_b64 v192, v[2:3] offset:2992
	v_fmac_f32_e32 v6, v143, v5
	v_fma_f32 v5, -v142, v7, v79
	v_cvt_pk_bf16_f32 v2, v4, v7
	v_fmac_f32_e32 v5, v173, v4
	v_fma_f32 v4, v142, v4, v47
	v_fmac_f32_e32 v4, v173, v7
	v_fma_f32 v7, -v144, v6, v63
	v_cvt_pk_bf16_f32 v3, v0, v6
	v_fmac_f32_e32 v7, v143, v0
	v_fma_f32 v0, v144, v0, v17
	ds_write_b64 v192, v[2:3] offset:3264
	v_fmac_f32_e32 v0, v143, v6
	v_fma_f32 v6, -v142, v4, v80
	v_cvt_pk_bf16_f32 v2, v5, v4
	v_fmac_f32_e32 v6, v173, v5
	v_fma_f32 v5, v142, v5, v48
	v_fmac_f32_e32 v5, v173, v4
	v_fma_f32 v4, -v144, v0, v64
	v_cvt_pk_bf16_f32 v3, v7, v0
	v_fmac_f32_e32 v4, v143, v7
	v_fma_f32 v7, v144, v7, v18
	v_fmac_f32_e32 v7, v143, v0
	ds_write_b64 v192, v[2:3] offset:3536
	s_nop 0
	v_fma_f32 v0, -v142, v5, v81
	v_fmac_f32_e32 v49, v142, v6
	v_fma_f32 v18, -v144, v7, v65
	v_fmac_f32_e32 v19, v144, v4
	v_cvt_pk_bf16_f32 v2, v6, v5
	v_cvt_pk_bf16_f32 v3, v4, v7
	v_fmac_f32_e32 v0, v173, v6
	v_fmac_f32_e32 v49, v173, v5
	v_fmac_f32_e32 v18, v143, v4
	v_fmac_f32_e32 v19, v143, v7
	ds_write_b64 v192, v[2:3] offset:3808
	v_mfma_f32_32x32x16_bf16 v[66:81], v[20:23], v[86:89], 0
	v_cvt_pk_bf16_f32 v2, v0, v49
	v_cvt_pk_bf16_f32 v3, v18, v19
	ds_write_b64 v192, v[2:3] offset:4080
	ds_read_b128 v[24:27], v145
	ds_read_b128 v[28:31], v145 offset:64
	ds_read_b128 v[206:209], v145 offset:128
	ds_read_b128 v[210:213], v145 offset:192
	s_waitcnt lgkmcnt(3)
; #define LAS __attribute__((address_space(3)))
; #define CFENCE() asm volatile("" ::: "memory")
; #define MFMA32(a, b, c) __builtin_amdgcn_mfma_f32_32x32x16_bf16((a), (b), (c), 0, 0, 0)
; __device__ __forceinline__ unsigned cvtpk_s(float lo, float hi) { f32x2_t v = {lo, hi}; bf16x2_t r = __builtin_convertvector(v, bf16x2_t); return __builtin_bit_cast(unsigned, r); }
; template <int DIR> __device__ __forceinline__ void s5_task2(const PP P, int sA, int sB, int g, LAS unsigned char* wl, int lane) {
;     ...
;         bu0 = MFMA32(ucur, bfr[0], bu0); bu1 = MFMA32(ucur, bfr[1], bu1); bu2 = MFMA32(ucur, bfr[2], bu2); bu3 = MFMA32(ucur, bfr[3], bu3);
; #pragma unroll
;         for (int i = 0; i < 16; ++i) {
;             const float n0r = fmaf(are[0], sre0, fmaf(-aim[0], sim0, bu0[i])), n0i = fmaf(are[0], sim0, fmaf(aim[0], sre0, bu1[i]));
;             sre0 = n0r; sim0 = n0i;
;             asm volatile("" : "+v"(sre0), "+v"(sim0));
;             const float n1r = fmaf(are[1], sre1, fmaf(-aim[1], sim1, bu2[i])), n1i = fmaf(are[1], sim1, fmaf(aim[1], sre1, bu3[i]));
;             sre1 = n1r; sim1 = n1i;
;             asm volatile("" : "+v"(sre1), "+v"(sim1));
;             const int tau = dir ? 15 - i : i;
;             u32x2 w; w.x = cvtpk_s(sre0, sim0); w.y = cvtpk_s(sre1, sim1);
;             *(LAS u32x2*)(sst + tau * SST_PITCH + pl * 8) = w;
;         }
;         CFENCE();
; #pragma unroll
;         for (int sq = 0; sq < 2; ++sq) {
;             f32x4 acc = {0.f, 0.f, 0.f, 0.f};
; #pragma unroll
;             for (int kb = 0; kb < 4; ++kb) {
;                 const bf16x8 a = *(const LAS bf16x8*)(wl + sq * SST_BYTES + cc * SST_PITCH + (kb * 32 + q * 8) * 2);
;                 acc = __builtin_amdgcn_mfma_f32_16x16x32_bf16(cf[kb], a, acc, 0, 0, 0);
;             }
;             bf16_t* yp = Y + ((sq ? rowB : rowA) + tb + cc) * 512 + g * 16 + q * 4;
;             u32x2 yw; yw.x = cvtpk_s(acc[0], acc[1]); yw.y = cvtpk_s(acc[2], acc[3]);
;             *(u32x2*)yp = yw;
;         }
	v_mfma_f32_16x16x32_bf16 v[24:27], v[102:105], v[24:27], 0
	s_waitcnt lgkmcnt(2)
	v_mfma_f32_16x16x32_bf16 v[24:27], v[106:109], v[28:31], v[24:27]
	s_waitcnt lgkmcnt(1)
	v_mfma_f32_16x16x32_bf16 v[24:27], v[110:113], v[206:209], v[24:27]
	s_waitcnt lgkmcnt(0)
	v_mfma_f32_16x16x32_bf16 v[24:27], v[114:117], v[210:213], v[24:27]
	ds_read_b128 v[28:31], v145 offset:4352
	ds_read_b128 v[32:35], v145 offset:4416
	ds_read_b128 v[214:217], v145 offset:4480
	ds_read_b128 v[218:221], v145 offset:4544
	s_waitcnt lgkmcnt(3)
	v_mfma_f32_16x16x32_bf16 v[28:31], v[102:105], v[28:31], 0
	s_waitcnt lgkmcnt(2)
	v_mfma_f32_16x16x32_bf16 v[28:31], v[106:109], v[32:35], v[28:31]
	s_nop 0
	v_cvt_pk_bf16_f32 v32, v24, v25
	v_cvt_pk_bf16_f32 v33, v26, v27
	s_waitcnt lgkmcnt(1)
	v_mfma_f32_16x16x32_bf16 v[28:31], v[110:113], v[214:217], v[28:31]
	v_add_co_u32_e32 v34, vcc, s11, v174
	s_waitcnt lgkmcnt(0)
	v_mfma_f32_16x16x32_bf16 v[24:27], v[114:117], v[218:221], v[28:31]
	v_addc_co_u32_e32 v35, vcc, 0, v175, vcc
	global_store_dwordx2 v[34:35], v[32:33], off
	v_mfma_f32_32x32x16_bf16 v[2:17], v[20:23], v[90:93], 0
	s_nop 4
	v_cvt_pk_bf16_f32 v24, v24, v25
	v_cvt_pk_bf16_f32 v25, v26, v27
	v_add_co_u32_e32 v26, vcc, s11, v176
	v_mfma_f32_32x32x16_bf16 v[50:65], v[20:23], v[94:97], 0
	s_nop 0
	v_addc_co_u32_e32 v27, vcc, 0, v177, vcc
	global_store_dwordx2 v[26:27], v[24:25], off
	v_mfma_f32_32x32x16_bf16 v[22:37], v[20:23], v[98:101], 0
	v_fma_f32 v20, -v142, v49, v66
	v_fmac_f32_e32 v20, v173, v0
	v_fma_f32 v0, v142, v0, v2
	s_nop 4
	v_fma_f32 v2, -v144, v19, v50
	v_fmac_f32_e32 v0, v173, v49
	v_fmac_f32_e32 v2, v143, v18
	s_nop 0
	v_fma_f32 v21, v144, v18, v22
	v_fmac_f32_e32 v21, v143, v19
	v_cvt_pk_bf16_f32 v18, v20, v0
	v_cvt_pk_bf16_f32 v19, v2, v21
	ds_write_b64 v192, v[18:19]
	v_fma_f32 v18, -v142, v0, v67
	v_fma_f32 v19, v142, v20, v3
	v_fmac_f32_e32 v18, v173, v20
	v_fmac_f32_e32 v19, v173, v0
	v_fma_f32 v0, -v144, v21, v51
	v_fma_f32 v20, v144, v2, v23
	v_fmac_f32_e32 v0, v143, v2
	v_fmac_f32_e32 v20, v143, v21
	v_fma_f32 v21, -v142, v19, v68
	v_cvt_pk_bf16_f32 v2, v18, v19
	v_fmac_f32_e32 v21, v173, v18
	v_fma_f32 v4, v142, v18, v4
	v_fma_f32 v18, -v144, v20, v52
	v_cvt_pk_bf16_f32 v3, v0, v20
	v_fmac_f32_e32 v4, v173, v19
	v_fmac_f32_e32 v18, v143, v0
	v_fma_f32 v0, v144, v0, v24
	ds_write_b64 v192, v[2:3] offset:272
	v_fmac_f32_e32 v0, v143, v20
	v_fma_f32 v5, v142, v21, v5
	v_cvt_pk_bf16_f32 v2, v21, v4
	v_fma_f32 v19, -v142, v4, v69
	v_fmac_f32_e32 v5, v173, v4
	v_fma_f32 v4, -v144, v0, v53
	v_cvt_pk_bf16_f32 v3, v18, v0
	v_fmac_f32_e32 v19, v173, v21
	v_fmac_f32_e32 v4, v143, v18
	v_fma_f32 v18, v144, v18, v25
	ds_write_b64 v192, v[2:3] offset:544
	v_fmac_f32_e32 v18, v143, v0
	v_fma_f32 v6, v142, v19, v6
	v_cvt_pk_bf16_f32 v2, v19, v5
	v_fma_f32 v0, -v142, v5, v70
	v_fmac_f32_e32 v6, v173, v5
	v_fma_f32 v5, -v144, v18, v54
	v_cvt_pk_bf16_f32 v3, v4, v18
	v_fmac_f32_e32 v0, v173, v19
	v_fmac_f32_e32 v5, v143, v4
	v_fma_f32 v4, v144, v4, v26
	ds_write_b64 v192, v[2:3] offset:816
	v_fmac_f32_e32 v4, v143, v18
	v_fma_f32 v18, -v142, v6, v71
	v_cvt_pk_bf16_f32 v2, v0, v6
	v_fmac_f32_e32 v18, v173, v0
	v_fma_f32 v0, v142, v0, v7
	v_fmac_f32_e32 v0, v173, v6
	v_fma_f32 v6, -v144, v4, v55
	v_cvt_pk_bf16_f32 v3, v5, v4
	v_fmac_f32_e32 v6, v143, v5
	v_fma_f32 v5, v144, v5, v27
	ds_write_b64 v192, v[2:3] offset:1088
	v_fmac_f32_e32 v5, v143, v4
	v_fma_f32 v7, v142, v18, v8
	v_cvt_pk_bf16_f32 v2, v18, v0
	v_fma_f32 v4, -v142, v0, v72
	v_fmac_f32_e32 v7, v173, v0
	v_fma_f32 v0, -v144, v5, v56
	v_cvt_pk_bf16_f32 v3, v6, v5
	v_fmac_f32_e32 v4, v173, v18
	v_fmac_f32_e32 v0, v143, v6
	v_fma_f32 v6, v144, v6, v28
	ds_write_b64 v192, v[2:3] offset:1360
	v_fmac_f32_e32 v6, v143, v5
	v_fma_f32 v5, -v142, v7, v73
	v_cvt_pk_bf16_f32 v2, v4, v7
	v_fmac_f32_e32 v5, v173, v4
	v_fma_f32 v4, v142, v4, v9
	v_fmac_f32_e32 v4, v173, v7
	v_fma_f32 v7, -v144, v6, v57
	v_cvt_pk_bf16_f32 v3, v0, v6
	v_fmac_f32_e32 v7, v143, v0
	v_fma_f32 v0, v144, v0, v29
	ds_write_b64 v192, v[2:3] offset:1632
	v_fmac_f32_e32 v0, v143, v6
	v_fma_f32 v6, -v142, v4, v74
	v_cvt_pk_bf16_f32 v2, v5, v4
	v_fmac_f32_e32 v6, v173, v5
	v_fma_f32 v5, v142, v5, v10
	v_fmac_f32_e32 v5, v173, v4
	v_fma_f32 v4, -v144, v0, v58
	v_cvt_pk_bf16_f32 v3, v7, v0
	v_fmac_f32_e32 v4, v143, v7
	v_fma_f32 v7, v144, v7, v30
	ds_write_b64 v192, v[2:3] offset:1904
	v_fmac_f32_e32 v7, v143, v0
	v_fma_f32 v0, -v142, v5, v75
	v_cvt_pk_bf16_f32 v2, v6, v5
	v_fmac_f32_e32 v0, v173, v6
	v_fma_f32 v6, v142, v6, v11
	v_fmac_f32_e32 v6, v173, v5
	v_fma_f32 v5, -v144, v7, v59
	v_cvt_pk_bf16_f32 v3, v4, v7
	v_fmac_f32_e32 v5, v143, v4
	v_fma_f32 v4, v144, v4, v31
	ds_write_b64 v192, v[2:3] offset:2176
	v_fmac_f32_e32 v4, v143, v7
	v_fma_f32 v7, -v142, v6, v76
	v_cvt_pk_bf16_f32 v2, v0, v6
	v_fmac_f32_e32 v7, v173, v0
	v_fma_f32 v0, v142, v0, v12
	v_fmac_f32_e32 v0, v173, v6
	v_fma_f32 v6, -v144, v4, v60
	v_cvt_pk_bf16_f32 v3, v5, v4
	v_fmac_f32_e32 v6, v143, v5
	v_fma_f32 v5, v144, v5, v32
	ds_write_b64 v192, v[2:3] offset:2448
	v_fmac_f32_e32 v5, v143, v4
	v_fma_f32 v4, -v142, v0, v77
	v_cvt_pk_bf16_f32 v2, v7, v0
	v_fmac_f32_e32 v4, v173, v7
	v_fma_f32 v7, v142, v7, v13
	v_fmac_f32_e32 v7, v173, v0
	v_fma_f32 v0, -v144, v5, v61
	v_cvt_pk_bf16_f32 v3, v6, v5
	v_fmac_f32_e32 v0, v143, v6
	v_fma_f32 v6, v144, v6, v33
	ds_write_b64 v192, v[2:3] offset:2720
	v_fmac_f32_e32 v6, v143, v5
	v_fma_f32 v5, -v142, v7, v78
	v_cvt_pk_bf16_f32 v2, v4, v7
	v_fmac_f32_e32 v5, v173, v4
	v_fma_f32 v4, v142, v4, v14
	v_fmac_f32_e32 v4, v173, v7
	v_fma_f32 v7, -v144, v6, v62
	v_cvt_pk_bf16_f32 v3, v0, v6
	v_fmac_f32_e32 v7, v143, v0
	v_fma_f32 v0, v144, v0, v34
; #define LAS __attribute__((address_space(3)))
; #define CFENCE() asm volatile("" ::: "memory")
; #define MFMA32(a, b, c) __builtin_amdgcn_mfma_f32_32x32x16_bf16((a), (b), (c), 0, 0, 0)
; __device__ __forceinline__ unsigned cvtpk_s(float lo, float hi) { f32x2_t v = {lo, hi}; bf16x2_t r = __builtin_convertvector(v, bf16x2_t); return __builtin_bit_cast(unsigned, r); }
; template <int DIR> __device__ __forceinline__ void s5_task2(const PP P, int sA, int sB, int g, LAS unsigned char* wl, int lane) {
;     ...
;         bu0 = MFMA32(ucur, bfr[0], bu0); bu1 = MFMA32(ucur, bfr[1], bu1); bu2 = MFMA32(ucur, bfr[2], bu2); bu3 = MFMA32(ucur, bfr[3], bu3);
; #pragma unroll
;         for (int i = 0; i < 16; ++i) {
;             const float n0r = fmaf(are[0], sre0, fmaf(-aim[0], sim0, bu0[i])), n0i = fmaf(are[0], sim0, fmaf(aim[0], sre0, bu1[i]));
;             sre0 = n0r; sim0 = n0i;
;             asm volatile("" : "+v"(sre0), "+v"(sim0));
;             const float n1r = fmaf(are[1], sre1, fmaf(-aim[1], sim1, bu2[i])), n1i = fmaf(are[1], sim1, fmaf(aim[1], sre1, bu3[i]));
;             sre1 = n1r; sim1 = n1i;
;             asm volatile("" : "+v"(sre1), "+v"(sim1));
;             const int tau = dir ? 15 - i : i;
;             u32x2 w; w.x = cvtpk_s(sre0, sim0); w.y = cvtpk_s(sre1, sim1);
;             *(LAS u32x2*)(sst + tau * SST_PITCH + pl * 8) = w;
;         }
;         CFENCE();
; #pragma unroll
;         for (int sq = 0; sq < 2; ++sq) {
;             f32x4 acc = {0.f, 0.f, 0.f, 0.f};
; #pragma unroll
;             for (int kb = 0; kb < 4; ++kb) {
;                 const bf16x8 a = *(const LAS bf16x8*)(wl + sq * SST_BYTES + cc * SST_PITCH + (kb * 32 + q * 8) * 2);
;                 acc = __builtin_amdgcn_mfma_f32_16x16x32_bf16(cf[kb], a, acc, 0, 0, 0);
;             }
;             bf16_t* yp = Y + ((sq ? rowB : rowA) + tb + cc) * 512 + g * 16 + q * 4;
;             u32x2 yw; yw.x = cvtpk_s(acc[0], acc[1]); yw.y = cvtpk_s(acc[2], acc[3]);
;             *(u32x2*)yp = yw;
;         }
	ds_write_b64 v192, v[2:3] offset:2992
	v_fmac_f32_e32 v0, v143, v6
	v_fma_f32 v6, -v142, v4, v79
	v_cvt_pk_bf16_f32 v2, v5, v4
	v_fmac_f32_e32 v6, v173, v5
	v_fma_f32 v5, v142, v5, v15
	v_fmac_f32_e32 v5, v173, v4
	v_fma_f32 v4, -v144, v0, v63
	v_cvt_pk_bf16_f32 v3, v7, v0
	v_fmac_f32_e32 v4, v143, v7
	v_fma_f32 v7, v144, v7, v35
	ds_write_b64 v192, v[2:3] offset:3264
	v_fmac_f32_e32 v7, v143, v0
	v_fma_f32 v0, -v142, v5, v80
	v_cvt_pk_bf16_f32 v2, v6, v5
	v_fmac_f32_e32 v0, v173, v6
	v_fma_f32 v6, v142, v6, v16
	v_fmac_f32_e32 v6, v173, v5
	v_fma_f32 v5, -v144, v7, v64
	v_cvt_pk_bf16_f32 v3, v4, v7
	v_fmac_f32_e32 v5, v143, v4
	v_fma_f32 v4, v144, v4, v36
	ds_write_b64 v192, v[2:3] offset:3536
	v_fmac_f32_e32 v4, v143, v7
	v_fma_f32 v14, -v142, v6, v81
	v_cvt_pk_bf16_f32 v2, v0, v6
	v_fmac_f32_e32 v14, v173, v0
	v_fmac_f32_e32 v17, v142, v0
	v_fma_f32 v0, -v144, v4, v65
	v_fmac_f32_e32 v37, v144, v5
	v_cvt_pk_bf16_f32 v3, v5, v4
	v_fmac_f32_e32 v17, v173, v6
	v_fmac_f32_e32 v0, v143, v5
	v_fmac_f32_e32 v37, v143, v4
	ds_write_b64 v192, v[2:3] offset:3808
	v_mfma_f32_32x32x16_bf16 v[70:85], v[138:141], v[86:89], 0
	v_cvt_pk_bf16_f32 v2, v14, v17
	v_cvt_pk_bf16_f32 v3, v0, v37
	ds_write_b64 v192, v[2:3] offset:4080
	ds_read_b128 v[2:5], v145
	ds_read_b128 v[6:9], v145 offset:64
	ds_read_b128 v[206:209], v145 offset:128
	ds_read_b128 v[210:213], v145 offset:192
	s_waitcnt lgkmcnt(3)
	v_mfma_f32_16x16x32_bf16 v[2:5], v[102:105], v[2:5], 0
	s_waitcnt lgkmcnt(2)
	v_mfma_f32_16x16x32_bf16 v[2:5], v[106:109], v[6:9], v[2:5]
	s_waitcnt lgkmcnt(1)
	v_mfma_f32_16x16x32_bf16 v[2:5], v[110:113], v[206:209], v[2:5]
	s_waitcnt lgkmcnt(0)
	v_mfma_f32_16x16x32_bf16 v[2:5], v[114:117], v[210:213], v[2:5]
	ds_read_b128 v[6:9], v145 offset:4352
	ds_read_b128 v[10:13], v145 offset:4416
	ds_read_b128 v[214:217], v145 offset:4480
	ds_read_b128 v[218:221], v145 offset:4544
	s_waitcnt lgkmcnt(3)
	v_mfma_f32_16x16x32_bf16 v[6:9], v[102:105], v[6:9], 0
	s_waitcnt lgkmcnt(2)
	v_mfma_f32_16x16x32_bf16 v[6:9], v[106:109], v[10:13], v[6:9]
	s_waitcnt lgkmcnt(1)
	v_mfma_f32_16x16x32_bf16 v[6:9], v[110:113], v[214:217], v[6:9]
	v_cvt_pk_bf16_f32 v10, v2, v3
	v_cvt_pk_bf16_f32 v11, v4, v5
	v_mfma_f32_32x32x16_bf16 v[20:35], v[138:141], v[90:93], 0
	v_mfma_f32_32x32x16_bf16 v[54:69], v[138:141], v[94:97], 0
	s_waitcnt lgkmcnt(0)
	v_mfma_f32_16x16x32_bf16 v[2:5], v[114:117], v[218:221], v[6:9]
	v_mfma_f32_32x32x16_bf16 v[38:53], v[138:141], v[98:101], 0
	s_nop 1
	v_add_co_u32_e32 v6, vcc, s18, v174
	s_nop 3
	v_cvt_pk_bf16_f32 v2, v2, v3
	v_addc_co_u32_e32 v7, vcc, 0, v175, vcc
	v_cvt_pk_bf16_f32 v3, v4, v5
	v_add_co_u32_e32 v4, vcc, s18, v176
	global_store_dwordx2 v[6:7], v[10:11], off
	s_nop 0
	v_addc_co_u32_e32 v5, vcc, 0, v177, vcc
	global_store_dwordx2 v[4:5], v[2:3], off
	v_fma_f32 v4, -v142, v17, v70
	v_fma_f32 v5, v142, v14, v20
	v_fmac_f32_e32 v4, v173, v14
	v_fmac_f32_e32 v5, v173, v17
	v_fma_f32 v6, -v144, v37, v54
	v_fmac_f32_e32 v6, v143, v0
	v_fma_f32 v0, v144, v0, v38
	v_fma_f32 v7, -v142, v5, v71
	v_fmac_f32_e32 v0, v143, v37
	v_cvt_pk_bf16_f32 v2, v4, v5
	v_fmac_f32_e32 v7, v173, v4
	v_fma_f32 v4, v142, v4, v21
	v_fmac_f32_e32 v4, v173, v5
	v_fma_f32 v5, -v144, v0, v55
	v_cvt_pk_bf16_f32 v3, v6, v0
	v_fmac_f32_e32 v5, v143, v6
	v_fma_f32 v6, v144, v6, v39
	ds_write_b64 v192, v[2:3]
	v_fmac_f32_e32 v6, v143, v0
	v_fma_f32 v0, -v142, v4, v72
	v_cvt_pk_bf16_f32 v2, v7, v4
	v_fmac_f32_e32 v0, v173, v7
	v_fma_f32 v7, v142, v7, v22
	v_fmac_f32_e32 v7, v173, v4
	v_fma_f32 v4, -v144, v6, v56
	v_cvt_pk_bf16_f32 v3, v5, v6
	v_fmac_f32_e32 v4, v143, v5
	v_fma_f32 v5, v144, v5, v40
	ds_write_b64 v192, v[2:3] offset:272
	v_fmac_f32_e32 v5, v143, v6
	v_fma_f32 v6, -v142, v7, v73
	v_cvt_pk_bf16_f32 v2, v0, v7
	v_fmac_f32_e32 v6, v173, v0
	v_fma_f32 v0, v142, v0, v23
	v_fmac_f32_e32 v0, v173, v7
	v_fma_f32 v7, -v144, v5, v57
	v_cvt_pk_bf16_f32 v3, v4, v5
	v_fmac_f32_e32 v7, v143, v4
	v_fma_f32 v4, v144, v4, v41
	ds_write_b64 v192, v[2:3] offset:544
	v_fmac_f32_e32 v4, v143, v5
	v_fma_f32 v5, -v142, v0, v74
	v_cvt_pk_bf16_f32 v2, v6, v0
	v_fmac_f32_e32 v5, v173, v6
	v_fma_f32 v6, v142, v6, v24
	v_fmac_f32_e32 v6, v173, v0
	v_fma_f32 v0, -v144, v4, v58
	v_cvt_pk_bf16_f32 v3, v7, v4
	v_fmac_f32_e32 v0, v143, v7
	v_fma_f32 v7, v144, v7, v42
	ds_write_b64 v192, v[2:3] offset:816
	v_fmac_f32_e32 v7, v143, v4
	v_fma_f32 v4, -v142, v6, v75
	v_cvt_pk_bf16_f32 v2, v5, v6
	v_fmac_f32_e32 v4, v173, v5
	v_fma_f32 v5, v142, v5, v25
	v_fmac_f32_e32 v5, v173, v6
	v_fma_f32 v6, -v144, v7, v59
	v_cvt_pk_bf16_f32 v3, v0, v7
	v_fmac_f32_e32 v6, v143, v0
	v_fma_f32 v0, v144, v0, v43
	ds_write_b64 v192, v[2:3] offset:1088
	v_fmac_f32_e32 v0, v143, v7
	v_fma_f32 v7, -v142, v5, v76
	v_cvt_pk_bf16_f32 v2, v4, v5
	v_fmac_f32_e32 v7, v173, v4
	v_fma_f32 v4, v142, v4, v26
	v_fmac_f32_e32 v4, v173, v5
	v_fma_f32 v5, -v144, v0, v60
	v_cvt_pk_bf16_f32 v3, v6, v0
	v_fmac_f32_e32 v5, v143, v6
	v_fma_f32 v6, v144, v6, v44
	ds_write_b64 v192, v[2:3] offset:1360
	v_fmac_f32_e32 v6, v143, v0
	v_fma_f32 v0, -v142, v4, v77
	v_cvt_pk_bf16_f32 v2, v7, v4
	v_fmac_f32_e32 v0, v173, v7
	v_fma_f32 v7, v142, v7, v27
	v_fmac_f32_e32 v7, v173, v4
	v_fma_f32 v4, -v144, v6, v61
	v_cvt_pk_bf16_f32 v3, v5, v6
	v_fmac_f32_e32 v4, v143, v5
	v_fma_f32 v5, v144, v5, v45
	ds_write_b64 v192, v[2:3] offset:1632
	v_fmac_f32_e32 v5, v143, v6
	v_fma_f32 v6, -v142, v7, v78
	v_cvt_pk_bf16_f32 v2, v0, v7
	v_fmac_f32_e32 v6, v173, v0
	v_fma_f32 v0, v142, v0, v28
	v_fmac_f32_e32 v0, v173, v7
	v_fma_f32 v7, -v144, v5, v62
	v_cvt_pk_bf16_f32 v3, v4, v5
	v_fmac_f32_e32 v7, v143, v4
	v_fma_f32 v4, v144, v4, v46
	ds_write_b64 v192, v[2:3] offset:1904
; #define LAS __attribute__((address_space(3)))
; #define CFENCE() asm volatile("" ::: "memory")
; #define MFMA32(a, b, c) __builtin_amdgcn_mfma_f32_32x32x16_bf16((a), (b), (c), 0, 0, 0)
; __device__ __forceinline__ unsigned cvtpk_s(float lo, float hi) { f32x2_t v = {lo, hi}; bf16x2_t r = __builtin_convertvector(v, bf16x2_t); return __builtin_bit_cast(unsigned, r); }
; template <int DIR> __device__ __forceinline__ void s5_task2(const PP P, int sA, int sB, int g, LAS unsigned char* wl, int lane) {
;     ...
;         bu0 = MFMA32(ucur, bfr[0], bu0); bu1 = MFMA32(ucur, bfr[1], bu1); bu2 = MFMA32(ucur, bfr[2], bu2); bu3 = MFMA32(ucur, bfr[3], bu3);
; #pragma unroll
;         for (int i = 0; i < 16; ++i) {
;             const float n0r = fmaf(are[0], sre0, fmaf(-aim[0], sim0, bu0[i])), n0i = fmaf(are[0], sim0, fmaf(aim[0], sre0, bu1[i]));
;             sre0 = n0r; sim0 = n0i;
;             asm volatile("" : "+v"(sre0), "+v"(sim0));
;             const float n1r = fmaf(are[1], sre1, fmaf(-aim[1], sim1, bu2[i])), n1i = fmaf(are[1], sim1, fmaf(aim[1], sre1, bu3[i]));
;             sre1 = n1r; sim1 = n1i;
;             asm volatile("" : "+v"(sre1), "+v"(sim1));
;             const int tau = dir ? 15 - i : i;
;             u32x2 w; w.x = cvtpk_s(sre0, sim0); w.y = cvtpk_s(sre1, sim1);
;             *(LAS u32x2*)(sst + tau * SST_PITCH + pl * 8) = w;
;         }
;         CFENCE();
; #pragma unroll
;         for (int sq = 0; sq < 2; ++sq) {
;             f32x4 acc = {0.f, 0.f, 0.f, 0.f};
; #pragma unroll
;             for (int kb = 0; kb < 4; ++kb) {
;                 const bf16x8 a = *(const LAS bf16x8*)(wl + sq * SST_BYTES + cc * SST_PITCH + (kb * 32 + q * 8) * 2);
;                 acc = __builtin_amdgcn_mfma_f32_16x16x32_bf16(cf[kb], a, acc, 0, 0, 0);
;             }
;             bf16_t* yp = Y + ((sq ? rowB : rowA) + tb + cc) * 512 + g * 16 + q * 4;
;             u32x2 yw; yw.x = cvtpk_s(acc[0], acc[1]); yw.y = cvtpk_s(acc[2], acc[3]);
;             *(u32x2*)yp = yw;
;         }
	v_fmac_f32_e32 v4, v143, v5
	v_fma_f32 v5, -v142, v0, v79
	v_cvt_pk_bf16_f32 v2, v6, v0
	v_fmac_f32_e32 v5, v173, v6
	v_fma_f32 v6, v142, v6, v29
	v_fmac_f32_e32 v6, v173, v0
	v_fma_f32 v0, -v144, v4, v63
	v_cvt_pk_bf16_f32 v3, v7, v4
	v_fmac_f32_e32 v0, v143, v7
	v_fma_f32 v7, v144, v7, v47
	ds_write_b64 v192, v[2:3] offset:2176
	v_fmac_f32_e32 v7, v143, v4
	v_fma_f32 v4, -v142, v6, v80
	v_cvt_pk_bf16_f32 v2, v5, v6
	v_fmac_f32_e32 v4, v173, v5
	v_fma_f32 v5, v142, v5, v30
	v_fmac_f32_e32 v5, v173, v6
	v_fma_f32 v6, -v144, v7, v64
	v_cvt_pk_bf16_f32 v3, v0, v7
	v_fmac_f32_e32 v6, v143, v0
	v_fma_f32 v0, v144, v0, v48
	ds_write_b64 v192, v[2:3] offset:2448
	v_fmac_f32_e32 v0, v143, v7
	v_fma_f32 v7, -v142, v5, v81
	v_cvt_pk_bf16_f32 v2, v4, v5
	v_fmac_f32_e32 v7, v173, v4
	v_fma_f32 v4, v142, v4, v31
	v_fmac_f32_e32 v4, v173, v5
	v_fma_f32 v5, -v144, v0, v65
	v_cvt_pk_bf16_f32 v3, v6, v0
	v_fmac_f32_e32 v5, v143, v6
	v_fma_f32 v6, v144, v6, v49
	ds_write_b64 v192, v[2:3] offset:2720
	v_fmac_f32_e32 v6, v143, v0
	v_fma_f32 v0, -v142, v4, v82
	v_cvt_pk_bf16_f32 v2, v7, v4
	v_fmac_f32_e32 v0, v173, v7
	v_fma_f32 v7, v142, v7, v32
	v_fmac_f32_e32 v7, v173, v4
	v_fma_f32 v4, -v144, v6, v66
	v_cvt_pk_bf16_f32 v3, v5, v6
	v_fmac_f32_e32 v4, v143, v5
	v_fma_f32 v5, v144, v5, v50
	ds_write_b64 v192, v[2:3] offset:2992
	v_fmac_f32_e32 v5, v143, v6
	v_fma_f32 v6, -v142, v7, v83
	v_cvt_pk_bf16_f32 v2, v0, v7
	v_fmac_f32_e32 v6, v173, v0
	v_fma_f32 v0, v142, v0, v33
	v_fmac_f32_e32 v0, v173, v7
	v_fma_f32 v7, -v144, v5, v67
	v_cvt_pk_bf16_f32 v3, v4, v5
	v_fmac_f32_e32 v7, v143, v4
	v_fma_f32 v4, v144, v4, v51
	ds_write_b64 v192, v[2:3] offset:3264
	v_fmac_f32_e32 v4, v143, v5
	v_fma_f32 v5, -v142, v0, v84
	v_cvt_pk_bf16_f32 v2, v6, v0
	v_fmac_f32_e32 v5, v173, v6
	v_fma_f32 v6, v142, v6, v34
	v_fmac_f32_e32 v6, v173, v0
	v_fma_f32 v0, -v144, v4, v68
	v_cvt_pk_bf16_f32 v3, v7, v4
	v_fmac_f32_e32 v0, v143, v7
	v_fma_f32 v7, v144, v7, v52
	v_fmac_f32_e32 v7, v143, v4
	ds_write_b64 v192, v[2:3] offset:3536
	v_mfma_f32_32x32x16_bf16 v[36:51], v[134:137], v[86:89], 0
	v_fma_f32 v34, -v142, v6, v85
	v_fmac_f32_e32 v35, v142, v5
	v_fma_f32 v52, -v144, v7, v69
	v_fmac_f32_e32 v53, v144, v0
	v_cvt_pk_bf16_f32 v2, v5, v6
	v_cvt_pk_bf16_f32 v3, v0, v7
	v_fmac_f32_e32 v34, v173, v5
	v_fmac_f32_e32 v35, v173, v6
	v_fmac_f32_e32 v52, v143, v0
	v_fmac_f32_e32 v53, v143, v7
	ds_write_b64 v192, v[2:3] offset:3808
	v_mfma_f32_32x32x16_bf16 v[2:17], v[134:137], v[90:93], 0
	v_cvt_pk_bf16_f32 v18, v34, v35
	v_cvt_pk_bf16_f32 v19, v52, v53
	ds_write_b64 v192, v[18:19] offset:4080
	ds_read_b128 v[18:21], v145
	ds_read_b128 v[22:25], v145 offset:64
	ds_read_b128 v[206:209], v145 offset:128
	ds_read_b128 v[210:213], v145 offset:192
	v_fma_f32 v0, -v142, v35, v36
	v_fmac_f32_e32 v0, v173, v34
	s_waitcnt lgkmcnt(3)
	v_mfma_f32_16x16x32_bf16 v[18:21], v[102:105], v[18:21], 0
	s_nop 2
	v_fma_f32 v2, v142, v34, v2
	v_fmac_f32_e32 v2, v173, v35
	s_waitcnt vmcnt(5)
	v_mov_b64_e32 v[140:141], v[128:129]
	s_waitcnt lgkmcnt(2)
	v_mfma_f32_16x16x32_bf16 v[18:21], v[106:109], v[22:25], v[18:21]
	v_mov_b64_e32 v[138:139], v[126:127]
	s_waitcnt lgkmcnt(1)
	v_mfma_f32_16x16x32_bf16 v[18:21], v[110:113], v[206:209], v[18:21]
	s_waitcnt lgkmcnt(0)
	v_mfma_f32_16x16x32_bf16 v[18:21], v[114:117], v[210:213], v[18:21]
	ds_read_b128 v[22:25], v145 offset:4352
	ds_read_b128 v[26:29], v145 offset:4416
	ds_read_b128 v[214:217], v145 offset:4480
	ds_read_b128 v[218:221], v145 offset:4544
	s_waitcnt lgkmcnt(3)
	v_mfma_f32_16x16x32_bf16 v[22:25], v[102:105], v[22:25], 0
	s_waitcnt lgkmcnt(2)
	v_mfma_f32_16x16x32_bf16 v[22:25], v[106:109], v[26:29], v[22:25]
	s_waitcnt lgkmcnt(1)
	v_mfma_f32_16x16x32_bf16 v[22:25], v[110:113], v[214:217], v[22:25]
	v_cvt_pk_bf16_f32 v26, v18, v19
	v_cvt_pk_bf16_f32 v27, v20, v21
	s_waitcnt lgkmcnt(0)
	v_mfma_f32_16x16x32_bf16 v[18:21], v[114:117], v[218:221], v[22:25]
	s_nop 3
	v_add_co_u32_e32 v22, vcc, s19, v174
	v_mfma_f32_32x32x16_bf16 v[54:69], v[134:137], v[94:97], 0
	s_nop 0
	v_addc_co_u32_e32 v23, vcc, 0, v175, vcc
	v_cvt_pk_bf16_f32 v18, v18, v19
	v_cvt_pk_bf16_f32 v19, v20, v21
	v_add_co_u32_e32 v20, vcc, s19, v176
	global_store_dwordx2 v[22:23], v[26:27], off
	s_nop 0
	v_addc_co_u32_e32 v21, vcc, 0, v177, vcc
	global_store_dwordx2 v[20:21], v[18:19], off
	v_mfma_f32_32x32x16_bf16 v[18:33], v[134:137], v[98:101], 0
	s_nop 1
	v_fma_f32 v36, -v144, v53, v54
	v_fmac_f32_e32 v36, v143, v52
	s_waitcnt vmcnt(6)
; #define LAS __attribute__((address_space(3)))
; #define CFENCE() asm volatile("" ::: "memory")
; #define MFMA32(a, b, c) __builtin_amdgcn_mfma_f32_32x32x16_bf16((a), (b), (c), 0, 0, 0)
; __device__ __forceinline__ unsigned cvtpk_s(float lo, float hi) { f32x2_t v = {lo, hi}; bf16x2_t r = __builtin_convertvector(v, bf16x2_t); return __builtin_bit_cast(unsigned, r); }
; template <int DIR> __device__ __forceinline__ void s5_task2(const PP P, int sA, int sB, int g, LAS unsigned char* wl, int lane) {
;     ...
;         bu0 = MFMA32(ucur, bfr[0], bu0); bu1 = MFMA32(ucur, bfr[1], bu1); bu2 = MFMA32(ucur, bfr[2], bu2); bu3 = MFMA32(ucur, bfr[3], bu3);
; #pragma unroll
;         for (int i = 0; i < 16; ++i) {
;             const float n0r = fmaf(are[0], sre0, fmaf(-aim[0], sim0, bu0[i])), n0i = fmaf(are[0], sim0, fmaf(aim[0], sre0, bu1[i]));
;             sre0 = n0r; sim0 = n0i;
;             asm volatile("" : "+v"(sre0), "+v"(sim0));
;             const float n1r = fmaf(are[1], sre1, fmaf(-aim[1], sim1, bu2[i])), n1i = fmaf(are[1], sim1, fmaf(aim[1], sre1, bu3[i]));
;             sre1 = n1r; sim1 = n1i;
;             asm volatile("" : "+v"(sre1), "+v"(sim1));
;             const int tau = dir ? 15 - i : i;
;             u32x2 w; w.x = cvtpk_s(sre0, sim0); w.y = cvtpk_s(sre1, sim1);
;             *(LAS u32x2*)(sst + tau * SST_PITCH + pl * 8) = w;
;         }
;         CFENCE();
; #pragma unroll
;         for (int sq = 0; sq < 2; ++sq) {
;             f32x4 acc = {0.f, 0.f, 0.f, 0.f};
; #pragma unroll
;             for (int kb = 0; kb < 4; ++kb) {
;                 const bf16x8 a = *(const LAS bf16x8*)(wl + sq * SST_BYTES + cc * SST_PITCH + (kb * 32 + q * 8) * 2);
;                 acc = __builtin_amdgcn_mfma_f32_16x16x32_bf16(cf[kb], a, acc, 0, 0, 0);
;             }
;             bf16_t* yp = Y + ((sq ? rowB : rowA) + tb + cc) * 512 + g * 16 + q * 4;
;             u32x2 yw; yw.x = cvtpk_s(acc[0], acc[1]); yw.y = cvtpk_s(acc[2], acc[3]);
;             *(u32x2*)yp = yw;
;         }
	v_mov_b64_e32 v[136:137], v[132:133]
	v_cvt_pk_bf16_f32 v34, v0, v2
	s_and_b64 vcc, exec, s[0:1]
	s_nop 3
	v_fma_f32 v18, v144, v52, v18
	v_fmac_f32_e32 v18, v143, v53
	v_mov_b64_e32 v[134:135], v[130:131]
	v_cvt_pk_bf16_f32 v35, v36, v18
	ds_write_b64 v192, v[34:35]
	v_fma_f32 v34, -v142, v2, v37
	v_fmac_f32_e32 v34, v173, v0
	v_fma_f32 v0, v142, v0, v3
	v_fmac_f32_e32 v0, v173, v2
	v_fma_f32 v35, -v144, v18, v55
	v_fma_f32 v19, v144, v36, v19
	v_fmac_f32_e32 v35, v143, v36
	v_fmac_f32_e32 v19, v143, v18
	v_fma_f32 v18, -v142, v0, v38
	v_fma_f32 v4, v142, v34, v4
	v_cvt_pk_bf16_f32 v2, v34, v0
	v_cvt_pk_bf16_f32 v3, v35, v19
	v_fmac_f32_e32 v18, v173, v34
	v_fmac_f32_e32 v4, v173, v0
	v_fma_f32 v0, -v144, v19, v56
	v_fma_f32 v20, v144, v35, v20
	ds_write_b64 v192, v[2:3] offset:272
	v_fmac_f32_e32 v0, v143, v35
	v_fmac_f32_e32 v20, v143, v19
	v_fma_f32 v5, v142, v18, v5
	v_cvt_pk_bf16_f32 v2, v18, v4
	v_fma_f32 v19, -v142, v4, v39
	v_fmac_f32_e32 v5, v173, v4
	v_fma_f32 v4, -v144, v20, v57
	v_cvt_pk_bf16_f32 v3, v0, v20
	v_fmac_f32_e32 v19, v173, v18
	v_fmac_f32_e32 v4, v143, v0
	v_fma_f32 v0, v144, v0, v21
	ds_write_b64 v192, v[2:3] offset:544
	v_fmac_f32_e32 v0, v143, v20
	v_fma_f32 v6, v142, v19, v6
	v_cvt_pk_bf16_f32 v2, v19, v5
	v_fma_f32 v18, -v142, v5, v40
	v_fmac_f32_e32 v6, v173, v5
	v_fma_f32 v5, -v144, v0, v58
	v_cvt_pk_bf16_f32 v3, v4, v0
	v_fmac_f32_e32 v18, v173, v19
	v_fmac_f32_e32 v5, v143, v4
	v_fma_f32 v4, v144, v4, v22
	ds_write_b64 v192, v[2:3] offset:816
	v_fmac_f32_e32 v4, v143, v0
	v_fma_f32 v7, v142, v18, v7
	v_cvt_pk_bf16_f32 v2, v18, v6
	v_fma_f32 v0, -v142, v6, v41
	v_fmac_f32_e32 v7, v173, v6
	v_fma_f32 v6, -v144, v4, v59
	v_cvt_pk_bf16_f32 v3, v5, v4
	v_fmac_f32_e32 v0, v173, v18
	v_fmac_f32_e32 v6, v143, v5
	v_fma_f32 v5, v144, v5, v23
	ds_write_b64 v192, v[2:3] offset:1088
	v_fmac_f32_e32 v5, v143, v4
	v_fma_f32 v4, -v142, v7, v42
	v_cvt_pk_bf16_f32 v2, v0, v7
	v_fmac_f32_e32 v4, v173, v0
	v_fma_f32 v0, v142, v0, v8
	v_fmac_f32_e32 v0, v173, v7
	v_fma_f32 v7, -v144, v5, v60
	v_cvt_pk_bf16_f32 v3, v6, v5
	v_fmac_f32_e32 v7, v143, v6
	v_fma_f32 v6, v144, v6, v24
	ds_write_b64 v192, v[2:3] offset:1360
	v_fmac_f32_e32 v6, v143, v5
	v_fma_f32 v5, -v142, v0, v43
	v_cvt_pk_bf16_f32 v2, v4, v0
	v_fmac_f32_e32 v5, v173, v4
	v_fma_f32 v4, v142, v4, v9
	v_fmac_f32_e32 v4, v173, v0
	v_fma_f32 v0, -v144, v6, v61
	v_cvt_pk_bf16_f32 v3, v7, v6
	v_fmac_f32_e32 v0, v143, v7
	v_fma_f32 v7, v144, v7, v25
	ds_write_b64 v192, v[2:3] offset:1632
	v_fmac_f32_e32 v7, v143, v6
	v_fma_f32 v6, -v142, v4, v44
	v_cvt_pk_bf16_f32 v2, v5, v4
	v_fmac_f32_e32 v6, v173, v5
	v_fma_f32 v5, v142, v5, v10
	v_fmac_f32_e32 v5, v173, v4
	v_fma_f32 v4, -v144, v7, v62
	v_cvt_pk_bf16_f32 v3, v0, v7
	v_fmac_f32_e32 v4, v143, v0
	v_fma_f32 v0, v144, v0, v26
	ds_write_b64 v192, v[2:3] offset:1904
	v_fmac_f32_e32 v0, v143, v7
	v_fma_f32 v7, -v142, v5, v45
	v_cvt_pk_bf16_f32 v2, v6, v5
	v_fmac_f32_e32 v7, v173, v6
	v_fma_f32 v6, v142, v6, v11
	v_fmac_f32_e32 v6, v173, v5
	v_fma_f32 v5, -v144, v0, v63
	v_cvt_pk_bf16_f32 v3, v4, v0
	v_fmac_f32_e32 v5, v143, v4
	v_fma_f32 v4, v144, v4, v27
	ds_write_b64 v192, v[2:3] offset:2176
	v_fmac_f32_e32 v4, v143, v0
	v_fma_f32 v0, -v142, v6, v46
	v_cvt_pk_bf16_f32 v2, v7, v6
	v_fmac_f32_e32 v0, v173, v7
	v_fma_f32 v7, v142, v7, v12
	v_fmac_f32_e32 v7, v173, v6
	v_fma_f32 v6, -v144, v4, v64
	v_cvt_pk_bf16_f32 v3, v5, v4
	v_fmac_f32_e32 v6, v143, v5
	v_fma_f32 v5, v144, v5, v28
	ds_write_b64 v192, v[2:3] offset:2448
	v_fmac_f32_e32 v5, v143, v4
	v_fma_f32 v4, -v142, v7, v47
	v_cvt_pk_bf16_f32 v2, v0, v7
	v_fmac_f32_e32 v4, v173, v0
	v_fma_f32 v0, v142, v0, v13
	v_fmac_f32_e32 v0, v173, v7
	v_fma_f32 v7, -v144, v5, v65
	v_cvt_pk_bf16_f32 v3, v6, v5
	v_fmac_f32_e32 v7, v143, v6
	v_fma_f32 v6, v144, v6, v29
	ds_write_b64 v192, v[2:3] offset:2720
	v_fmac_f32_e32 v6, v143, v5
	v_fma_f32 v5, -v142, v0, v48
	v_cvt_pk_bf16_f32 v2, v4, v0
	v_fmac_f32_e32 v5, v173, v4
	v_fma_f32 v4, v142, v4, v14
	v_fmac_f32_e32 v4, v173, v0
	v_fma_f32 v0, -v144, v6, v66
	v_cvt_pk_bf16_f32 v3, v7, v6
	v_fmac_f32_e32 v0, v143, v7
	v_fma_f32 v7, v144, v7, v30
	ds_write_b64 v192, v[2:3] offset:2992
	v_fmac_f32_e32 v7, v143, v6
	v_fma_f32 v6, -v142, v4, v49
	v_cvt_pk_bf16_f32 v2, v5, v4
	v_fmac_f32_e32 v6, v173, v5
	v_fma_f32 v5, v142, v5, v15
	v_fmac_f32_e32 v5, v173, v4
	v_fma_f32 v4, -v144, v7, v67
	v_cvt_pk_bf16_f32 v3, v0, v7
	v_fmac_f32_e32 v4, v143, v0
	v_fma_f32 v0, v144, v0, v31
	ds_write_b64 v192, v[2:3] offset:3264
	v_fmac_f32_e32 v0, v143, v7
	v_fma_f32 v7, -v142, v5, v50
	v_cvt_pk_bf16_f32 v2, v6, v5
	v_fmac_f32_e32 v7, v173, v6
	v_fma_f32 v6, v142, v6, v16
	v_fmac_f32_e32 v6, v173, v5
	v_fma_f32 v5, -v144, v0, v68
	v_cvt_pk_bf16_f32 v3, v4, v0
	v_fmac_f32_e32 v5, v143, v4
	v_fma_f32 v4, v144, v4, v32
	v_fmac_f32_e32 v4, v143, v0
	ds_write_b64 v192, v[2:3] offset:3536
	v_or_b32_e32 v0, s2, v195
	v_fma_f32 v28, -v142, v6, v51
	v_fmac_f32_e32 v17, v142, v7
	v_fma_f32 v24, -v144, v4, v69
	v_fmac_f32_e32 v33, v144, v5
	v_cvt_pk_bf16_f32 v2, v7, v6
	v_cvt_pk_bf16_f32 v3, v5, v4
	v_fmac_f32_e32 v28, v173, v7
	v_fmac_f32_e32 v17, v173, v6
	v_fmac_f32_e32 v24, v143, v5
	v_fmac_f32_e32 v33, v143, v4
	ds_write_b64 v192, v[2:3] offset:3808
	v_lshl_add_u64 v[14:15], s[62:63], 0, v[0:1]
	v_cvt_pk_bf16_f32 v2, v28, v17
	v_cvt_pk_bf16_f32 v3, v24, v33
	ds_write_b64 v192, v[2:3] offset:4080
	ds_read_b128 v[2:5], v145
	ds_read_b128 v[6:9], v145 offset:64
	ds_read_b128 v[206:209], v145 offset:128
	ds_read_b128 v[210:213], v145 offset:192
	s_waitcnt lgkmcnt(3)
	v_mfma_f32_16x16x32_bf16 v[2:5], v[102:105], v[2:5], 0
	s_add_i32 s2, s2, 64
	s_waitcnt lgkmcnt(2)
	v_mfma_f32_16x16x32_bf16 v[2:5], v[106:109], v[6:9], v[2:5]
	s_waitcnt lgkmcnt(1)
	v_mfma_f32_16x16x32_bf16 v[2:5], v[110:113], v[206:209], v[2:5]
	s_waitcnt lgkmcnt(0)
	v_mfma_f32_16x16x32_bf16 v[2:5], v[114:117], v[210:213], v[2:5]
	ds_read_b128 v[6:9], v145 offset:4352
	ds_read_b128 v[10:13], v145 offset:4416
	ds_read_b128 v[214:217], v145 offset:4480
	ds_read_b128 v[218:221], v145 offset:4544
	s_waitcnt lgkmcnt(3)
	v_mfma_f32_16x16x32_bf16 v[6:9], v[102:105], v[6:9], 0
	s_nop 2
	v_cvt_pk_bf16_f32 v2, v2, v3
	v_cvt_pk_bf16_f32 v3, v4, v5
	s_waitcnt lgkmcnt(2)
	v_mfma_f32_16x16x32_bf16 v[6:9], v[106:109], v[10:13], v[6:9]
	v_lshlrev_b64 v[10:11], 10, v[14:15]
	v_lshl_add_u64 v[14:15], v[146:147], 0, v[10:11]
	s_waitcnt lgkmcnt(1)
	v_mfma_f32_16x16x32_bf16 v[6:9], v[110:113], v[214:217], v[6:9]
	global_store_dwordx2 v[14:15], v[2:3], off
	v_mov_b64_e32 v[20:21], v[122:123]
	v_mov_b64_e32 v[22:23], v[124:125]
	s_waitcnt lgkmcnt(0)
	v_mfma_f32_16x16x32_bf16 v[2:5], v[114:117], v[218:221], v[6:9]
	s_nop 2
	v_lshl_add_u64 v[6:7], s[64:65], 0, v[0:1]
	v_lshlrev_b64 v[6:7], 10, v[6:7]
	v_lshl_add_u64 v[6:7], v[146:147], 0, v[6:7]
	s_nop 1
	v_cvt_pk_bf16_f32 v2, v2, v3
	v_cvt_pk_bf16_f32 v3, v4, v5
	global_store_dwordx2 v[6:7], v[2:3], off
	v_mov_b64_e32 v[2:3], v[118:119]
	v_mov_b64_e32 v[4:5], v[120:121]
	s_cbranch_vccnz .LBB0_220

; #define PG8_STAGE(bufoff, gbase, voff) do { _Pragma("unroll") for (int _i = 0; _i < 2; ++_i) \
;         __builtin_amdgcn_global_load_lds((const unsigned*)((const char*)(gbase) + (voff)[_i]), (PG8_LAS unsigned*)(lds + (bufoff) + ldsw + _i * 8192), 16, 0, 0); } while (0)
; #define PG8_LDA(dst, b, h) do { _Pragma("unroll") for (int m = 0; m < 4; ++m) _Pragma("unroll") for (int k = 0; k < 2; ++k) dst[m][k] = *(const PG8_LAS bf16x8*)(lds + PG8_SA(b, h) + aoff + m * 2048 + k * 1024); } while (0)
; #define PG8_BAR __builtin_amdgcn_s_barrier()
; template <class Epi, class Sched, bool ALIGN_EPI = false, bool SP2 = false>
; __device__ __forceinline__ void gemm_phase(PG8_LAS unsigned char* lds, const Gemm g, const Sched& S, const Epi& E) {
;     ...
;         const char* nA = has_next ? (const char*)g.A + (size_t)nxt.pm * tstep : cA; const char* nB = has_next ? (const char*)g.Bt + (size_t)nxt.pn * tstep : cB;
;         for (int t = 0; t < nt; t += 2) {
;             const bool last = (t == nt - 2);
;             const char* a1 = cA + (size_t)(t + 1) * kstep;
;             const char* a2 = last ? nA : cA + (size_t)(t + 2) * kstep; const char* b2 = last ? nB : cB + (size_t)(t + 2) * kstep;
;             const char* a3 = a2 + kstep; const char* b3 = b2 + kstep;
;             if (last && has_next) S.a_ready(nxt);
;             if constexpr (SP2) {
;             PG8_LDB(B0, 0, 0); PG8_LDB(B1, 0, 1); PG8_SCHED; PG8_LDA(At, 0, 0); PG8_STAGE(PG8_SA(1, 1), a1 + hstep, voffA);
;             PG8_WAIT_V(8); PG8_WAIT_L(0); PG8_BAR; PG8_MMA(0, 0, At, B0); PG8_MMA(0, 1, At, B1); PG8_BAR; PG8_SCHED;
;             PG8_LDA(At, 0, 1); PG8_STAGE(PG8_SB(0, 0), b2, voffB); PG8_STAGE(PG8_SB(0, 1), b2 + hstep, voffB); PG8_STAGE(PG8_SA(0, 0), a2, voffA);
;             PG8_WAIT_V(8); PG8_WAIT_L(0); PG8_BAR; PG8_MMA(1, 0, At, B0); PG8_MMA(1, 1, At, B1); PG8_BAR; PG8_SCHED;
;             PG8_LDB(B0, 1, 0); PG8_LDB(B1, 1, 1); PG8_SCHED; PG8_LDA(At, 1, 0); PG8_STAGE(PG8_SA(0, 1), a2 + hstep, voffA);
;             PG8_WAIT_V(8); PG8_WAIT_L(0); PG8_BAR; PG8_MMA(0, 0, At, B0); PG8_MMA(0, 1, At, B1); PG8_BAR; PG8_SCHED;
;             PG8_LDA(At, 1, 1); PG8_STAGE(PG8_SB(1, 0), b3, voffB); PG8_STAGE(PG8_SB(1, 1), b3 + hstep, voffB); PG8_STAGE(PG8_SA(1, 0), a3, voffA);
;             PG8_WAIT_V(8); PG8_WAIT_L(0); PG8_BAR; PG8_MMA(1, 0, At, B0); PG8_MMA(1, 1, At, B1); PG8_BAR; PG8_SCHED;
.LBB0_370:
	s_ashr_i32 s23, s22, 31
	s_lshl_b64 s[46:47], s[22:23], 19
	s_add_u32 s46, s73, s46
	s_addc_u32 s47, s72, s47
	s_and_b64 s[48:49], s[40:41], exec
	s_cselect_b32 s1, s47, s51
	s_cselect_b32 s11, s46, s50
	s_ashr_i32 s19, s18, 31
	s_lshl_b64 s[48:49], s[18:19], 19
	s_add_u32 s48, s75, s48
	s_addc_u32 s49, s74, s49
	s_and_b64 s[52:53], s[40:41], exec
	s_cselect_b32 s19, s49, s25
	s_cselect_b32 s23, s48, s24
	s_add_u32 s50, s50, 0x40080
	s_addc_u32 s51, s51, 0
	s_add_u32 s35, s24, 0x100
	s_addc_u32 s86, s25, 0
	s_mov_b32 s87, -2
	s_add_u32 s24, s50, 0xfffc0080
	s_addc_u32 s25, s51, -1
	s_add_i32 s88, 0, 0x10000
	s_cmp_eq_u32 s87, 12
	s_cselect_b32 s53, s1, s25
	s_cselect_b32 s52, s11, s24
	s_cselect_b32 s25, s19, s86
	s_cselect_b32 s24, s23, s35
	s_add_i32 s90, 0, 0x14000
	v_add_u32_e32 v142, s88, v191
	v_add_u32_e32 v170, s90, v191
	ds_read_b128 v[130:133], v142
	ds_read_b128 v[134:137], v142 offset:1024
	ds_read_b128 v[138:141], v142 offset:2048
	ds_read_b128 v[142:145], v142 offset:3072
	ds_read_b128 v[146:149], v170
	ds_read_b128 v[150:153], v170 offset:1024
	ds_read_b128 v[166:169], v170 offset:2048
	ds_read_b128 v[170:173], v170 offset:3072
	v_lshl_add_u64 v[186:187], s[50:51], 0, v[162:163]
	s_add_i32 m0, s3, 0xc000
	ds_read_b128 v[174:177], v195
	ds_read_b128 v[178:181], v195 offset:1024
	ds_read_b128 v[182:185], v195 offset:2048
	ds_read_b128 v[196:199], v195 offset:3072
	ds_read_b128 v[206:209], v195 offset:4096
	ds_read_b128 v[210:213], v195 offset:5120
	ds_read_b128 v[214:217], v195 offset:6144
	ds_read_b128 v[218:221], v195 offset:7168
	global_load_lds_dwordx4 v[186:187], off
	v_lshl_add_u64 v[186:187], s[50:51], 0, v[164:165]
	s_add_i32 m0, s3, 0xe000
	s_nop 0
	global_load_lds_dwordx4 v[186:187], off
	s_waitcnt vmcnt(8)
	s_waitcnt lgkmcnt(0)
	s_barrier
	s_setprio 1
	v_mfma_f32_16x16x32_bf16 v[126:129], v[130:133], v[174:177], 0
	v_mfma_f32_16x16x32_bf16 v[122:125], v[138:141], v[174:177], 0
	v_mfma_f32_16x16x32_bf16 v[110:113], v[130:133], v[182:185], 0
	v_mfma_f32_16x16x32_bf16 v[106:109], v[138:141], v[182:185], 0
	v_mfma_f32_16x16x32_bf16 v[94:97], v[130:133], v[206:209], 0
	v_mfma_f32_16x16x32_bf16 v[90:93], v[138:141], v[206:209], 0
	v_mfma_f32_16x16x32_bf16 v[78:81], v[130:133], v[214:217], 0
	v_mfma_f32_16x16x32_bf16 v[74:77], v[138:141], v[214:217], 0
	v_mfma_f32_16x16x32_bf16 v[126:129], v[134:137], v[178:181], v[126:129]
	v_mfma_f32_16x16x32_bf16 v[122:125], v[142:145], v[178:181], v[122:125]
	v_mfma_f32_16x16x32_bf16 v[110:113], v[134:137], v[196:199], v[110:113]
	v_mfma_f32_16x16x32_bf16 v[106:109], v[142:145], v[196:199], v[106:109]
	v_mfma_f32_16x16x32_bf16 v[94:97], v[134:137], v[210:213], v[94:97]
	v_mfma_f32_16x16x32_bf16 v[90:93], v[142:145], v[210:213], v[90:93]
	v_mfma_f32_16x16x32_bf16 v[78:81], v[134:137], v[218:221], v[78:81]
	v_mfma_f32_16x16x32_bf16 v[74:77], v[142:145], v[218:221], v[74:77]
	v_mfma_f32_16x16x32_bf16 v[118:121], v[146:149], v[174:177], 0
	v_mfma_f32_16x16x32_bf16 v[114:117], v[166:169], v[174:177], 0
	v_mfma_f32_16x16x32_bf16 v[102:105], v[146:149], v[182:185], 0
	v_mfma_f32_16x16x32_bf16 v[98:101], v[166:169], v[182:185], 0
	v_mfma_f32_16x16x32_bf16 v[86:89], v[146:149], v[206:209], 0
	v_mfma_f32_16x16x32_bf16 v[82:85], v[166:169], v[206:209], 0
	v_mfma_f32_16x16x32_bf16 v[70:73], v[146:149], v[214:217], 0
	v_mfma_f32_16x16x32_bf16 v[66:69], v[166:169], v[214:217], 0
	v_mfma_f32_16x16x32_bf16 v[118:121], v[150:153], v[178:181], v[118:121]
	v_mfma_f32_16x16x32_bf16 v[114:117], v[170:173], v[178:181], v[114:117]
	v_mfma_f32_16x16x32_bf16 v[102:105], v[150:153], v[196:199], v[102:105]
	v_mfma_f32_16x16x32_bf16 v[98:101], v[170:173], v[196:199], v[98:101]
	v_mfma_f32_16x16x32_bf16 v[86:89], v[150:153], v[210:213], v[86:89]
	v_mfma_f32_16x16x32_bf16 v[82:85], v[170:173], v[210:213], v[82:85]
	v_mfma_f32_16x16x32_bf16 v[70:73], v[150:153], v[218:221], v[70:73]
	v_mfma_f32_16x16x32_bf16 v[66:69], v[170:173], v[218:221], v[66:69]
	s_setprio 0
	s_barrier
	s_add_i32 s88, s88, s76
	v_lshl_add_u64 v[186:187], s[24:25], 0, v[0:1]
	s_mov_b32 m0, s88
	ds_read_b128 v[174:177], v195 offset:16384
	ds_read_b128 v[178:181], v195 offset:17408
	ds_read_b128 v[182:185], v195 offset:18432
	ds_read_b128 v[196:199], v195 offset:19456
	ds_read_b128 v[206:209], v195 offset:20480
	ds_read_b128 v[210:213], v195 offset:21504
	ds_read_b128 v[214:217], v195 offset:22528
	ds_read_b128 v[218:221], v195 offset:23552
	global_load_lds_dwordx4 v[186:187], off
	s_add_i32 m0, s88, 0x2000
	s_add_u32 s88, s24, 0x40000
	v_lshl_add_u64 v[200:201], s[24:25], 0, v[158:159]
	s_addc_u32 s89, s25, 0
	s_add_i32 s90, s90, s76
	global_load_lds_dwordx4 v[200:201], off
	v_lshl_add_u64 v[222:223], s[88:89], 0, v[0:1]
	s_mov_b32 m0, s90
	v_lshl_add_u64 v[224:225], s[52:53], 0, v[156:157]
	global_load_lds_dwordx4 v[222:223], off
	v_lshl_add_u64 v[222:223], s[88:89], 0, v[158:159]
	s_add_i32 m0, s90, 0x2000
	s_nop 0
	global_load_lds_dwordx4 v[222:223], off
	v_lshl_add_u64 v[222:223], s[52:53], 0, v[154:155]
	s_mov_b32 m0, s3
	s_nop 0
	global_load_lds_dwordx4 v[222:223], off
	s_mov_b32 m0, s79
	s_nop 0
	global_load_lds_dwordx4 v[224:225], off
	s_waitcnt vmcnt(8)
	s_waitcnt lgkmcnt(0)
	s_barrier
; #define PG8_STAGE(bufoff, gbase, voff) do { _Pragma("unroll") for (int _i = 0; _i < 2; ++_i) \
;         __builtin_amdgcn_global_load_lds((const unsigned*)((const char*)(gbase) + (voff)[_i]), (PG8_LAS unsigned*)(lds + (bufoff) + ldsw + _i * 8192), 16, 0, 0); } while (0)
; #define PG8_LDA(dst, b, h) do { _Pragma("unroll") for (int m = 0; m < 4; ++m) _Pragma("unroll") for (int k = 0; k < 2; ++k) dst[m][k] = *(const PG8_LAS bf16x8*)(lds + PG8_SA(b, h) + aoff + m * 2048 + k * 1024); } while (0)
; #define PG8_LDB(dst, b, h) do { _Pragma("unroll") for (int n = 0; n < 2; ++n) _Pragma("unroll") for (int k = 0; k < 2; ++k) dst[n][k] = *(const PG8_LAS bf16x8*)(lds + PG8_SB(b, h) + boff + n * 2048 + k * 1024); } while (0)
; #define PG8_MMA(ai, bj, At, Bt) do { __builtin_amdgcn_s_setprio(1); _Pragma("unroll") for (int m = 0; m < 4; ++m) _Pragma("unroll") for (int n = 0; n < 2; ++n) _Pragma("unroll") for (int k = 0; k < 2; ++k) \
;         acc[ai][bj][m][n] = __builtin_amdgcn_mfma_f32_16x16x32_bf16(Bt[n][k], At[m][k], acc[ai][bj][m][n], 0, 0, 0); __builtin_amdgcn_s_setprio(0); } while (0)
; #define PG8_WAIT_V(n) asm volatile("s_waitcnt vmcnt(" #n ")" ::: "memory")
; #define PG8_WAIT_L(n) asm volatile("s_waitcnt lgkmcnt(" #n ")" ::: "memory")
; #define PG8_BAR __builtin_amdgcn_s_barrier()
; #define PG8_SCHED __builtin_amdgcn_sched_barrier(0)
; template <class Epi, class Sched, bool ALIGN_EPI = false, bool SP2 = false>
; __device__ __forceinline__ void gemm_phase(PG8_LAS unsigned char* lds, const Gemm g, const Sched& S, const Epi& E) {
;     ...
;             PG8_LDB(B0, 0, 0); PG8_LDB(B1, 0, 1); PG8_SCHED; PG8_LDA(At, 0, 0); PG8_STAGE(PG8_SA(1, 1), a1 + hstep, voffA);
;             PG8_WAIT_V(8); PG8_WAIT_L(0); PG8_BAR; PG8_MMA(0, 0, At, B0); PG8_MMA(0, 1, At, B1); PG8_BAR; PG8_SCHED;
;             PG8_LDA(At, 0, 1); PG8_STAGE(PG8_SB(0, 0), b2, voffB); PG8_STAGE(PG8_SB(0, 1), b2 + hstep, voffB); PG8_STAGE(PG8_SA(0, 0), a2, voffA);
;             PG8_WAIT_V(8); PG8_WAIT_L(0); PG8_BAR; PG8_MMA(1, 0, At, B0); PG8_MMA(1, 1, At, B1); PG8_BAR; PG8_SCHED;
;             PG8_LDB(B0, 1, 0); PG8_LDB(B1, 1, 1); PG8_SCHED; PG8_LDA(At, 1, 0); PG8_STAGE(PG8_SA(0, 1), a2 + hstep, voffA);
;             PG8_WAIT_V(8); PG8_WAIT_L(0); PG8_BAR; PG8_MMA(0, 0, At, B0); PG8_MMA(0, 1, At, B1); PG8_BAR; PG8_SCHED;
	s_setprio 1
	v_mfma_f32_16x16x32_bf16 v[62:65], v[130:133], v[174:177], 0
	v_mfma_f32_16x16x32_bf16 v[58:61], v[138:141], v[174:177], 0
	v_mfma_f32_16x16x32_bf16 v[46:49], v[130:133], v[182:185], 0
	v_mfma_f32_16x16x32_bf16 v[42:45], v[138:141], v[182:185], 0
	v_mfma_f32_16x16x32_bf16 v[30:33], v[130:133], v[206:209], 0
	v_mfma_f32_16x16x32_bf16 v[26:29], v[138:141], v[206:209], 0
	v_mfma_f32_16x16x32_bf16 v[14:17], v[130:133], v[214:217], 0
	v_mfma_f32_16x16x32_bf16 v[10:13], v[138:141], v[214:217], 0
	v_mfma_f32_16x16x32_bf16 v[62:65], v[134:137], v[178:181], v[62:65]
	v_mfma_f32_16x16x32_bf16 v[58:61], v[142:145], v[178:181], v[58:61]
	v_mfma_f32_16x16x32_bf16 v[46:49], v[134:137], v[196:199], v[46:49]
	v_mfma_f32_16x16x32_bf16 v[42:45], v[142:145], v[196:199], v[42:45]
	v_mfma_f32_16x16x32_bf16 v[30:33], v[134:137], v[210:213], v[30:33]
	v_mfma_f32_16x16x32_bf16 v[26:29], v[142:145], v[210:213], v[26:29]
	v_mfma_f32_16x16x32_bf16 v[14:17], v[134:137], v[218:221], v[14:17]
	v_mfma_f32_16x16x32_bf16 v[10:13], v[142:145], v[218:221], v[10:13]
	v_mfma_f32_16x16x32_bf16 v[54:57], v[146:149], v[174:177], 0
	v_mfma_f32_16x16x32_bf16 v[50:53], v[166:169], v[174:177], 0
	v_mfma_f32_16x16x32_bf16 v[38:41], v[146:149], v[182:185], 0
	v_mfma_f32_16x16x32_bf16 v[34:37], v[166:169], v[182:185], 0
	v_mfma_f32_16x16x32_bf16 v[22:25], v[146:149], v[206:209], 0
	v_mfma_f32_16x16x32_bf16 v[18:21], v[166:169], v[206:209], 0
	v_mfma_f32_16x16x32_bf16 v[6:9], v[146:149], v[214:217], 0
	v_mfma_f32_16x16x32_bf16 v[2:5], v[166:169], v[214:217], 0
	v_mfma_f32_16x16x32_bf16 v[54:57], v[150:153], v[178:181], v[54:57]
	v_mfma_f32_16x16x32_bf16 v[50:53], v[170:173], v[178:181], v[50:53]
	v_mfma_f32_16x16x32_bf16 v[38:41], v[150:153], v[196:199], v[38:41]
	v_mfma_f32_16x16x32_bf16 v[34:37], v[170:173], v[196:199], v[34:37]
	v_mfma_f32_16x16x32_bf16 v[22:25], v[150:153], v[210:213], v[22:25]
	v_mfma_f32_16x16x32_bf16 v[18:21], v[170:173], v[210:213], v[18:21]
	v_mfma_f32_16x16x32_bf16 v[6:9], v[150:153], v[218:221], v[6:9]
	v_mfma_f32_16x16x32_bf16 v[2:5], v[170:173], v[218:221], v[2:5]
	s_setprio 0
	s_barrier
	s_add_i32 s88, 0, 0x18000
	s_add_i32 s89, 0, 0x1c000
	v_add_u32_e32 v142, s88, v191
	v_add_u32_e32 v170, s89, v191
	ds_read_b128 v[130:133], v142
	ds_read_b128 v[134:137], v142 offset:1024
	ds_read_b128 v[138:141], v142 offset:2048
	ds_read_b128 v[142:145], v142 offset:3072
	ds_read_b128 v[146:149], v170
	ds_read_b128 v[150:153], v170 offset:1024
	ds_read_b128 v[166:169], v170 offset:2048
	ds_read_b128 v[170:173], v170 offset:3072
	s_add_u32 s52, s52, 0x40000
	s_addc_u32 s53, s53, 0
	s_mov_b32 m0, s80
	v_lshl_add_u64 v[226:227], s[52:53], 0, v[154:155]
	ds_read_b128 v[174:177], v195 offset:32768
	ds_read_b128 v[178:181], v195 offset:33792
	ds_read_b128 v[182:185], v195 offset:34816
	ds_read_b128 v[196:199], v195 offset:35840
	ds_read_b128 v[206:209], v195 offset:36864
	ds_read_b128 v[210:213], v195 offset:37888
	ds_read_b128 v[214:217], v195 offset:38912
	ds_read_b128 v[218:221], v195 offset:39936
	global_load_lds_dwordx4 v[226:227], off
	v_lshl_add_u64 v[226:227], s[52:53], 0, v[156:157]
	s_mov_b32 m0, s81
	s_nop 0
	global_load_lds_dwordx4 v[226:227], off
	s_waitcnt vmcnt(8)
	s_waitcnt lgkmcnt(0)
	s_barrier
	s_setprio 1
	v_mfma_f32_16x16x32_bf16 v[126:129], v[130:133], v[174:177], v[126:129]
	v_mfma_f32_16x16x32_bf16 v[122:125], v[138:141], v[174:177], v[122:125]
	v_mfma_f32_16x16x32_bf16 v[110:113], v[130:133], v[182:185], v[110:113]
	v_mfma_f32_16x16x32_bf16 v[106:109], v[138:141], v[182:185], v[106:109]
	v_mfma_f32_16x16x32_bf16 v[94:97], v[130:133], v[206:209], v[94:97]
	v_mfma_f32_16x16x32_bf16 v[90:93], v[138:141], v[206:209], v[90:93]
	v_mfma_f32_16x16x32_bf16 v[78:81], v[130:133], v[214:217], v[78:81]
	v_mfma_f32_16x16x32_bf16 v[74:77], v[138:141], v[214:217], v[74:77]
	v_mfma_f32_16x16x32_bf16 v[126:129], v[134:137], v[178:181], v[126:129]
	v_mfma_f32_16x16x32_bf16 v[122:125], v[142:145], v[178:181], v[122:125]
	v_mfma_f32_16x16x32_bf16 v[110:113], v[134:137], v[196:199], v[110:113]
	v_mfma_f32_16x16x32_bf16 v[106:109], v[142:145], v[196:199], v[106:109]
	v_mfma_f32_16x16x32_bf16 v[94:97], v[134:137], v[210:213], v[94:97]
	v_mfma_f32_16x16x32_bf16 v[90:93], v[142:145], v[210:213], v[90:93]
	v_mfma_f32_16x16x32_bf16 v[78:81], v[134:137], v[218:221], v[78:81]
	v_mfma_f32_16x16x32_bf16 v[74:77], v[142:145], v[218:221], v[74:77]
	v_mfma_f32_16x16x32_bf16 v[118:121], v[146:149], v[174:177], v[118:121]
	v_mfma_f32_16x16x32_bf16 v[114:117], v[166:169], v[174:177], v[114:117]
	v_mfma_f32_16x16x32_bf16 v[102:105], v[146:149], v[182:185], v[102:105]
	v_mfma_f32_16x16x32_bf16 v[98:101], v[166:169], v[182:185], v[98:101]
	v_mfma_f32_16x16x32_bf16 v[86:89], v[146:149], v[206:209], v[86:89]
	v_mfma_f32_16x16x32_bf16 v[82:85], v[166:169], v[206:209], v[82:85]
	v_mfma_f32_16x16x32_bf16 v[70:73], v[146:149], v[214:217], v[70:73]
	v_mfma_f32_16x16x32_bf16 v[66:69], v[166:169], v[214:217], v[66:69]
	v_mfma_f32_16x16x32_bf16 v[118:121], v[150:153], v[178:181], v[118:121]
	v_mfma_f32_16x16x32_bf16 v[114:117], v[170:173], v[178:181], v[114:117]
	v_mfma_f32_16x16x32_bf16 v[102:105], v[150:153], v[196:199], v[102:105]
	v_mfma_f32_16x16x32_bf16 v[98:101], v[170:173], v[196:199], v[98:101]
	v_mfma_f32_16x16x32_bf16 v[86:89], v[150:153], v[210:213], v[86:89]
	v_mfma_f32_16x16x32_bf16 v[82:85], v[170:173], v[210:213], v[82:85]
	v_mfma_f32_16x16x32_bf16 v[70:73], v[150:153], v[218:221], v[70:73]
	v_mfma_f32_16x16x32_bf16 v[66:69], v[170:173], v[218:221], v[66:69]
	s_setprio 0
	s_barrier
; #define PG8_STAGE(bufoff, gbase, voff) do { _Pragma("unroll") for (int _i = 0; _i < 2; ++_i) \
;         __builtin_amdgcn_global_load_lds((const unsigned*)((const char*)(gbase) + (voff)[_i]), (PG8_LAS unsigned*)(lds + (bufoff) + ldsw + _i * 8192), 16, 0, 0); } while (0)
; #define PG8_LDA(dst, b, h) do { _Pragma("unroll") for (int m = 0; m < 4; ++m) _Pragma("unroll") for (int k = 0; k < 2; ++k) dst[m][k] = *(const PG8_LAS bf16x8*)(lds + PG8_SA(b, h) + aoff + m * 2048 + k * 1024); } while (0)
; #define PG8_MMA(ai, bj, At, Bt) do { __builtin_amdgcn_s_setprio(1); _Pragma("unroll") for (int m = 0; m < 4; ++m) _Pragma("unroll") for (int n = 0; n < 2; ++n) _Pragma("unroll") for (int k = 0; k < 2; ++k) \
;         acc[ai][bj][m][n] = __builtin_amdgcn_mfma_f32_16x16x32_bf16(Bt[n][k], At[m][k], acc[ai][bj][m][n], 0, 0, 0); __builtin_amdgcn_s_setprio(0); } while (0)
; #define PG8_WAIT_V(n) asm volatile("s_waitcnt vmcnt(" #n ")" ::: "memory")
; #define PG8_WAIT_L(n) asm volatile("s_waitcnt lgkmcnt(" #n ")" ::: "memory")
; #define PG8_BAR __builtin_amdgcn_s_barrier()
; #define PG8_SCHED __builtin_amdgcn_sched_barrier(0)
; template <class Epi, class Sched, bool ALIGN_EPI = false, bool SP2 = false>
; __device__ __forceinline__ void gemm_phase(PG8_LAS unsigned char* lds, const Gemm g, const Sched& S, const Epi& E) {
;     ...
;         for (int t = 0; t < nt; t += 2) {
;     ...
;             PG8_LDA(At, 1, 1); PG8_STAGE(PG8_SB(1, 0), b3, voffB); PG8_STAGE(PG8_SB(1, 1), b3 + hstep, voffB); PG8_STAGE(PG8_SA(1, 0), a3, voffA);
;             PG8_WAIT_V(8); PG8_WAIT_L(0); PG8_BAR; PG8_MMA(1, 0, At, B0); PG8_MMA(1, 1, At, B1); PG8_BAR; PG8_SCHED;
	s_add_i32 s52, s88, s76
	v_lshl_add_u64 v[186:187], v[186:187], 0, s[28:29]
	s_mov_b32 m0, s52
	ds_read_b128 v[174:177], v195 offset:49152
	ds_read_b128 v[178:181], v195 offset:50176
	ds_read_b128 v[182:185], v195 offset:51200
	ds_read_b128 v[196:199], v195 offset:52224
	ds_read_b128 v[206:209], v195 offset:53248
	ds_read_b128 v[210:213], v195 offset:54272
	ds_read_b128 v[214:217], v195 offset:55296
	ds_read_b128 v[218:221], v195 offset:56320
	global_load_lds_dwordx4 v[186:187], off
	s_add_i32 m0, s52, 0x2000
	s_add_u32 s24, s24, 0x40080
	v_lshl_add_u64 v[186:187], v[200:201], 0, s[28:29]
	s_addc_u32 s25, s25, 0
	s_add_i32 s52, s89, s76
	global_load_lds_dwordx4 v[186:187], off
	v_lshl_add_u64 v[186:187], s[24:25], 0, v[0:1]
	s_mov_b32 m0, s52
	s_nop 0
	global_load_lds_dwordx4 v[186:187], off
	v_lshl_add_u64 v[186:187], s[24:25], 0, v[158:159]
	s_add_i32 m0, s52, 0x2000
	s_nop 0
	global_load_lds_dwordx4 v[186:187], off
	v_lshl_add_u64 v[186:187], v[222:223], 0, s[28:29]
	s_mov_b32 m0, s83
	s_nop 0
	global_load_lds_dwordx4 v[186:187], off
	v_lshl_add_u64 v[186:187], v[224:225], 0, s[28:29]
	s_mov_b32 m0, s84
	s_nop 0
	global_load_lds_dwordx4 v[186:187], off
	s_waitcnt vmcnt(8)
	s_waitcnt lgkmcnt(0)
	s_barrier
	s_setprio 1
	v_mfma_f32_16x16x32_bf16 v[62:65], v[130:133], v[174:177], v[62:65]
	v_mfma_f32_16x16x32_bf16 v[58:61], v[138:141], v[174:177], v[58:61]
	v_mfma_f32_16x16x32_bf16 v[46:49], v[130:133], v[182:185], v[46:49]
	v_mfma_f32_16x16x32_bf16 v[42:45], v[138:141], v[182:185], v[42:45]
	v_mfma_f32_16x16x32_bf16 v[30:33], v[130:133], v[206:209], v[30:33]
	v_mfma_f32_16x16x32_bf16 v[26:29], v[138:141], v[206:209], v[26:29]
	v_mfma_f32_16x16x32_bf16 v[14:17], v[130:133], v[214:217], v[14:17]
	v_mfma_f32_16x16x32_bf16 v[10:13], v[138:141], v[214:217], v[10:13]
	v_mfma_f32_16x16x32_bf16 v[62:65], v[134:137], v[178:181], v[62:65]
	v_mfma_f32_16x16x32_bf16 v[58:61], v[142:145], v[178:181], v[58:61]
	v_mfma_f32_16x16x32_bf16 v[46:49], v[134:137], v[196:199], v[46:49]
	v_mfma_f32_16x16x32_bf16 v[42:45], v[142:145], v[196:199], v[42:45]
	v_mfma_f32_16x16x32_bf16 v[30:33], v[134:137], v[210:213], v[30:33]
	v_mfma_f32_16x16x32_bf16 v[26:29], v[142:145], v[210:213], v[26:29]
	v_mfma_f32_16x16x32_bf16 v[14:17], v[134:137], v[218:221], v[14:17]
	v_mfma_f32_16x16x32_bf16 v[10:13], v[142:145], v[218:221], v[10:13]
	v_mfma_f32_16x16x32_bf16 v[54:57], v[146:149], v[174:177], v[54:57]
	v_mfma_f32_16x16x32_bf16 v[50:53], v[166:169], v[174:177], v[50:53]
	v_mfma_f32_16x16x32_bf16 v[38:41], v[146:149], v[182:185], v[38:41]
	v_mfma_f32_16x16x32_bf16 v[34:37], v[166:169], v[182:185], v[34:37]
	v_mfma_f32_16x16x32_bf16 v[22:25], v[146:149], v[206:209], v[22:25]
	v_mfma_f32_16x16x32_bf16 v[18:21], v[166:169], v[206:209], v[18:21]
	v_mfma_f32_16x16x32_bf16 v[6:9], v[146:149], v[214:217], v[6:9]
	v_mfma_f32_16x16x32_bf16 v[2:5], v[166:169], v[214:217], v[2:5]
	v_mfma_f32_16x16x32_bf16 v[54:57], v[150:153], v[178:181], v[54:57]
	v_mfma_f32_16x16x32_bf16 v[50:53], v[170:173], v[178:181], v[50:53]
	v_mfma_f32_16x16x32_bf16 v[38:41], v[150:153], v[196:199], v[38:41]
	v_mfma_f32_16x16x32_bf16 v[34:37], v[170:173], v[196:199], v[34:37]
	v_mfma_f32_16x16x32_bf16 v[22:25], v[150:153], v[210:213], v[22:25]
	v_mfma_f32_16x16x32_bf16 v[18:21], v[170:173], v[210:213], v[18:21]
	v_mfma_f32_16x16x32_bf16 v[6:9], v[150:153], v[218:221], v[6:9]
	v_mfma_f32_16x16x32_bf16 v[2:5], v[170:173], v[218:221], v[2:5]
	s_setprio 0
	s_barrier
	s_add_i32 s87, s87, 2
	s_add_u32 s50, s50, 0x100
	s_addc_u32 s51, s51, 0
	s_add_u32 s35, s35, 0x100
	s_addc_u32 s86, s86, 0
	s_cmp_gt_u32 s87, 13

; #define PG8_STAGE(bufoff, gbase, voff) do { _Pragma("unroll") for (int _i = 0; _i < 2; ++_i) \
;         __builtin_amdgcn_global_load_lds((const unsigned*)((const char*)(gbase) + (voff)[_i]), (PG8_LAS unsigned*)(lds + (bufoff) + ldsw + _i * 8192), 16, 0, 0); } while (0)
; #define PG8_LDA(dst, b, h) do { _Pragma("unroll") for (int m = 0; m < 4; ++m) _Pragma("unroll") for (int k = 0; k < 2; ++k) dst[m][k] = *(const PG8_LAS bf16x8*)(lds + PG8_SA(b, h) + aoff + m * 2048 + k * 1024); } while (0)
; #define PG8_BAR __builtin_amdgcn_s_barrier()
; template <class Epi, class Sched, bool ALIGN_EPI = false, bool SP2 = false>
; __device__ __forceinline__ void gemm_phase(PG8_LAS unsigned char* lds, const Gemm g, const Sched& S, const Epi& E) {
;     ...
;         const char* nA = has_next ? (const char*)g.A + (size_t)nxt.pm * tstep : cA; const char* nB = has_next ? (const char*)g.Bt + (size_t)nxt.pn * tstep : cB;
;         for (int t = 0; t < nt; t += 2) {
;             const bool last = (t == nt - 2);
;             const char* a1 = cA + (size_t)(t + 1) * kstep;
;             const char* a2 = last ? nA : cA + (size_t)(t + 2) * kstep; const char* b2 = last ? nB : cB + (size_t)(t + 2) * kstep;
;             const char* a3 = a2 + kstep; const char* b3 = b2 + kstep;
;             if (last && has_next) S.a_ready(nxt);
;             if constexpr (SP2) {
;             PG8_LDB(B0, 0, 0); PG8_LDB(B1, 0, 1); PG8_SCHED; PG8_LDA(At, 0, 0); PG8_STAGE(PG8_SA(1, 1), a1 + hstep, voffA);
;             PG8_WAIT_V(8); PG8_WAIT_L(0); PG8_BAR; PG8_MMA(0, 0, At, B0); PG8_MMA(0, 1, At, B1); PG8_BAR; PG8_SCHED;
;             PG8_LDA(At, 0, 1); PG8_STAGE(PG8_SB(0, 0), b2, voffB); PG8_STAGE(PG8_SB(0, 1), b2 + hstep, voffB); PG8_STAGE(PG8_SA(0, 0), a2, voffA);
;             PG8_WAIT_V(8); PG8_WAIT_L(0); PG8_BAR; PG8_MMA(1, 0, At, B0); PG8_MMA(1, 1, At, B1); PG8_BAR; PG8_SCHED;
;             PG8_LDB(B0, 1, 0); PG8_LDB(B1, 1, 1); PG8_SCHED; PG8_LDA(At, 1, 0); PG8_STAGE(PG8_SA(0, 1), a2 + hstep, voffA);
;             PG8_WAIT_V(8); PG8_WAIT_L(0); PG8_BAR; PG8_MMA(0, 0, At, B0); PG8_MMA(0, 1, At, B1); PG8_BAR; PG8_SCHED;
;             PG8_LDA(At, 1, 1); PG8_STAGE(PG8_SB(1, 0), b3, voffB); PG8_STAGE(PG8_SB(1, 1), b3 + hstep, voffB); PG8_STAGE(PG8_SA(1, 0), a3, voffA);
;             PG8_WAIT_V(8); PG8_WAIT_L(0); PG8_BAR; PG8_MMA(1, 0, At, B0); PG8_MMA(1, 1, At, B1); PG8_BAR; PG8_SCHED;
.LBB0_418:
	s_add_u32 s44, s44, 0x80
	s_addc_u32 s45, s45, 0
	s_add_u32 s63, s24, 0x100
	s_addc_u32 s64, s25, 0
	s_mov_b32 s24, 0
	s_waitcnt vmcnt(0)
	s_add_i32 s65, s24, 2
	s_add_u32 s66, s44, 0x80
	s_addc_u32 s25, s45, 0
	s_add_i32 s68, 0, 0x10000
	s_cmp_eq_u32 s58, s24
	s_cselect_b32 s25, s9, s25
	s_cselect_b32 s24, s8, s66
	s_cselect_b32 s67, s41, s64
	s_cselect_b32 s66, s40, s63
	s_add_i32 s69, 0, 0x14000
	v_add_u32_e32 v142, s68, v210
	v_add_u32_e32 v158, s69, v210
	ds_read_b128 v[130:133], v142
	ds_read_b128 v[134:137], v142 offset:1024
	ds_read_b128 v[138:141], v142 offset:2048
	ds_read_b128 v[142:145], v142 offset:3072
	ds_read_b128 v[146:149], v158
	ds_read_b128 v[150:153], v158 offset:1024
	ds_read_b128 v[154:157], v158 offset:2048
	ds_read_b128 v[158:161], v158 offset:3072
	v_lshl_add_u64 v[216:217], s[44:45], 0, v[198:199]
	s_add_i32 m0, s17, 0xc000
	ds_read_b128 v[162:165], v211
	ds_read_b128 v[166:169], v211 offset:1024
	ds_read_b128 v[170:173], v211 offset:2048
	ds_read_b128 v[174:177], v211 offset:3072
	ds_read_b128 v[178:181], v211 offset:4096
	ds_read_b128 v[182:185], v211 offset:5120
	ds_read_b128 v[206:209], v211 offset:6144
	ds_read_b128 v[212:215], v211 offset:7168
	global_load_lds_dwordx4 v[216:217], off
	v_lshl_add_u64 v[216:217], s[44:45], 0, v[200:201]
	s_add_i32 m0, s17, 0xe000
	s_nop 0
	global_load_lds_dwordx4 v[216:217], off
	s_waitcnt vmcnt(8)
	s_waitcnt lgkmcnt(0)
	s_barrier
	s_setprio 1
	v_mfma_f32_16x16x32_bf16 v[118:121], v[130:133], v[162:165], 0
	v_mfma_f32_16x16x32_bf16 v[114:117], v[138:141], v[162:165], 0
	v_mfma_f32_16x16x32_bf16 v[110:113], v[130:133], v[170:173], 0
	v_mfma_f32_16x16x32_bf16 v[106:109], v[138:141], v[170:173], 0
	v_mfma_f32_16x16x32_bf16 v[94:97], v[130:133], v[178:181], 0
	v_mfma_f32_16x16x32_bf16 v[90:93], v[138:141], v[178:181], 0
	v_mfma_f32_16x16x32_bf16 v[78:81], v[130:133], v[206:209], 0
	v_mfma_f32_16x16x32_bf16 v[74:77], v[138:141], v[206:209], 0
	v_mfma_f32_16x16x32_bf16 v[118:121], v[134:137], v[166:169], v[118:121]
	v_mfma_f32_16x16x32_bf16 v[114:117], v[142:145], v[166:169], v[114:117]
	v_mfma_f32_16x16x32_bf16 v[110:113], v[134:137], v[174:177], v[110:113]
	v_mfma_f32_16x16x32_bf16 v[106:109], v[142:145], v[174:177], v[106:109]
	v_mfma_f32_16x16x32_bf16 v[94:97], v[134:137], v[182:185], v[94:97]
	v_mfma_f32_16x16x32_bf16 v[90:93], v[142:145], v[182:185], v[90:93]
	v_mfma_f32_16x16x32_bf16 v[78:81], v[134:137], v[212:215], v[78:81]
	v_mfma_f32_16x16x32_bf16 v[74:77], v[142:145], v[212:215], v[74:77]
	v_mfma_f32_16x16x32_bf16 v[126:129], v[146:149], v[162:165], 0
	v_mfma_f32_16x16x32_bf16 v[122:125], v[154:157], v[162:165], 0
	v_mfma_f32_16x16x32_bf16 v[102:105], v[146:149], v[170:173], 0
	v_mfma_f32_16x16x32_bf16 v[98:101], v[154:157], v[170:173], 0
	v_mfma_f32_16x16x32_bf16 v[86:89], v[146:149], v[178:181], 0
	v_mfma_f32_16x16x32_bf16 v[82:85], v[154:157], v[178:181], 0
	v_mfma_f32_16x16x32_bf16 v[70:73], v[146:149], v[206:209], 0
	v_mfma_f32_16x16x32_bf16 v[66:69], v[154:157], v[206:209], 0
	v_mfma_f32_16x16x32_bf16 v[126:129], v[150:153], v[166:169], v[126:129]
	v_mfma_f32_16x16x32_bf16 v[122:125], v[158:161], v[166:169], v[122:125]
	v_mfma_f32_16x16x32_bf16 v[102:105], v[150:153], v[174:177], v[102:105]
	v_mfma_f32_16x16x32_bf16 v[98:101], v[158:161], v[174:177], v[98:101]
	v_mfma_f32_16x16x32_bf16 v[86:89], v[150:153], v[182:185], v[86:89]
	v_mfma_f32_16x16x32_bf16 v[82:85], v[158:161], v[182:185], v[82:85]
	v_mfma_f32_16x16x32_bf16 v[70:73], v[150:153], v[212:215], v[70:73]
	v_mfma_f32_16x16x32_bf16 v[66:69], v[158:161], v[212:215], v[66:69]
	s_setprio 0
	s_barrier
	s_add_i32 s68, s68, s16
	v_lshl_add_u64 v[216:217], s[66:67], 0, v[0:1]
	s_mov_b32 m0, s68
	ds_read_b128 v[162:165], v211 offset:16384
	ds_read_b128 v[166:169], v211 offset:17408
	ds_read_b128 v[170:173], v211 offset:18432
	ds_read_b128 v[174:177], v211 offset:19456
	ds_read_b128 v[178:181], v211 offset:20480
	ds_read_b128 v[182:185], v211 offset:21504
	ds_read_b128 v[206:209], v211 offset:22528
	ds_read_b128 v[212:215], v211 offset:23552
	global_load_lds_dwordx4 v[216:217], off
	s_add_i32 m0, s68, 0x2000
	v_lshl_add_u64 v[218:219], s[66:67], 0, v[190:191]
	s_add_u32 s66, s66, s0
	s_addc_u32 s67, s67, 0
	s_add_i32 s68, s69, s16
	global_load_lds_dwordx4 v[218:219], off
	v_lshl_add_u64 v[220:221], s[66:67], 0, v[0:1]
	s_mov_b32 m0, s68
	v_lshl_add_u64 v[222:223], s[66:67], 0, v[190:191]
	global_load_lds_dwordx4 v[220:221], off
	s_add_i32 m0, s68, 0x2000
	v_lshl_add_u64 v[224:225], s[24:25], 0, v[186:187]
	global_load_lds_dwordx4 v[222:223], off
	s_mov_b32 m0, s17
	v_lshl_add_u64 v[226:227], s[24:25], 0, v[188:189]
	global_load_lds_dwordx4 v[224:225], off
	s_mov_b32 m0, s35
	s_nop 0
	global_load_lds_dwordx4 v[226:227], off
	s_waitcnt vmcnt(8)
	s_waitcnt lgkmcnt(0)
	s_barrier
; #define PG8_STAGE(bufoff, gbase, voff) do { _Pragma("unroll") for (int _i = 0; _i < 2; ++_i) \
;         __builtin_amdgcn_global_load_lds((const unsigned*)((const char*)(gbase) + (voff)[_i]), (PG8_LAS unsigned*)(lds + (bufoff) + ldsw + _i * 8192), 16, 0, 0); } while (0)
; #define PG8_LDA(dst, b, h) do { _Pragma("unroll") for (int m = 0; m < 4; ++m) _Pragma("unroll") for (int k = 0; k < 2; ++k) dst[m][k] = *(const PG8_LAS bf16x8*)(lds + PG8_SA(b, h) + aoff + m * 2048 + k * 1024); } while (0)
; #define PG8_LDB(dst, b, h) do { _Pragma("unroll") for (int n = 0; n < 2; ++n) _Pragma("unroll") for (int k = 0; k < 2; ++k) dst[n][k] = *(const PG8_LAS bf16x8*)(lds + PG8_SB(b, h) + boff + n * 2048 + k * 1024); } while (0)
; #define PG8_MMA(ai, bj, At, Bt) do { __builtin_amdgcn_s_setprio(1); _Pragma("unroll") for (int m = 0; m < 4; ++m) _Pragma("unroll") for (int n = 0; n < 2; ++n) _Pragma("unroll") for (int k = 0; k < 2; ++k) \
;         acc[ai][bj][m][n] = __builtin_amdgcn_mfma_f32_16x16x32_bf16(Bt[n][k], At[m][k], acc[ai][bj][m][n], 0, 0, 0); __builtin_amdgcn_s_setprio(0); } while (0)
; #define PG8_WAIT_V(n) asm volatile("s_waitcnt vmcnt(" #n ")" ::: "memory")
; #define PG8_WAIT_L(n) asm volatile("s_waitcnt lgkmcnt(" #n ")" ::: "memory")
; #define PG8_BAR __builtin_amdgcn_s_barrier()
; #define PG8_SCHED __builtin_amdgcn_sched_barrier(0)
; template <class Epi, class Sched, bool ALIGN_EPI = false, bool SP2 = false>
; __device__ __forceinline__ void gemm_phase(PG8_LAS unsigned char* lds, const Gemm g, const Sched& S, const Epi& E) {
;     ...
;             PG8_LDB(B0, 0, 0); PG8_LDB(B1, 0, 1); PG8_SCHED; PG8_LDA(At, 0, 0); PG8_STAGE(PG8_SA(1, 1), a1 + hstep, voffA);
;             PG8_WAIT_V(8); PG8_WAIT_L(0); PG8_BAR; PG8_MMA(0, 0, At, B0); PG8_MMA(0, 1, At, B1); PG8_BAR; PG8_SCHED;
;             PG8_LDA(At, 0, 1); PG8_STAGE(PG8_SB(0, 0), b2, voffB); PG8_STAGE(PG8_SB(0, 1), b2 + hstep, voffB); PG8_STAGE(PG8_SA(0, 0), a2, voffA);
;             PG8_WAIT_V(8); PG8_WAIT_L(0); PG8_BAR; PG8_MMA(1, 0, At, B0); PG8_MMA(1, 1, At, B1); PG8_BAR; PG8_SCHED;
;             PG8_LDB(B0, 1, 0); PG8_LDB(B1, 1, 1); PG8_SCHED; PG8_LDA(At, 1, 0); PG8_STAGE(PG8_SA(0, 1), a2 + hstep, voffA);
;             PG8_WAIT_V(8); PG8_WAIT_L(0); PG8_BAR; PG8_MMA(0, 0, At, B0); PG8_MMA(0, 1, At, B1); PG8_BAR; PG8_SCHED;
	s_setprio 1
	v_mfma_f32_16x16x32_bf16 v[62:65], v[130:133], v[162:165], 0
	v_mfma_f32_16x16x32_bf16 v[58:61], v[138:141], v[162:165], 0
	v_mfma_f32_16x16x32_bf16 v[46:49], v[130:133], v[170:173], 0
	v_mfma_f32_16x16x32_bf16 v[42:45], v[138:141], v[170:173], 0
	v_mfma_f32_16x16x32_bf16 v[30:33], v[130:133], v[178:181], 0
	v_mfma_f32_16x16x32_bf16 v[26:29], v[138:141], v[178:181], 0
	v_mfma_f32_16x16x32_bf16 v[14:17], v[130:133], v[206:209], 0
	v_mfma_f32_16x16x32_bf16 v[10:13], v[138:141], v[206:209], 0
	v_mfma_f32_16x16x32_bf16 v[62:65], v[134:137], v[166:169], v[62:65]
	v_mfma_f32_16x16x32_bf16 v[58:61], v[142:145], v[166:169], v[58:61]
	v_mfma_f32_16x16x32_bf16 v[46:49], v[134:137], v[174:177], v[46:49]
	v_mfma_f32_16x16x32_bf16 v[42:45], v[142:145], v[174:177], v[42:45]
	v_mfma_f32_16x16x32_bf16 v[30:33], v[134:137], v[182:185], v[30:33]
	v_mfma_f32_16x16x32_bf16 v[26:29], v[142:145], v[182:185], v[26:29]
	v_mfma_f32_16x16x32_bf16 v[14:17], v[134:137], v[212:215], v[14:17]
	v_mfma_f32_16x16x32_bf16 v[10:13], v[142:145], v[212:215], v[10:13]
	v_mfma_f32_16x16x32_bf16 v[54:57], v[146:149], v[162:165], 0
	v_mfma_f32_16x16x32_bf16 v[50:53], v[154:157], v[162:165], 0
	v_mfma_f32_16x16x32_bf16 v[38:41], v[146:149], v[170:173], 0
	v_mfma_f32_16x16x32_bf16 v[34:37], v[154:157], v[170:173], 0
	v_mfma_f32_16x16x32_bf16 v[22:25], v[146:149], v[178:181], 0
	v_mfma_f32_16x16x32_bf16 v[18:21], v[154:157], v[178:181], 0
	v_mfma_f32_16x16x32_bf16 v[6:9], v[146:149], v[206:209], 0
	v_mfma_f32_16x16x32_bf16 v[2:5], v[154:157], v[206:209], 0
	v_mfma_f32_16x16x32_bf16 v[54:57], v[150:153], v[166:169], v[54:57]
	v_mfma_f32_16x16x32_bf16 v[50:53], v[158:161], v[166:169], v[50:53]
	v_mfma_f32_16x16x32_bf16 v[38:41], v[150:153], v[174:177], v[38:41]
	v_mfma_f32_16x16x32_bf16 v[34:37], v[158:161], v[174:177], v[34:37]
	v_mfma_f32_16x16x32_bf16 v[22:25], v[150:153], v[182:185], v[22:25]
	v_mfma_f32_16x16x32_bf16 v[18:21], v[158:161], v[182:185], v[18:21]
	v_mfma_f32_16x16x32_bf16 v[6:9], v[150:153], v[212:215], v[6:9]
	v_mfma_f32_16x16x32_bf16 v[2:5], v[158:161], v[212:215], v[2:5]
	s_setprio 0
	s_barrier
	s_add_i32 s66, 0, 0x18000
	s_add_i32 s67, 0, 0x1c000
	v_add_u32_e32 v142, s66, v210
	v_add_u32_e32 v158, s67, v210
	ds_read_b128 v[130:133], v142
	ds_read_b128 v[134:137], v142 offset:1024
	ds_read_b128 v[138:141], v142 offset:2048
	ds_read_b128 v[142:145], v142 offset:3072
	ds_read_b128 v[146:149], v158
	ds_read_b128 v[150:153], v158 offset:1024
	ds_read_b128 v[154:157], v158 offset:2048
	ds_read_b128 v[158:161], v158 offset:3072
	s_add_u32 s24, s24, s0
	s_addc_u32 s25, s25, 0
	s_mov_b32 m0, s46
	v_lshl_add_u64 v[228:229], s[24:25], 0, v[186:187]
	ds_read_b128 v[162:165], v211 offset:32768
	ds_read_b128 v[166:169], v211 offset:33792
	ds_read_b128 v[170:173], v211 offset:34816
	ds_read_b128 v[174:177], v211 offset:35840
	ds_read_b128 v[178:181], v211 offset:36864
	ds_read_b128 v[182:185], v211 offset:37888
	ds_read_b128 v[206:209], v211 offset:38912
	ds_read_b128 v[212:215], v211 offset:39936
	global_load_lds_dwordx4 v[228:229], off
	v_lshl_add_u64 v[228:229], s[24:25], 0, v[188:189]
	s_mov_b32 m0, s47
	s_nop 0
	global_load_lds_dwordx4 v[228:229], off
	s_waitcnt vmcnt(8)
	s_waitcnt lgkmcnt(0)
	s_barrier
	s_setprio 1
	v_mfma_f32_16x16x32_bf16 v[118:121], v[130:133], v[162:165], v[118:121]
	v_mfma_f32_16x16x32_bf16 v[114:117], v[138:141], v[162:165], v[114:117]
	v_mfma_f32_16x16x32_bf16 v[110:113], v[130:133], v[170:173], v[110:113]
	v_mfma_f32_16x16x32_bf16 v[106:109], v[138:141], v[170:173], v[106:109]
	v_mfma_f32_16x16x32_bf16 v[94:97], v[130:133], v[178:181], v[94:97]
	v_mfma_f32_16x16x32_bf16 v[90:93], v[138:141], v[178:181], v[90:93]
	v_mfma_f32_16x16x32_bf16 v[78:81], v[130:133], v[206:209], v[78:81]
	v_mfma_f32_16x16x32_bf16 v[74:77], v[138:141], v[206:209], v[74:77]
	v_mfma_f32_16x16x32_bf16 v[118:121], v[134:137], v[166:169], v[118:121]
	v_mfma_f32_16x16x32_bf16 v[114:117], v[142:145], v[166:169], v[114:117]
	v_mfma_f32_16x16x32_bf16 v[110:113], v[134:137], v[174:177], v[110:113]
	v_mfma_f32_16x16x32_bf16 v[106:109], v[142:145], v[174:177], v[106:109]
	v_mfma_f32_16x16x32_bf16 v[94:97], v[134:137], v[182:185], v[94:97]
	v_mfma_f32_16x16x32_bf16 v[90:93], v[142:145], v[182:185], v[90:93]
	v_mfma_f32_16x16x32_bf16 v[78:81], v[134:137], v[212:215], v[78:81]
	v_mfma_f32_16x16x32_bf16 v[74:77], v[142:145], v[212:215], v[74:77]
	v_mfma_f32_16x16x32_bf16 v[126:129], v[146:149], v[162:165], v[126:129]
	v_mfma_f32_16x16x32_bf16 v[122:125], v[154:157], v[162:165], v[122:125]
	v_mfma_f32_16x16x32_bf16 v[102:105], v[146:149], v[170:173], v[102:105]
	v_mfma_f32_16x16x32_bf16 v[98:101], v[154:157], v[170:173], v[98:101]
	v_mfma_f32_16x16x32_bf16 v[86:89], v[146:149], v[178:181], v[86:89]
	v_mfma_f32_16x16x32_bf16 v[82:85], v[154:157], v[178:181], v[82:85]
	v_mfma_f32_16x16x32_bf16 v[70:73], v[146:149], v[206:209], v[70:73]
	v_mfma_f32_16x16x32_bf16 v[66:69], v[154:157], v[206:209], v[66:69]
	v_mfma_f32_16x16x32_bf16 v[126:129], v[150:153], v[166:169], v[126:129]
	v_mfma_f32_16x16x32_bf16 v[122:125], v[158:161], v[166:169], v[122:125]
	v_mfma_f32_16x16x32_bf16 v[102:105], v[150:153], v[174:177], v[102:105]
	v_mfma_f32_16x16x32_bf16 v[98:101], v[158:161], v[174:177], v[98:101]
	v_mfma_f32_16x16x32_bf16 v[86:89], v[150:153], v[182:185], v[86:89]
	v_mfma_f32_16x16x32_bf16 v[82:85], v[158:161], v[182:185], v[82:85]
	v_mfma_f32_16x16x32_bf16 v[70:73], v[150:153], v[212:215], v[70:73]
	v_mfma_f32_16x16x32_bf16 v[66:69], v[158:161], v[212:215], v[66:69]
	s_setprio 0
	s_barrier
; #define PG8_STAGE(bufoff, gbase, voff) do { _Pragma("unroll") for (int _i = 0; _i < 2; ++_i) \
;         __builtin_amdgcn_global_load_lds((const unsigned*)((const char*)(gbase) + (voff)[_i]), (PG8_LAS unsigned*)(lds + (bufoff) + ldsw + _i * 8192), 16, 0, 0); } while (0)
; #define PG8_LDA(dst, b, h) do { _Pragma("unroll") for (int m = 0; m < 4; ++m) _Pragma("unroll") for (int k = 0; k < 2; ++k) dst[m][k] = *(const PG8_LAS bf16x8*)(lds + PG8_SA(b, h) + aoff + m * 2048 + k * 1024); } while (0)
; #define PG8_MMA(ai, bj, At, Bt) do { __builtin_amdgcn_s_setprio(1); _Pragma("unroll") for (int m = 0; m < 4; ++m) _Pragma("unroll") for (int n = 0; n < 2; ++n) _Pragma("unroll") for (int k = 0; k < 2; ++k) \
;         acc[ai][bj][m][n] = __builtin_amdgcn_mfma_f32_16x16x32_bf16(Bt[n][k], At[m][k], acc[ai][bj][m][n], 0, 0, 0); __builtin_amdgcn_s_setprio(0); } while (0)
; #define PG8_WAIT_V(n) asm volatile("s_waitcnt vmcnt(" #n ")" ::: "memory")
; #define PG8_WAIT_L(n) asm volatile("s_waitcnt lgkmcnt(" #n ")" ::: "memory")
; #define PG8_BAR __builtin_amdgcn_s_barrier()
; #define PG8_SCHED __builtin_amdgcn_sched_barrier(0)
; template <class Epi, class Sched, bool ALIGN_EPI = false, bool SP2 = false>
; __device__ __forceinline__ void gemm_phase(PG8_LAS unsigned char* lds, const Gemm g, const Sched& S, const Epi& E) {
;     ...
;         for (int t = 0; t < nt; t += 2) {
;     ...
;             PG8_LDA(At, 1, 1); PG8_STAGE(PG8_SB(1, 0), b3, voffB); PG8_STAGE(PG8_SB(1, 1), b3 + hstep, voffB); PG8_STAGE(PG8_SA(1, 0), a3, voffA);
;             PG8_WAIT_V(8); PG8_WAIT_L(0); PG8_BAR; PG8_MMA(1, 0, At, B0); PG8_MMA(1, 1, At, B1); PG8_BAR; PG8_SCHED;
	s_add_i32 s24, s66, s16
	v_lshl_add_u64 v[216:217], v[216:217], 0, s[28:29]
	s_mov_b32 m0, s24
	ds_read_b128 v[162:165], v211 offset:49152
	ds_read_b128 v[166:169], v211 offset:50176
	ds_read_b128 v[170:173], v211 offset:51200
	ds_read_b128 v[174:177], v211 offset:52224
	ds_read_b128 v[178:181], v211 offset:53248
	ds_read_b128 v[182:185], v211 offset:54272
	ds_read_b128 v[206:209], v211 offset:55296
	ds_read_b128 v[212:215], v211 offset:56320
	global_load_lds_dwordx4 v[216:217], off
	v_lshl_add_u64 v[216:217], v[218:219], 0, s[28:29]
	s_add_i32 m0, s24, 0x2000
	s_add_i32 s24, s67, s16
	global_load_lds_dwordx4 v[216:217], off
	v_lshl_add_u64 v[216:217], v[220:221], 0, s[28:29]
	s_mov_b32 m0, s24
	s_nop 0
	global_load_lds_dwordx4 v[216:217], off
	v_lshl_add_u64 v[216:217], v[222:223], 0, s[28:29]
	s_add_i32 m0, s24, 0x2000
	s_nop 0
	global_load_lds_dwordx4 v[216:217], off
	v_lshl_add_u64 v[216:217], v[224:225], 0, s[28:29]
	s_mov_b32 m0, s50
	s_nop 0
	global_load_lds_dwordx4 v[216:217], off
	v_lshl_add_u64 v[216:217], v[226:227], 0, s[28:29]
	s_mov_b32 m0, s51
	s_nop 0
	global_load_lds_dwordx4 v[216:217], off
	s_waitcnt vmcnt(8)
	s_waitcnt lgkmcnt(0)
	s_barrier
	s_setprio 1
	v_mfma_f32_16x16x32_bf16 v[62:65], v[130:133], v[162:165], v[62:65]
	v_mfma_f32_16x16x32_bf16 v[58:61], v[138:141], v[162:165], v[58:61]
	v_mfma_f32_16x16x32_bf16 v[46:49], v[130:133], v[170:173], v[46:49]
	v_mfma_f32_16x16x32_bf16 v[42:45], v[138:141], v[170:173], v[42:45]
	v_mfma_f32_16x16x32_bf16 v[30:33], v[130:133], v[178:181], v[30:33]
	v_mfma_f32_16x16x32_bf16 v[26:29], v[138:141], v[178:181], v[26:29]
	v_mfma_f32_16x16x32_bf16 v[14:17], v[130:133], v[206:209], v[14:17]
	v_mfma_f32_16x16x32_bf16 v[10:13], v[138:141], v[206:209], v[10:13]
	v_mfma_f32_16x16x32_bf16 v[62:65], v[134:137], v[166:169], v[62:65]
	v_mfma_f32_16x16x32_bf16 v[58:61], v[142:145], v[166:169], v[58:61]
	v_mfma_f32_16x16x32_bf16 v[46:49], v[134:137], v[174:177], v[46:49]
	v_mfma_f32_16x16x32_bf16 v[42:45], v[142:145], v[174:177], v[42:45]
	v_mfma_f32_16x16x32_bf16 v[30:33], v[134:137], v[182:185], v[30:33]
	v_mfma_f32_16x16x32_bf16 v[26:29], v[142:145], v[182:185], v[26:29]
	v_mfma_f32_16x16x32_bf16 v[14:17], v[134:137], v[212:215], v[14:17]
	v_mfma_f32_16x16x32_bf16 v[10:13], v[142:145], v[212:215], v[10:13]
	v_mfma_f32_16x16x32_bf16 v[54:57], v[146:149], v[162:165], v[54:57]
	v_mfma_f32_16x16x32_bf16 v[50:53], v[154:157], v[162:165], v[50:53]
	v_mfma_f32_16x16x32_bf16 v[38:41], v[146:149], v[170:173], v[38:41]
	v_mfma_f32_16x16x32_bf16 v[34:37], v[154:157], v[170:173], v[34:37]
	v_mfma_f32_16x16x32_bf16 v[22:25], v[146:149], v[178:181], v[22:25]
	v_mfma_f32_16x16x32_bf16 v[18:21], v[154:157], v[178:181], v[18:21]
	v_mfma_f32_16x16x32_bf16 v[6:9], v[146:149], v[206:209], v[6:9]
	v_mfma_f32_16x16x32_bf16 v[2:5], v[154:157], v[206:209], v[2:5]
	v_mfma_f32_16x16x32_bf16 v[54:57], v[150:153], v[166:169], v[54:57]
	v_mfma_f32_16x16x32_bf16 v[50:53], v[158:161], v[166:169], v[50:53]
	v_mfma_f32_16x16x32_bf16 v[38:41], v[150:153], v[174:177], v[38:41]
	v_mfma_f32_16x16x32_bf16 v[34:37], v[158:161], v[174:177], v[34:37]
	v_mfma_f32_16x16x32_bf16 v[22:25], v[150:153], v[182:185], v[22:25]
	v_mfma_f32_16x16x32_bf16 v[18:21], v[158:161], v[182:185], v[18:21]
	v_mfma_f32_16x16x32_bf16 v[6:9], v[150:153], v[212:215], v[6:9]
	v_mfma_f32_16x16x32_bf16 v[2:5], v[158:161], v[212:215], v[2:5]
	s_setprio 0
	s_barrier
	s_add_u32 s44, s44, 0x100
	s_addc_u32 s45, s45, 0
	s_add_u32 s63, s63, 0x100
	s_addc_u32 s64, s64, 0
	s_cmp_ge_u32 s65, s56
	s_mov_b32 s24, s65

; #define PG8_STAGE(bufoff, gbase, voff) do { _Pragma("unroll") for (int _i = 0; _i < 2; ++_i) \
;         __builtin_amdgcn_global_load_lds((const unsigned*)((const char*)(gbase) + (voff)[_i]), (PG8_LAS unsigned*)(lds + (bufoff) + ldsw + _i * 8192), 16, 0, 0); } while (0)
; #define PG8_LDA(dst, b, h) do { _Pragma("unroll") for (int m = 0; m < 4; ++m) _Pragma("unroll") for (int k = 0; k < 2; ++k) dst[m][k] = *(const PG8_LAS bf16x8*)(lds + PG8_SA(b, h) + aoff + m * 2048 + k * 1024); } while (0)
; #define PG8_BAR __builtin_amdgcn_s_barrier()
; template <class Epi, class Sched, bool ALIGN_EPI = false, bool SP2 = false>
; __device__ __forceinline__ void gemm_phase(PG8_LAS unsigned char* lds, const Gemm g, const Sched& S, const Epi& E) {
;     ...
;         const char* nA = has_next ? (const char*)g.A + (size_t)nxt.pm * tstep : cA; const char* nB = has_next ? (const char*)g.Bt + (size_t)nxt.pn * tstep : cB;
;         for (int t = 0; t < nt; t += 2) {
;             const bool last = (t == nt - 2);
;             const char* a1 = cA + (size_t)(t + 1) * kstep;
;             const char* a2 = last ? nA : cA + (size_t)(t + 2) * kstep; const char* b2 = last ? nB : cB + (size_t)(t + 2) * kstep;
;             const char* a3 = a2 + kstep; const char* b3 = b2 + kstep;
;             if (last && has_next) S.a_ready(nxt);
;             if constexpr (SP2) {
;             PG8_LDB(B0, 0, 0); PG8_LDB(B1, 0, 1); PG8_SCHED; PG8_LDA(At, 0, 0); PG8_STAGE(PG8_SA(1, 1), a1 + hstep, voffA);
;             PG8_WAIT_V(8); PG8_WAIT_L(0); PG8_BAR; PG8_MMA(0, 0, At, B0); PG8_MMA(0, 1, At, B1); PG8_BAR; PG8_SCHED;
;             PG8_LDA(At, 0, 1); PG8_STAGE(PG8_SB(0, 0), b2, voffB); PG8_STAGE(PG8_SB(0, 1), b2 + hstep, voffB); PG8_STAGE(PG8_SA(0, 0), a2, voffA);
;             PG8_WAIT_V(8); PG8_WAIT_L(0); PG8_BAR; PG8_MMA(1, 0, At, B0); PG8_MMA(1, 1, At, B1); PG8_BAR; PG8_SCHED;
;             PG8_LDB(B0, 1, 0); PG8_LDB(B1, 1, 1); PG8_SCHED; PG8_LDA(At, 1, 0); PG8_STAGE(PG8_SA(0, 1), a2 + hstep, voffA);
;             PG8_WAIT_V(8); PG8_WAIT_L(0); PG8_BAR; PG8_MMA(0, 0, At, B0); PG8_MMA(0, 1, At, B1); PG8_BAR; PG8_SCHED;
;             PG8_LDA(At, 1, 1); PG8_STAGE(PG8_SB(1, 0), b3, voffB); PG8_STAGE(PG8_SB(1, 1), b3 + hstep, voffB); PG8_STAGE(PG8_SA(1, 0), a3, voffA);
;             PG8_WAIT_V(8); PG8_WAIT_L(0); PG8_BAR; PG8_MMA(1, 0, At, B0); PG8_MMA(1, 1, At, B1); PG8_BAR; PG8_SCHED;
.LBB0_456:
	s_ashr_i32 s19, s18, 31
	s_lshl_b64 s[22:23], s[18:19], 19
	s_add_u32 s22, s20, s22
	s_addc_u32 s23, s35, s23
	s_and_b64 s[40:41], s[8:9], exec
	s_cselect_b32 s19, s23, s47
	s_cselect_b32 s60, s22, s46
	s_ashr_i32 s17, s16, 31
	s_lshl_b64 s[40:41], s[16:17], 19
	s_add_u32 s40, s50, s40
	s_addc_u32 s41, s51, s41
	s_and_b64 s[48:49], s[8:9], exec
	s_cselect_b32 s17, s41, s25
	s_cselect_b32 s61, s40, s24
	s_add_u32 s46, s46, 0x40080
	s_addc_u32 s47, s47, 0
	s_add_u32 s62, s24, 0x100
	s_addc_u32 s63, s25, 0
	s_mov_b32 s64, -2
	s_add_u32 s24, s46, 0xfffc0080
	s_addc_u32 s25, s47, -1
	s_add_i32 s65, 0, 0x10000
	s_cmp_eq_u32 s64, 12
	s_cselect_b32 s49, s19, s25
	s_cselect_b32 s48, s60, s24
	s_cselect_b32 s25, s17, s63
	s_cselect_b32 s24, s61, s62
	s_add_i32 s68, 0, 0x14000
	v_add_u32_e32 v142, s65, v189
	v_add_u32_e32 v170, s68, v189
	ds_read_b128 v[130:133], v142
	ds_read_b128 v[134:137], v142 offset:1024
	ds_read_b128 v[138:141], v142 offset:2048
	ds_read_b128 v[142:145], v142 offset:3072
	ds_read_b128 v[146:149], v170
	ds_read_b128 v[150:153], v170 offset:1024
	ds_read_b128 v[154:157], v170 offset:2048
	ds_read_b128 v[170:173], v170 offset:3072
	v_lshl_add_u64 v[186:187], s[46:47], 0, v[166:167]
	s_add_i32 m0, s43, 0xc000
	ds_read_b128 v[174:177], v192
	ds_read_b128 v[178:181], v192 offset:1024
	ds_read_b128 v[182:185], v192 offset:2048
	ds_read_b128 v[194:197], v192 offset:3072
	ds_read_b128 v[198:201], v192 offset:4096
	ds_read_b128 v[206:209], v192 offset:5120
	ds_read_b128 v[210:213], v192 offset:6144
	ds_read_b128 v[214:217], v192 offset:7168
	global_load_lds_dwordx4 v[186:187], off
	v_lshl_add_u64 v[186:187], s[46:47], 0, v[168:169]
	s_add_i32 m0, s43, 0xe000
	s_nop 0
	global_load_lds_dwordx4 v[186:187], off
	s_waitcnt vmcnt(8)
	s_waitcnt lgkmcnt(0)
	s_barrier
	s_setprio 1
	v_mfma_f32_16x16x32_bf16 v[126:129], v[130:133], v[174:177], 0
	v_mfma_f32_16x16x32_bf16 v[122:125], v[138:141], v[174:177], 0
	v_mfma_f32_16x16x32_bf16 v[110:113], v[130:133], v[182:185], 0
	v_mfma_f32_16x16x32_bf16 v[106:109], v[138:141], v[182:185], 0
	v_mfma_f32_16x16x32_bf16 v[94:97], v[130:133], v[198:201], 0
	v_mfma_f32_16x16x32_bf16 v[90:93], v[138:141], v[198:201], 0
	v_mfma_f32_16x16x32_bf16 v[78:81], v[130:133], v[210:213], 0
	v_mfma_f32_16x16x32_bf16 v[74:77], v[138:141], v[210:213], 0
	v_mfma_f32_16x16x32_bf16 v[126:129], v[134:137], v[178:181], v[126:129]
	v_mfma_f32_16x16x32_bf16 v[122:125], v[142:145], v[178:181], v[122:125]
	v_mfma_f32_16x16x32_bf16 v[110:113], v[134:137], v[194:197], v[110:113]
	v_mfma_f32_16x16x32_bf16 v[106:109], v[142:145], v[194:197], v[106:109]
	v_mfma_f32_16x16x32_bf16 v[94:97], v[134:137], v[206:209], v[94:97]
	v_mfma_f32_16x16x32_bf16 v[90:93], v[142:145], v[206:209], v[90:93]
	v_mfma_f32_16x16x32_bf16 v[78:81], v[134:137], v[214:217], v[78:81]
	v_mfma_f32_16x16x32_bf16 v[74:77], v[142:145], v[214:217], v[74:77]
	v_mfma_f32_16x16x32_bf16 v[118:121], v[146:149], v[174:177], 0
	v_mfma_f32_16x16x32_bf16 v[114:117], v[154:157], v[174:177], 0
	v_mfma_f32_16x16x32_bf16 v[102:105], v[146:149], v[182:185], 0
	v_mfma_f32_16x16x32_bf16 v[98:101], v[154:157], v[182:185], 0
	v_mfma_f32_16x16x32_bf16 v[86:89], v[146:149], v[198:201], 0
	v_mfma_f32_16x16x32_bf16 v[82:85], v[154:157], v[198:201], 0
	v_mfma_f32_16x16x32_bf16 v[70:73], v[146:149], v[210:213], 0
	v_mfma_f32_16x16x32_bf16 v[66:69], v[154:157], v[210:213], 0
	v_mfma_f32_16x16x32_bf16 v[118:121], v[150:153], v[178:181], v[118:121]
	v_mfma_f32_16x16x32_bf16 v[114:117], v[170:173], v[178:181], v[114:117]
	v_mfma_f32_16x16x32_bf16 v[102:105], v[150:153], v[194:197], v[102:105]
	v_mfma_f32_16x16x32_bf16 v[98:101], v[170:173], v[194:197], v[98:101]
	v_mfma_f32_16x16x32_bf16 v[86:89], v[150:153], v[206:209], v[86:89]
	v_mfma_f32_16x16x32_bf16 v[82:85], v[170:173], v[206:209], v[82:85]
	v_mfma_f32_16x16x32_bf16 v[70:73], v[150:153], v[214:217], v[70:73]
	v_mfma_f32_16x16x32_bf16 v[66:69], v[170:173], v[214:217], v[66:69]
	s_setprio 0
	s_barrier
	s_add_i32 s65, s65, s11
	v_lshl_add_u64 v[186:187], s[24:25], 0, v[0:1]
	s_mov_b32 m0, s65
	ds_read_b128 v[174:177], v192 offset:16384
	ds_read_b128 v[178:181], v192 offset:17408
	ds_read_b128 v[182:185], v192 offset:18432
	ds_read_b128 v[194:197], v192 offset:19456
	ds_read_b128 v[198:201], v192 offset:20480
	ds_read_b128 v[206:209], v192 offset:21504
	ds_read_b128 v[210:213], v192 offset:22528
	ds_read_b128 v[214:217], v192 offset:23552
	global_load_lds_dwordx4 v[186:187], off
	s_add_i32 m0, s65, 0x2000
	s_add_u32 s66, s24, 0x40000
	v_lshl_add_u64 v[218:219], s[24:25], 0, v[162:163]
	s_addc_u32 s67, s25, 0
	s_add_i32 s65, s68, s11
	global_load_lds_dwordx4 v[218:219], off
	v_lshl_add_u64 v[220:221], s[66:67], 0, v[0:1]
	s_mov_b32 m0, s65
	v_lshl_add_u64 v[222:223], s[48:49], 0, v[160:161]
	global_load_lds_dwordx4 v[220:221], off
	v_lshl_add_u64 v[220:221], s[66:67], 0, v[162:163]
	s_add_i32 m0, s65, 0x2000
	s_nop 0
	global_load_lds_dwordx4 v[220:221], off
	v_lshl_add_u64 v[220:221], s[48:49], 0, v[158:159]
	s_mov_b32 m0, s43
	s_nop 0
	global_load_lds_dwordx4 v[220:221], off
	s_mov_b32 m0, s45
	s_nop 0
	global_load_lds_dwordx4 v[222:223], off
	s_waitcnt vmcnt(8)
	s_waitcnt lgkmcnt(0)
	s_barrier
; #define PG8_STAGE(bufoff, gbase, voff) do { _Pragma("unroll") for (int _i = 0; _i < 2; ++_i) \
;         __builtin_amdgcn_global_load_lds((const unsigned*)((const char*)(gbase) + (voff)[_i]), (PG8_LAS unsigned*)(lds + (bufoff) + ldsw + _i * 8192), 16, 0, 0); } while (0)
; #define PG8_LDA(dst, b, h) do { _Pragma("unroll") for (int m = 0; m < 4; ++m) _Pragma("unroll") for (int k = 0; k < 2; ++k) dst[m][k] = *(const PG8_LAS bf16x8*)(lds + PG8_SA(b, h) + aoff + m * 2048 + k * 1024); } while (0)
; #define PG8_LDB(dst, b, h) do { _Pragma("unroll") for (int n = 0; n < 2; ++n) _Pragma("unroll") for (int k = 0; k < 2; ++k) dst[n][k] = *(const PG8_LAS bf16x8*)(lds + PG8_SB(b, h) + boff + n * 2048 + k * 1024); } while (0)
; #define PG8_MMA(ai, bj, At, Bt) do { __builtin_amdgcn_s_setprio(1); _Pragma("unroll") for (int m = 0; m < 4; ++m) _Pragma("unroll") for (int n = 0; n < 2; ++n) _Pragma("unroll") for (int k = 0; k < 2; ++k) \
;         acc[ai][bj][m][n] = __builtin_amdgcn_mfma_f32_16x16x32_bf16(Bt[n][k], At[m][k], acc[ai][bj][m][n], 0, 0, 0); __builtin_amdgcn_s_setprio(0); } while (0)
; #define PG8_WAIT_V(n) asm volatile("s_waitcnt vmcnt(" #n ")" ::: "memory")
; #define PG8_WAIT_L(n) asm volatile("s_waitcnt lgkmcnt(" #n ")" ::: "memory")
; #define PG8_BAR __builtin_amdgcn_s_barrier()
; #define PG8_SCHED __builtin_amdgcn_sched_barrier(0)
; template <class Epi, class Sched, bool ALIGN_EPI = false, bool SP2 = false>
; __device__ __forceinline__ void gemm_phase(PG8_LAS unsigned char* lds, const Gemm g, const Sched& S, const Epi& E) {
;     ...
;             PG8_LDB(B0, 0, 0); PG8_LDB(B1, 0, 1); PG8_SCHED; PG8_LDA(At, 0, 0); PG8_STAGE(PG8_SA(1, 1), a1 + hstep, voffA);
;             PG8_WAIT_V(8); PG8_WAIT_L(0); PG8_BAR; PG8_MMA(0, 0, At, B0); PG8_MMA(0, 1, At, B1); PG8_BAR; PG8_SCHED;
;             PG8_LDA(At, 0, 1); PG8_STAGE(PG8_SB(0, 0), b2, voffB); PG8_STAGE(PG8_SB(0, 1), b2 + hstep, voffB); PG8_STAGE(PG8_SA(0, 0), a2, voffA);
;             PG8_WAIT_V(8); PG8_WAIT_L(0); PG8_BAR; PG8_MMA(1, 0, At, B0); PG8_MMA(1, 1, At, B1); PG8_BAR; PG8_SCHED;
;             PG8_LDB(B0, 1, 0); PG8_LDB(B1, 1, 1); PG8_SCHED; PG8_LDA(At, 1, 0); PG8_STAGE(PG8_SA(0, 1), a2 + hstep, voffA);
;             PG8_WAIT_V(8); PG8_WAIT_L(0); PG8_BAR; PG8_MMA(0, 0, At, B0); PG8_MMA(0, 1, At, B1); PG8_BAR; PG8_SCHED;
	s_setprio 1
	v_mfma_f32_16x16x32_bf16 v[62:65], v[130:133], v[174:177], 0
	v_mfma_f32_16x16x32_bf16 v[58:61], v[138:141], v[174:177], 0
	v_mfma_f32_16x16x32_bf16 v[46:49], v[130:133], v[182:185], 0
	v_mfma_f32_16x16x32_bf16 v[42:45], v[138:141], v[182:185], 0
	v_mfma_f32_16x16x32_bf16 v[30:33], v[130:133], v[198:201], 0
	v_mfma_f32_16x16x32_bf16 v[26:29], v[138:141], v[198:201], 0
	v_mfma_f32_16x16x32_bf16 v[14:17], v[130:133], v[210:213], 0
	v_mfma_f32_16x16x32_bf16 v[10:13], v[138:141], v[210:213], 0
	v_mfma_f32_16x16x32_bf16 v[62:65], v[134:137], v[178:181], v[62:65]
	v_mfma_f32_16x16x32_bf16 v[58:61], v[142:145], v[178:181], v[58:61]
	v_mfma_f32_16x16x32_bf16 v[46:49], v[134:137], v[194:197], v[46:49]
	v_mfma_f32_16x16x32_bf16 v[42:45], v[142:145], v[194:197], v[42:45]
	v_mfma_f32_16x16x32_bf16 v[30:33], v[134:137], v[206:209], v[30:33]
	v_mfma_f32_16x16x32_bf16 v[26:29], v[142:145], v[206:209], v[26:29]
	v_mfma_f32_16x16x32_bf16 v[14:17], v[134:137], v[214:217], v[14:17]
	v_mfma_f32_16x16x32_bf16 v[10:13], v[142:145], v[214:217], v[10:13]
	v_mfma_f32_16x16x32_bf16 v[54:57], v[146:149], v[174:177], 0
	v_mfma_f32_16x16x32_bf16 v[50:53], v[154:157], v[174:177], 0
	v_mfma_f32_16x16x32_bf16 v[38:41], v[146:149], v[182:185], 0
	v_mfma_f32_16x16x32_bf16 v[34:37], v[154:157], v[182:185], 0
	v_mfma_f32_16x16x32_bf16 v[22:25], v[146:149], v[198:201], 0
	v_mfma_f32_16x16x32_bf16 v[18:21], v[154:157], v[198:201], 0
	v_mfma_f32_16x16x32_bf16 v[6:9], v[146:149], v[210:213], 0
	v_mfma_f32_16x16x32_bf16 v[2:5], v[154:157], v[210:213], 0
	v_mfma_f32_16x16x32_bf16 v[54:57], v[150:153], v[178:181], v[54:57]
	v_mfma_f32_16x16x32_bf16 v[50:53], v[170:173], v[178:181], v[50:53]
	v_mfma_f32_16x16x32_bf16 v[38:41], v[150:153], v[194:197], v[38:41]
	v_mfma_f32_16x16x32_bf16 v[34:37], v[170:173], v[194:197], v[34:37]
	v_mfma_f32_16x16x32_bf16 v[22:25], v[150:153], v[206:209], v[22:25]
	v_mfma_f32_16x16x32_bf16 v[18:21], v[170:173], v[206:209], v[18:21]
	v_mfma_f32_16x16x32_bf16 v[6:9], v[150:153], v[214:217], v[6:9]
	v_mfma_f32_16x16x32_bf16 v[2:5], v[170:173], v[214:217], v[2:5]
	s_setprio 0
	s_barrier
	s_add_i32 s65, 0, 0x18000
	s_add_i32 s66, 0, 0x1c000
	v_add_u32_e32 v142, s65, v189
	v_add_u32_e32 v170, s66, v189
	ds_read_b128 v[130:133], v142
	ds_read_b128 v[134:137], v142 offset:1024
	ds_read_b128 v[138:141], v142 offset:2048
	ds_read_b128 v[142:145], v142 offset:3072
	ds_read_b128 v[146:149], v170
	ds_read_b128 v[150:153], v170 offset:1024
	ds_read_b128 v[154:157], v170 offset:2048
	ds_read_b128 v[170:173], v170 offset:3072
	s_add_u32 s48, s48, 0x40000
	s_addc_u32 s49, s49, 0
	s_mov_b32 m0, s52
	v_lshl_add_u64 v[224:225], s[48:49], 0, v[158:159]
	ds_read_b128 v[174:177], v192 offset:32768
	ds_read_b128 v[178:181], v192 offset:33792
	ds_read_b128 v[182:185], v192 offset:34816
	ds_read_b128 v[194:197], v192 offset:35840
	ds_read_b128 v[198:201], v192 offset:36864
	ds_read_b128 v[206:209], v192 offset:37888
	ds_read_b128 v[210:213], v192 offset:38912
	ds_read_b128 v[214:217], v192 offset:39936
	global_load_lds_dwordx4 v[224:225], off
	v_lshl_add_u64 v[224:225], s[48:49], 0, v[160:161]
	s_mov_b32 m0, s53
	s_nop 0
	global_load_lds_dwordx4 v[224:225], off
	s_waitcnt vmcnt(8)
	s_waitcnt lgkmcnt(0)
	s_barrier
	s_setprio 1
	v_mfma_f32_16x16x32_bf16 v[126:129], v[130:133], v[174:177], v[126:129]
	v_mfma_f32_16x16x32_bf16 v[122:125], v[138:141], v[174:177], v[122:125]
	v_mfma_f32_16x16x32_bf16 v[110:113], v[130:133], v[182:185], v[110:113]
	v_mfma_f32_16x16x32_bf16 v[106:109], v[138:141], v[182:185], v[106:109]
	v_mfma_f32_16x16x32_bf16 v[94:97], v[130:133], v[198:201], v[94:97]
	v_mfma_f32_16x16x32_bf16 v[90:93], v[138:141], v[198:201], v[90:93]
	v_mfma_f32_16x16x32_bf16 v[78:81], v[130:133], v[210:213], v[78:81]
	v_mfma_f32_16x16x32_bf16 v[74:77], v[138:141], v[210:213], v[74:77]
	v_mfma_f32_16x16x32_bf16 v[126:129], v[134:137], v[178:181], v[126:129]
	v_mfma_f32_16x16x32_bf16 v[122:125], v[142:145], v[178:181], v[122:125]
	v_mfma_f32_16x16x32_bf16 v[110:113], v[134:137], v[194:197], v[110:113]
	v_mfma_f32_16x16x32_bf16 v[106:109], v[142:145], v[194:197], v[106:109]
	v_mfma_f32_16x16x32_bf16 v[94:97], v[134:137], v[206:209], v[94:97]
	v_mfma_f32_16x16x32_bf16 v[90:93], v[142:145], v[206:209], v[90:93]
	v_mfma_f32_16x16x32_bf16 v[78:81], v[134:137], v[214:217], v[78:81]
	v_mfma_f32_16x16x32_bf16 v[74:77], v[142:145], v[214:217], v[74:77]
	v_mfma_f32_16x16x32_bf16 v[118:121], v[146:149], v[174:177], v[118:121]
	v_mfma_f32_16x16x32_bf16 v[114:117], v[154:157], v[174:177], v[114:117]
	v_mfma_f32_16x16x32_bf16 v[102:105], v[146:149], v[182:185], v[102:105]
	v_mfma_f32_16x16x32_bf16 v[98:101], v[154:157], v[182:185], v[98:101]
	v_mfma_f32_16x16x32_bf16 v[86:89], v[146:149], v[198:201], v[86:89]
	v_mfma_f32_16x16x32_bf16 v[82:85], v[154:157], v[198:201], v[82:85]
	v_mfma_f32_16x16x32_bf16 v[70:73], v[146:149], v[210:213], v[70:73]
	v_mfma_f32_16x16x32_bf16 v[66:69], v[154:157], v[210:213], v[66:69]
	v_mfma_f32_16x16x32_bf16 v[118:121], v[150:153], v[178:181], v[118:121]
	v_mfma_f32_16x16x32_bf16 v[114:117], v[170:173], v[178:181], v[114:117]
	v_mfma_f32_16x16x32_bf16 v[102:105], v[150:153], v[194:197], v[102:105]
	v_mfma_f32_16x16x32_bf16 v[98:101], v[170:173], v[194:197], v[98:101]
	v_mfma_f32_16x16x32_bf16 v[86:89], v[150:153], v[206:209], v[86:89]
	v_mfma_f32_16x16x32_bf16 v[82:85], v[170:173], v[206:209], v[82:85]
	v_mfma_f32_16x16x32_bf16 v[70:73], v[150:153], v[214:217], v[70:73]
	v_mfma_f32_16x16x32_bf16 v[66:69], v[170:173], v[214:217], v[66:69]
	s_setprio 0
	s_barrier
; #define PG8_STAGE(bufoff, gbase, voff) do { _Pragma("unroll") for (int _i = 0; _i < 2; ++_i) \
;         __builtin_amdgcn_global_load_lds((const unsigned*)((const char*)(gbase) + (voff)[_i]), (PG8_LAS unsigned*)(lds + (bufoff) + ldsw + _i * 8192), 16, 0, 0); } while (0)
; #define PG8_LDA(dst, b, h) do { _Pragma("unroll") for (int m = 0; m < 4; ++m) _Pragma("unroll") for (int k = 0; k < 2; ++k) dst[m][k] = *(const PG8_LAS bf16x8*)(lds + PG8_SA(b, h) + aoff + m * 2048 + k * 1024); } while (0)
; #define PG8_MMA(ai, bj, At, Bt) do { __builtin_amdgcn_s_setprio(1); _Pragma("unroll") for (int m = 0; m < 4; ++m) _Pragma("unroll") for (int n = 0; n < 2; ++n) _Pragma("unroll") for (int k = 0; k < 2; ++k) \
;         acc[ai][bj][m][n] = __builtin_amdgcn_mfma_f32_16x16x32_bf16(Bt[n][k], At[m][k], acc[ai][bj][m][n], 0, 0, 0); __builtin_amdgcn_s_setprio(0); } while (0)
; #define PG8_WAIT_V(n) asm volatile("s_waitcnt vmcnt(" #n ")" ::: "memory")
; #define PG8_WAIT_L(n) asm volatile("s_waitcnt lgkmcnt(" #n ")" ::: "memory")
; #define PG8_BAR __builtin_amdgcn_s_barrier()
; #define PG8_SCHED __builtin_amdgcn_sched_barrier(0)
; template <class Epi, class Sched, bool ALIGN_EPI = false, bool SP2 = false>
; __device__ __forceinline__ void gemm_phase(PG8_LAS unsigned char* lds, const Gemm g, const Sched& S, const Epi& E) {
;     ...
;         for (int t = 0; t < nt; t += 2) {
;     ...
;             PG8_LDA(At, 1, 1); PG8_STAGE(PG8_SB(1, 0), b3, voffB); PG8_STAGE(PG8_SB(1, 1), b3 + hstep, voffB); PG8_STAGE(PG8_SA(1, 0), a3, voffA);
;             PG8_WAIT_V(8); PG8_WAIT_L(0); PG8_BAR; PG8_MMA(1, 0, At, B0); PG8_MMA(1, 1, At, B1); PG8_BAR; PG8_SCHED;
	s_add_i32 s48, s65, s11
	v_lshl_add_u64 v[186:187], v[186:187], 0, s[28:29]
	s_mov_b32 m0, s48
	ds_read_b128 v[174:177], v192 offset:49152
	ds_read_b128 v[178:181], v192 offset:50176
	ds_read_b128 v[182:185], v192 offset:51200
	ds_read_b128 v[194:197], v192 offset:52224
	ds_read_b128 v[198:201], v192 offset:53248
	ds_read_b128 v[206:209], v192 offset:54272
	ds_read_b128 v[210:213], v192 offset:55296
	ds_read_b128 v[214:217], v192 offset:56320
	global_load_lds_dwordx4 v[186:187], off
	s_add_i32 m0, s48, 0x2000
	s_add_u32 s24, s24, 0x40080
	v_lshl_add_u64 v[186:187], v[218:219], 0, s[28:29]
	s_addc_u32 s25, s25, 0
	s_add_i32 s48, s66, s11
	global_load_lds_dwordx4 v[186:187], off
	v_lshl_add_u64 v[186:187], s[24:25], 0, v[0:1]
	s_mov_b32 m0, s48
	s_nop 0
	global_load_lds_dwordx4 v[186:187], off
	v_lshl_add_u64 v[186:187], s[24:25], 0, v[162:163]
	s_add_i32 m0, s48, 0x2000
	s_nop 0
	global_load_lds_dwordx4 v[186:187], off
	v_lshl_add_u64 v[186:187], v[220:221], 0, s[28:29]
	s_mov_b32 m0, s54
	s_nop 0
	global_load_lds_dwordx4 v[186:187], off
	v_lshl_add_u64 v[186:187], v[222:223], 0, s[28:29]
	s_mov_b32 m0, s55
	s_nop 0
	global_load_lds_dwordx4 v[186:187], off
	s_waitcnt vmcnt(8)
	s_waitcnt lgkmcnt(0)
	s_barrier
	s_setprio 1
	v_mfma_f32_16x16x32_bf16 v[62:65], v[130:133], v[174:177], v[62:65]
	v_mfma_f32_16x16x32_bf16 v[58:61], v[138:141], v[174:177], v[58:61]
	v_mfma_f32_16x16x32_bf16 v[46:49], v[130:133], v[182:185], v[46:49]
	v_mfma_f32_16x16x32_bf16 v[42:45], v[138:141], v[182:185], v[42:45]
	v_mfma_f32_16x16x32_bf16 v[30:33], v[130:133], v[198:201], v[30:33]
	v_mfma_f32_16x16x32_bf16 v[26:29], v[138:141], v[198:201], v[26:29]
	v_mfma_f32_16x16x32_bf16 v[14:17], v[130:133], v[210:213], v[14:17]
	v_mfma_f32_16x16x32_bf16 v[10:13], v[138:141], v[210:213], v[10:13]
	v_mfma_f32_16x16x32_bf16 v[62:65], v[134:137], v[178:181], v[62:65]
	v_mfma_f32_16x16x32_bf16 v[58:61], v[142:145], v[178:181], v[58:61]
	v_mfma_f32_16x16x32_bf16 v[46:49], v[134:137], v[194:197], v[46:49]
	v_mfma_f32_16x16x32_bf16 v[42:45], v[142:145], v[194:197], v[42:45]
	v_mfma_f32_16x16x32_bf16 v[30:33], v[134:137], v[206:209], v[30:33]
	v_mfma_f32_16x16x32_bf16 v[26:29], v[142:145], v[206:209], v[26:29]
	v_mfma_f32_16x16x32_bf16 v[14:17], v[134:137], v[214:217], v[14:17]
	v_mfma_f32_16x16x32_bf16 v[10:13], v[142:145], v[214:217], v[10:13]
	v_mfma_f32_16x16x32_bf16 v[54:57], v[146:149], v[174:177], v[54:57]
	v_mfma_f32_16x16x32_bf16 v[50:53], v[154:157], v[174:177], v[50:53]
	v_mfma_f32_16x16x32_bf16 v[38:41], v[146:149], v[182:185], v[38:41]
	v_mfma_f32_16x16x32_bf16 v[34:37], v[154:157], v[182:185], v[34:37]
	v_mfma_f32_16x16x32_bf16 v[22:25], v[146:149], v[198:201], v[22:25]
	v_mfma_f32_16x16x32_bf16 v[18:21], v[154:157], v[198:201], v[18:21]
	v_mfma_f32_16x16x32_bf16 v[6:9], v[146:149], v[210:213], v[6:9]
	v_mfma_f32_16x16x32_bf16 v[2:5], v[154:157], v[210:213], v[2:5]
	v_mfma_f32_16x16x32_bf16 v[54:57], v[150:153], v[178:181], v[54:57]
	v_mfma_f32_16x16x32_bf16 v[50:53], v[170:173], v[178:181], v[50:53]
	v_mfma_f32_16x16x32_bf16 v[38:41], v[150:153], v[194:197], v[38:41]
	v_mfma_f32_16x16x32_bf16 v[34:37], v[170:173], v[194:197], v[34:37]
	v_mfma_f32_16x16x32_bf16 v[22:25], v[150:153], v[206:209], v[22:25]
	v_mfma_f32_16x16x32_bf16 v[18:21], v[170:173], v[206:209], v[18:21]
	v_mfma_f32_16x16x32_bf16 v[6:9], v[150:153], v[214:217], v[6:9]
	v_mfma_f32_16x16x32_bf16 v[2:5], v[170:173], v[214:217], v[2:5]
	s_setprio 0
	s_barrier
	s_add_i32 s64, s64, 2
	s_add_u32 s46, s46, 0x100
	s_addc_u32 s47, s47, 0
	s_add_u32 s62, s62, 0x100
	s_addc_u32 s63, s63, 0
	s_cmp_gt_u32 s64, 13

; __device__ __forceinline__ unsigned cvt_pk_bf16(float lo, float hi) { unsigned r; asm volatile("v_cvt_pk_bf16_f32 %0, %1, %2" : "=v"(r) : "v"(lo), "v"(hi)); return r; }
;     __device__ __forceinline__ void operator()(const f32x4 (&acc)[2][2][4][2], const Unit& u, int wr, int wc, int fr, int fq) const {
;     ...
; #pragma unroll
;         for (int ai = 0; ai < 2; ++ai)
; #pragma unroll
;             for (int m = 0; m < 4; ++m) {
;                 bf16_t* rowp = H + (size_t)(row0 + ai * HALF + m * 16) * ldh + col0;
;                 const float rs = rsv[ai][m], rsl = rs * -1.4426950408889634f, rs2 = rs * rs;
;                 float tq[8], pq8[8], hv[8];
; #pragma unroll
;                 for (int k = 0; k < 8; ++k) { tq[k] = acc[ai][0][m][k >> 2][k & 3] * rsl; asm volatile("" : "+v"(tq[k])); }
; #pragma unroll
;                 for (int k = 0; k < 8; ++k) { tq[k] = __builtin_amdgcn_exp2f(tq[k]); asm volatile("" : "+v"(tq[k])); }
; #pragma unroll
;                 for (int k = 0; k < 8; ++k) { pq8[k] = acc[ai][0][m][k >> 2][k & 3] * acc[ai][1][m][k >> 2][k & 3]; asm volatile("" : "+v"(pq8[k])); }
; #pragma unroll
;                 for (int k = 0; k < 8; ++k) { tq[k] = tq[k] + 1.0f; asm volatile("" : "+v"(tq[k])); }
; #pragma unroll
;                 for (int k = 0; k < 8; ++k) { tq[k] = __builtin_amdgcn_rcpf(tq[k]); asm volatile("" : "+v"(tq[k])); }
; #pragma unroll
;                 for (int k = 0; k < 8; ++k) { pq8[k] = pq8[k] * rs2; asm volatile("" : "+v"(pq8[k])); }
; #pragma unroll
;                 for (int k = 0; k < 8; ++k) hv[k] = pq8[k] * tq[k];
;                 u32x4 w; w.x = cvt_pk_bf16(hv[0], hv[1]); w.y = cvt_pk_bf16(hv[2], hv[3]); w.z = cvt_pk_bf16(hv[4], hv[5]); w.w = cvt_pk_bf16(hv[6], hv[7]);
;                 __builtin_nontemporal_store(w, (u32x4*)rowp);
.LBB0_482:
	v_mov_b64_e32 v[130:131], s[2:3]
	s_movk_i32 s17, 0x1600
	v_mad_u64_u32 v[136:137], s[24:25], v186, s17, v[130:131]
	v_mov_b32_e32 v138, v137
	v_mad_u64_u32 v[138:139], s[24:25], v187, s17, v[138:139]
	v_mov_b32_e32 v137, v138
	s_waitcnt lgkmcnt(0)
	v_mul_f32_e32 v138, 0xbfb8aa3b, v182
	v_mul_f32_e32 v226, v182, v182
	v_rcp_f32_e32 v226, v226
	v_mul_f32_e32 v139, v126, v138
	v_mul_f32_e32 v140, v127, v138
	v_mul_f32_e32 v141, v128, v138
	v_mul_f32_e32 v144, v129, v138
	v_mul_f32_e32 v145, v122, v138
	v_mul_f32_e32 v146, v123, v138
	v_mul_f32_e32 v147, v124, v138
	v_mul_f32_e32 v138, v125, v138
	s_nop 0
	v_exp_f32_e32 v139, v139
	v_exp_f32_e32 v140, v140
	v_exp_f32_e32 v141, v141
	v_exp_f32_e32 v144, v144
	v_exp_f32_e32 v145, v145
	v_exp_f32_e32 v146, v146
	v_exp_f32_e32 v147, v147
	v_exp_f32_e32 v138, v138
	v_mul_f32_e32 v118, v126, v118
	v_mul_f32_e32 v119, v127, v119
	v_mul_f32_e32 v120, v128, v120
	v_mul_f32_e32 v121, v129, v121
	v_mul_f32_e32 v114, v122, v114
	v_mul_f32_e32 v115, v123, v115
	v_mul_f32_e32 v116, v124, v116
	v_mul_f32_e32 v117, v125, v117
	v_fma_f32 v122, v139, v226, v226
	v_fma_f32 v123, v140, v226, v226
	v_fma_f32 v124, v141, v226, v226
	v_fma_f32 v125, v144, v226, v226
	v_fma_f32 v126, v145, v226, v226
	v_fma_f32 v127, v146, v226, v226
	v_fma_f32 v128, v147, v226, v226
	v_fma_f32 v129, v138, v226, v226
	v_lshl_or_b32 v132, s42, 7, v190
	v_ashrrev_i32_e32 v133, 31, v132
	v_rcp_f32_e32 v122, v122
	v_rcp_f32_e32 v123, v123
	v_rcp_f32_e32 v124, v124
	v_rcp_f32_e32 v125, v125
	v_rcp_f32_e32 v126, v126
	v_rcp_f32_e32 v127, v127
	v_rcp_f32_e32 v128, v128
	v_rcp_f32_e32 v129, v129
	v_lshlrev_b64 v[132:133], 1, v[132:133]
	v_lshl_add_u64 v[136:137], v[136:137], 0, v[132:133]
	v_mov_b64_e32 v[228:229], v[136:137]
	v_mul_f32_e32 v118, v122, v118
	v_mul_f32_e32 v119, v123, v119
	v_mul_f32_e32 v120, v124, v120
	v_mul_f32_e32 v121, v125, v121
	v_mul_f32_e32 v122, v126, v114
	v_mul_f32_e32 v123, v127, v115
	v_mul_f32_e32 v117, v129, v117
	v_cvt_pk_bf16_f32 v114, v118, v119
	v_cvt_pk_bf16_f32 v115, v120, v121
	v_mul_f32_e32 v124, v128, v116
	v_cvt_pk_bf16_f32 v116, v122, v123
	v_cvt_pk_bf16_f32 v117, v124, v117
	global_store_dwordx4 v[136:137], v[114:117], off nt
	v_mul_f32_e32 v102, v110, v102
	v_mul_f32_e32 v103, v111, v103
	v_mul_f32_e32 v116, 0xbfb8aa3b, v183
	v_mul_f32_e32 v227, v183, v183
	v_rcp_f32_e32 v227, v227
	v_mul_f32_e32 v117, v110, v116
	v_mul_f32_e32 v118, v111, v116
	v_mul_f32_e32 v119, v112, v116
	v_mul_f32_e32 v120, v113, v116
	v_mul_f32_e32 v121, v106, v116
	v_mul_f32_e32 v122, v107, v116
	v_mul_f32_e32 v123, v108, v116
	v_mul_f32_e32 v116, v109, v116
	s_nop 0
	v_exp_f32_e32 v117, v117
	v_exp_f32_e32 v118, v118
	v_exp_f32_e32 v119, v119
	v_exp_f32_e32 v120, v120
	v_exp_f32_e32 v121, v121
	v_exp_f32_e32 v122, v122
	v_exp_f32_e32 v123, v123
	v_exp_f32_e32 v116, v116
	v_mul_f32_e32 v104, v112, v104
	v_mul_f32_e32 v105, v113, v105
	v_mul_f32_e32 v98, v106, v98
	v_mul_f32_e32 v99, v107, v99
	v_mul_f32_e32 v100, v108, v100
	v_mul_f32_e32 v101, v109, v101
	v_fma_f32 v106, v117, v227, v227
	v_fma_f32 v107, v118, v227, v227
	v_fma_f32 v108, v119, v227, v227
	v_fma_f32 v109, v120, v227, v227
	v_fma_f32 v110, v121, v227, v227
	v_fma_f32 v111, v122, v227, v227
	v_fma_f32 v112, v123, v227, v227
	v_fma_f32 v113, v116, v227, v227
	v_rcp_f32_e32 v106, v106
	v_rcp_f32_e32 v107, v107
	v_rcp_f32_e32 v108, v108
	v_rcp_f32_e32 v109, v109
	v_rcp_f32_e32 v110, v110
	v_rcp_f32_e32 v111, v111
	v_rcp_f32_e32 v112, v112
	v_rcp_f32_e32 v113, v113
	s_mov_b32 s24, 0x16000
	s_mov_b32 s25, 0
	v_lshl_add_u64 v[114:115], v[228:229], 0, s[24:25]
	v_mul_f32_e32 v102, v106, v102
	v_mul_f32_e32 v103, v107, v103
	v_mul_f32_e32 v104, v108, v104
	v_mul_f32_e32 v105, v109, v105
	v_mul_f32_e32 v106, v110, v98
	v_mul_f32_e32 v107, v111, v99
	v_mul_f32_e32 v101, v113, v101
	v_cvt_pk_bf16_f32 v98, v102, v103
	v_cvt_pk_bf16_f32 v99, v104, v105
	v_mul_f32_e32 v108, v112, v100
	v_cvt_pk_bf16_f32 v100, v106, v107
	v_cvt_pk_bf16_f32 v101, v108, v101
	global_store_dwordx4 v[114:115], v[98:101], off nt
	v_mul_f32_e32 v86, v94, v86
	v_mul_f32_e32 v87, v95, v87
	v_mul_f32_e32 v100, 0xbfb8aa3b, v150
	v_mul_f32_e32 v226, v150, v150
	v_rcp_f32_e32 v226, v226
	v_mul_f32_e32 v101, v94, v100
	v_mul_f32_e32 v102, v95, v100
	v_mul_f32_e32 v103, v96, v100
	v_mul_f32_e32 v104, v97, v100
	v_mul_f32_e32 v105, v90, v100
	v_mul_f32_e32 v106, v91, v100
	v_mul_f32_e32 v107, v92, v100
	v_mul_f32_e32 v100, v93, v100
	s_nop 0
	v_exp_f32_e32 v101, v101
	v_exp_f32_e32 v102, v102
	v_exp_f32_e32 v103, v103
	v_exp_f32_e32 v104, v104
	v_exp_f32_e32 v105, v105
	v_exp_f32_e32 v106, v106
	v_exp_f32_e32 v107, v107
	v_exp_f32_e32 v100, v100
	v_mul_f32_e32 v88, v96, v88
	v_mul_f32_e32 v89, v97, v89
	v_mul_f32_e32 v82, v90, v82
	v_mul_f32_e32 v83, v91, v83
	v_mul_f32_e32 v84, v92, v84
	v_mul_f32_e32 v85, v93, v85
	v_fma_f32 v90, v101, v226, v226
	v_fma_f32 v91, v102, v226, v226
	v_fma_f32 v92, v103, v226, v226
	v_fma_f32 v93, v104, v226, v226
	v_fma_f32 v94, v105, v226, v226
	v_fma_f32 v95, v106, v226, v226
	v_fma_f32 v96, v107, v226, v226
	v_fma_f32 v97, v100, v226, v226
	v_rcp_f32_e32 v90, v90
	v_rcp_f32_e32 v91, v91
	v_rcp_f32_e32 v92, v92
	v_rcp_f32_e32 v93, v93
	v_rcp_f32_e32 v94, v94
	v_rcp_f32_e32 v95, v95
	v_rcp_f32_e32 v96, v96
	v_rcp_f32_e32 v97, v97
	s_mov_b32 s24, 0x2c000
	s_mov_b32 s25, 0
	v_lshl_add_u64 v[98:99], v[228:229], 0, s[24:25]
	v_mul_f32_e32 v86, v90, v86
	v_mul_f32_e32 v87, v91, v87
	v_mul_f32_e32 v88, v92, v88
	v_mul_f32_e32 v89, v93, v89
	v_mul_f32_e32 v90, v94, v82
	v_mul_f32_e32 v91, v95, v83
	v_mul_f32_e32 v85, v97, v85
	v_cvt_pk_bf16_f32 v82, v86, v87
; __device__ __forceinline__ unsigned cvt_pk_bf16(float lo, float hi) { unsigned r; asm volatile("v_cvt_pk_bf16_f32 %0, %1, %2" : "=v"(r) : "v"(lo), "v"(hi)); return r; }
;     __device__ __forceinline__ void operator()(const f32x4 (&acc)[2][2][4][2], const Unit& u, int wr, int wc, int fr, int fq) const {
;     ...
; #pragma unroll
;         for (int ai = 0; ai < 2; ++ai)
; #pragma unroll
;             for (int m = 0; m < 4; ++m) {
;                 bf16_t* rowp = H + (size_t)(row0 + ai * HALF + m * 16) * ldh + col0;
;                 const float rs = rsv[ai][m], rsl = rs * -1.4426950408889634f, rs2 = rs * rs;
;                 float tq[8], pq8[8], hv[8];
; #pragma unroll
;                 for (int k = 0; k < 8; ++k) { tq[k] = acc[ai][0][m][k >> 2][k & 3] * rsl; asm volatile("" : "+v"(tq[k])); }
; #pragma unroll
;                 for (int k = 0; k < 8; ++k) { tq[k] = __builtin_amdgcn_exp2f(tq[k]); asm volatile("" : "+v"(tq[k])); }
; #pragma unroll
;                 for (int k = 0; k < 8; ++k) { pq8[k] = acc[ai][0][m][k >> 2][k & 3] * acc[ai][1][m][k >> 2][k & 3]; asm volatile("" : "+v"(pq8[k])); }
; #pragma unroll
;                 for (int k = 0; k < 8; ++k) { tq[k] = tq[k] + 1.0f; asm volatile("" : "+v"(tq[k])); }
; #pragma unroll
;                 for (int k = 0; k < 8; ++k) { tq[k] = __builtin_amdgcn_rcpf(tq[k]); asm volatile("" : "+v"(tq[k])); }
; #pragma unroll
;                 for (int k = 0; k < 8; ++k) { pq8[k] = pq8[k] * rs2; asm volatile("" : "+v"(pq8[k])); }
; #pragma unroll
;                 for (int k = 0; k < 8; ++k) hv[k] = pq8[k] * tq[k];
;                 u32x4 w; w.x = cvt_pk_bf16(hv[0], hv[1]); w.y = cvt_pk_bf16(hv[2], hv[3]); w.z = cvt_pk_bf16(hv[4], hv[5]); w.w = cvt_pk_bf16(hv[6], hv[7]);
;                 __builtin_nontemporal_store(w, (u32x4*)rowp);
	v_cvt_pk_bf16_f32 v83, v88, v89
	v_mul_f32_e32 v92, v96, v84
	v_cvt_pk_bf16_f32 v84, v90, v91
	v_cvt_pk_bf16_f32 v85, v92, v85
	global_store_dwordx4 v[98:99], v[82:85], off nt
	v_mul_f32_e32 v70, v78, v70
	v_mul_f32_e32 v71, v79, v71
	v_mul_f32_e32 v84, 0xbfb8aa3b, v151
	v_mul_f32_e32 v227, v151, v151
	v_rcp_f32_e32 v227, v227
	v_mul_f32_e32 v85, v78, v84
	v_mul_f32_e32 v86, v79, v84
	v_mul_f32_e32 v87, v80, v84
	v_mul_f32_e32 v88, v81, v84
	v_mul_f32_e32 v89, v74, v84
	v_mul_f32_e32 v90, v75, v84
	v_mul_f32_e32 v91, v76, v84
	v_mul_f32_e32 v84, v77, v84
	s_nop 0
	v_exp_f32_e32 v85, v85
	v_exp_f32_e32 v86, v86
	v_exp_f32_e32 v87, v87
	v_exp_f32_e32 v88, v88
	v_exp_f32_e32 v89, v89
	v_exp_f32_e32 v90, v90
	v_exp_f32_e32 v91, v91
	v_exp_f32_e32 v84, v84
	v_mul_f32_e32 v72, v80, v72
	v_mul_f32_e32 v73, v81, v73
	v_mul_f32_e32 v66, v74, v66
	v_mul_f32_e32 v67, v75, v67
	v_mul_f32_e32 v68, v76, v68
	v_mul_f32_e32 v69, v77, v69
	v_fma_f32 v74, v85, v227, v227
	v_fma_f32 v75, v86, v227, v227
	v_fma_f32 v76, v87, v227, v227
	v_fma_f32 v77, v88, v227, v227
	v_fma_f32 v78, v89, v227, v227
	v_fma_f32 v79, v90, v227, v227
	v_fma_f32 v80, v91, v227, v227
	v_fma_f32 v81, v84, v227, v227
	v_rcp_f32_e32 v74, v74
	v_rcp_f32_e32 v75, v75
	v_rcp_f32_e32 v76, v76
	v_rcp_f32_e32 v77, v77
	v_rcp_f32_e32 v78, v78
	v_rcp_f32_e32 v79, v79
	v_rcp_f32_e32 v80, v80
	v_rcp_f32_e32 v81, v81
	s_mov_b32 s24, 0x42000
	s_mov_b32 s25, 0
	v_lshl_add_u64 v[82:83], v[228:229], 0, s[24:25]
	v_mul_f32_e32 v70, v74, v70
	v_mul_f32_e32 v71, v75, v71
	v_mul_f32_e32 v72, v76, v72
	v_mul_f32_e32 v73, v77, v73
	v_mul_f32_e32 v74, v78, v66
	v_mul_f32_e32 v75, v79, v67
	v_mul_f32_e32 v69, v81, v69
	v_cvt_pk_bf16_f32 v66, v70, v71
	v_cvt_pk_bf16_f32 v67, v72, v73
	v_mul_f32_e32 v76, v80, v68
	v_cvt_pk_bf16_f32 v68, v74, v75
	v_cvt_pk_bf16_f32 v69, v76, v69
	global_store_dwordx4 v[82:83], v[66:69], off nt
	v_mul_f32_e32 v54, v62, v54
	v_mul_f32_e32 v55, v63, v55
	v_mul_f32_e32 v68, 0xbfb8aa3b, v142
	v_mul_f32_e32 v226, v142, v142
	v_rcp_f32_e32 v226, v226
	v_mul_f32_e32 v69, v62, v68
	v_mul_f32_e32 v70, v63, v68
	v_mul_f32_e32 v71, v64, v68
	v_mul_f32_e32 v72, v65, v68
	v_mul_f32_e32 v73, v58, v68
	v_mul_f32_e32 v74, v59, v68
	v_mul_f32_e32 v75, v60, v68
	v_mul_f32_e32 v68, v61, v68
	s_nop 0
	v_exp_f32_e32 v69, v69
	v_exp_f32_e32 v70, v70
	v_exp_f32_e32 v71, v71
	v_exp_f32_e32 v72, v72
	v_exp_f32_e32 v73, v73
	v_exp_f32_e32 v74, v74
	v_exp_f32_e32 v75, v75
	v_exp_f32_e32 v68, v68
	v_mul_f32_e32 v56, v64, v56
	v_mul_f32_e32 v57, v65, v57
	v_mul_f32_e32 v50, v58, v50
	v_mul_f32_e32 v51, v59, v51
	v_mul_f32_e32 v52, v60, v52
	v_mul_f32_e32 v53, v61, v53
	v_fma_f32 v58, v69, v226, v226
	v_fma_f32 v59, v70, v226, v226
	v_fma_f32 v60, v71, v226, v226
	v_fma_f32 v61, v72, v226, v226
	v_fma_f32 v62, v73, v226, v226
	v_fma_f32 v63, v74, v226, v226
	v_fma_f32 v64, v75, v226, v226
	v_fma_f32 v65, v68, v226, v226
	v_rcp_f32_e32 v58, v58
	v_rcp_f32_e32 v59, v59
	v_rcp_f32_e32 v60, v60
	v_rcp_f32_e32 v61, v61
	v_rcp_f32_e32 v62, v62
	v_rcp_f32_e32 v63, v63
	v_rcp_f32_e32 v64, v64
	v_rcp_f32_e32 v65, v65
	s_mov_b32 s24, 0xb0000
	s_mov_b32 s25, 0
	v_lshl_add_u64 v[66:67], v[228:229], 0, s[24:25]
	v_mul_f32_e32 v54, v58, v54
	v_mul_f32_e32 v55, v59, v55
	v_mul_f32_e32 v56, v60, v56
	v_mul_f32_e32 v57, v61, v57
	v_mul_f32_e32 v58, v62, v50
	v_mul_f32_e32 v59, v63, v51
	v_mul_f32_e32 v53, v65, v53
	v_cvt_pk_bf16_f32 v50, v54, v55
	v_cvt_pk_bf16_f32 v51, v56, v57
	v_mul_f32_e32 v60, v64, v52
	v_cvt_pk_bf16_f32 v52, v58, v59
	v_cvt_pk_bf16_f32 v53, v60, v53
	global_store_dwordx4 v[66:67], v[50:53], off nt
	v_mul_f32_e32 v38, v46, v38
	v_mul_f32_e32 v39, v47, v39
	v_mul_f32_e32 v52, 0xbfb8aa3b, v143
	v_mul_f32_e32 v227, v143, v143
	v_rcp_f32_e32 v227, v227
	v_mul_f32_e32 v53, v46, v52
	v_mul_f32_e32 v54, v47, v52
	v_mul_f32_e32 v55, v48, v52
	v_mul_f32_e32 v56, v49, v52
	v_mul_f32_e32 v57, v42, v52
	v_mul_f32_e32 v58, v43, v52
	v_mul_f32_e32 v59, v44, v52
	v_mul_f32_e32 v52, v45, v52
	s_nop 0
	v_exp_f32_e32 v53, v53
	v_exp_f32_e32 v54, v54
	v_exp_f32_e32 v55, v55
	v_exp_f32_e32 v56, v56
	v_exp_f32_e32 v57, v57
	v_exp_f32_e32 v58, v58
	v_exp_f32_e32 v59, v59
	v_exp_f32_e32 v52, v52
	v_mul_f32_e32 v40, v48, v40
	v_mul_f32_e32 v41, v49, v41
	v_mul_f32_e32 v34, v42, v34
	v_mul_f32_e32 v35, v43, v35
	v_mul_f32_e32 v36, v44, v36
	v_mul_f32_e32 v37, v45, v37
	v_fma_f32 v42, v53, v227, v227
	v_fma_f32 v43, v54, v227, v227
; __device__ __forceinline__ unsigned cvt_pk_bf16(float lo, float hi) { unsigned r; asm volatile("v_cvt_pk_bf16_f32 %0, %1, %2" : "=v"(r) : "v"(lo), "v"(hi)); return r; }
;     __device__ __forceinline__ void operator()(const f32x4 (&acc)[2][2][4][2], const Unit& u, int wr, int wc, int fr, int fq) const {
;     ...
;                 bf16_t* rowp = H + (size_t)(row0 + ai * HALF + m * 16) * ldh + col0;
;                 const float rs = rsv[ai][m], rsl = rs * -1.4426950408889634f, rs2 = rs * rs;
;                 float tq[8], pq8[8], hv[8];
; #pragma unroll
;                 for (int k = 0; k < 8; ++k) { tq[k] = acc[ai][0][m][k >> 2][k & 3] * rsl; asm volatile("" : "+v"(tq[k])); }
; #pragma unroll
;                 for (int k = 0; k < 8; ++k) { tq[k] = __builtin_amdgcn_exp2f(tq[k]); asm volatile("" : "+v"(tq[k])); }
; #pragma unroll
;                 for (int k = 0; k < 8; ++k) { pq8[k] = acc[ai][0][m][k >> 2][k & 3] * acc[ai][1][m][k >> 2][k & 3]; asm volatile("" : "+v"(pq8[k])); }
; #pragma unroll
;                 for (int k = 0; k < 8; ++k) { tq[k] = tq[k] + 1.0f; asm volatile("" : "+v"(tq[k])); }
; #pragma unroll
;                 for (int k = 0; k < 8; ++k) { tq[k] = __builtin_amdgcn_rcpf(tq[k]); asm volatile("" : "+v"(tq[k])); }
; #pragma unroll
;                 for (int k = 0; k < 8; ++k) { pq8[k] = pq8[k] * rs2; asm volatile("" : "+v"(pq8[k])); }
; #pragma unroll
;                 for (int k = 0; k < 8; ++k) hv[k] = pq8[k] * tq[k];
;                 u32x4 w; w.x = cvt_pk_bf16(hv[0], hv[1]); w.y = cvt_pk_bf16(hv[2], hv[3]); w.z = cvt_pk_bf16(hv[4], hv[5]); w.w = cvt_pk_bf16(hv[6], hv[7]);
;                 __builtin_nontemporal_store(w, (u32x4*)rowp);
	v_fma_f32 v44, v55, v227, v227
	v_fma_f32 v45, v56, v227, v227
	v_fma_f32 v46, v57, v227, v227
	v_fma_f32 v47, v58, v227, v227
	v_fma_f32 v48, v59, v227, v227
	v_fma_f32 v49, v52, v227, v227
	v_rcp_f32_e32 v42, v42
	v_rcp_f32_e32 v43, v43
	v_rcp_f32_e32 v44, v44
	v_rcp_f32_e32 v45, v45
	v_rcp_f32_e32 v46, v46
	v_rcp_f32_e32 v47, v47
	v_rcp_f32_e32 v48, v48
	v_rcp_f32_e32 v49, v49
	s_mov_b32 s24, 0xc6000
	s_mov_b32 s25, 0
	v_lshl_add_u64 v[50:51], v[228:229], 0, s[24:25]
	v_mul_f32_e32 v38, v42, v38
	v_mul_f32_e32 v39, v43, v39
	v_mul_f32_e32 v40, v44, v40
	v_mul_f32_e32 v41, v45, v41
	v_mul_f32_e32 v42, v46, v34
	v_mul_f32_e32 v43, v47, v35
	v_mul_f32_e32 v37, v49, v37
	v_cvt_pk_bf16_f32 v34, v38, v39
	v_cvt_pk_bf16_f32 v35, v40, v41
	v_mul_f32_e32 v44, v48, v36
	v_cvt_pk_bf16_f32 v36, v42, v43
	v_cvt_pk_bf16_f32 v37, v44, v37
	global_store_dwordx4 v[50:51], v[34:37], off nt
	v_mul_f32_e32 v22, v30, v22
	v_mul_f32_e32 v23, v31, v23
	v_mul_f32_e32 v36, 0xbfb8aa3b, v134
	v_mul_f32_e32 v226, v134, v134
	v_rcp_f32_e32 v226, v226
	v_mul_f32_e32 v37, v30, v36
	v_mul_f32_e32 v38, v31, v36
	v_mul_f32_e32 v39, v32, v36
	v_mul_f32_e32 v40, v33, v36
	v_mul_f32_e32 v41, v26, v36
	v_mul_f32_e32 v42, v27, v36
	v_mul_f32_e32 v43, v28, v36
	v_mul_f32_e32 v36, v29, v36
	s_nop 0
	v_exp_f32_e32 v37, v37
	v_exp_f32_e32 v38, v38
	v_exp_f32_e32 v39, v39
	v_exp_f32_e32 v40, v40
	v_exp_f32_e32 v41, v41
	v_exp_f32_e32 v42, v42
	v_exp_f32_e32 v43, v43
	v_exp_f32_e32 v36, v36
	v_mul_f32_e32 v24, v32, v24
	v_mul_f32_e32 v25, v33, v25
	v_mul_f32_e32 v18, v26, v18
	v_mul_f32_e32 v19, v27, v19
	v_mul_f32_e32 v20, v28, v20
	v_mul_f32_e32 v21, v29, v21
	v_fma_f32 v26, v37, v226, v226
	v_fma_f32 v27, v38, v226, v226
	v_fma_f32 v28, v39, v226, v226
	v_fma_f32 v29, v40, v226, v226
	v_fma_f32 v30, v41, v226, v226
	v_fma_f32 v31, v42, v226, v226
	v_fma_f32 v32, v43, v226, v226
	v_fma_f32 v33, v36, v226, v226
	v_rcp_f32_e32 v26, v26
	v_rcp_f32_e32 v27, v27
	v_rcp_f32_e32 v28, v28
	v_rcp_f32_e32 v29, v29
	v_rcp_f32_e32 v30, v30
	v_rcp_f32_e32 v31, v31
	v_rcp_f32_e32 v32, v32
	v_rcp_f32_e32 v33, v33
	s_mov_b32 s24, 0xdc000
	s_mov_b32 s25, 0
	v_lshl_add_u64 v[34:35], v[228:229], 0, s[24:25]
	v_mul_f32_e32 v22, v26, v22
	v_mul_f32_e32 v23, v27, v23
	v_mul_f32_e32 v24, v28, v24
	v_mul_f32_e32 v25, v29, v25
	v_mul_f32_e32 v26, v30, v18
	v_mul_f32_e32 v27, v31, v19
	v_mul_f32_e32 v21, v33, v21
	v_cvt_pk_bf16_f32 v18, v22, v23
	v_cvt_pk_bf16_f32 v19, v24, v25
	v_mul_f32_e32 v28, v32, v20
	v_cvt_pk_bf16_f32 v20, v26, v27
	v_cvt_pk_bf16_f32 v21, v28, v21
	global_store_dwordx4 v[34:35], v[18:21], off nt
	v_mul_f32_e32 v6, v14, v6
	v_mul_f32_e32 v7, v15, v7
	v_mul_f32_e32 v20, 0xbfb8aa3b, v135
	v_mul_f32_e32 v227, v135, v135
	v_rcp_f32_e32 v227, v227
	v_mul_f32_e32 v21, v14, v20
	v_mul_f32_e32 v22, v15, v20
	v_mul_f32_e32 v23, v16, v20
	v_mul_f32_e32 v24, v17, v20
	v_mul_f32_e32 v25, v10, v20
	v_mul_f32_e32 v26, v11, v20
	v_mul_f32_e32 v27, v12, v20
	v_mul_f32_e32 v20, v13, v20
	s_nop 0
	v_exp_f32_e32 v21, v21
	v_exp_f32_e32 v22, v22
	v_exp_f32_e32 v23, v23
	v_exp_f32_e32 v24, v24
	v_exp_f32_e32 v25, v25
	v_exp_f32_e32 v26, v26
	v_exp_f32_e32 v27, v27
	v_exp_f32_e32 v20, v20
	v_mul_f32_e32 v8, v16, v8
	v_mul_f32_e32 v9, v17, v9
	v_mul_f32_e32 v2, v10, v2
	v_mul_f32_e32 v3, v11, v3
	v_mul_f32_e32 v4, v12, v4
	v_mul_f32_e32 v5, v13, v5
	v_fma_f32 v10, v21, v227, v227
	v_fma_f32 v11, v22, v227, v227
	v_fma_f32 v12, v23, v227, v227
	v_fma_f32 v13, v24, v227, v227
	v_fma_f32 v14, v25, v227, v227
	v_fma_f32 v15, v26, v227, v227
	v_fma_f32 v16, v27, v227, v227
	v_fma_f32 v17, v20, v227, v227
	v_rcp_f32_e32 v10, v10
	v_rcp_f32_e32 v11, v11
	v_rcp_f32_e32 v12, v12
	v_rcp_f32_e32 v13, v13
	v_rcp_f32_e32 v14, v14
	v_rcp_f32_e32 v15, v15
	v_rcp_f32_e32 v16, v16
	v_rcp_f32_e32 v17, v17
	s_mov_b32 s24, 0xf2000
	s_mov_b32 s25, 0
	v_lshl_add_u64 v[18:19], v[228:229], 0, s[24:25]
	v_mul_f32_e32 v5, v17, v5
	s_andn2_b64 vcc, exec, s[8:9]
	s_mov_b64 s[8:9], -1
	v_mul_f32_e32 v6, v10, v6
	v_mul_f32_e32 v7, v11, v7
	v_mul_f32_e32 v8, v12, v8
	v_mul_f32_e32 v9, v13, v9
	v_mul_f32_e32 v10, v14, v2
	v_mul_f32_e32 v11, v15, v3
	v_mul_f32_e32 v12, v16, v4
	v_cvt_pk_bf16_f32 v2, v6, v7
	v_cvt_pk_bf16_f32 v3, v8, v9
	v_cvt_pk_bf16_f32 v4, v10, v11
	v_cvt_pk_bf16_f32 v5, v12, v5
	global_store_dwordx4 v[18:19], v[2:5], off nt
	s_cbranch_vccnz .LBB0_453
	s_andn2_b64 vcc, exec, s[0:1]
	s_cbranch_vccnz .LBB0_452
	s_barrier
	s_branch .LBB0_452
